# v33 + exact counted lgkmcnt waits at first consumer in both attention phases
# speedup vs baseline: 1.0113x; 1.0113x over previous
.LBB0_726:
	v_add_u32_e32 v142, s11, v127
	v_add_u32_e32 v143, v142, v128
	v_exp_f32_e32 v50, v50
	v_exp_f32_e32 v51, v51
	v_exp_f32_e32 v52, v52
	v_exp_f32_e32 v53, v53
	ds_read_b64_tr_b16 v[144:145], v143 offset:16384
	ds_read_b64_tr_b16 v[146:147], v143 offset:17408
	v_exp_f32_e32 v54, v54
	v_exp_f32_e32 v55, v55
	v_exp_f32_e32 v56, v56
	v_exp_f32_e32 v57, v57
	v_cvt_pk_bf16_f32 v148, v50, v51
	v_cvt_pk_bf16_f32 v149, v52, v53
	v_cvt_pk_bf16_f32 v150, v54, v55
	v_cvt_pk_bf16_f32 v151, v56, v57
	v_add_u32_e32 v142, v142, v129
	v_exp_f32_e32 v58, v58
	s_waitcnt lgkmcnt(0)
	v_mfma_f32_32x32x16_bf16 v[2:17], v[144:147], v[148:151], v[2:17]
	ds_read_b64_tr_b16 v[144:145], v142 offset:16384
	ds_read_b64_tr_b16 v[146:147], v142 offset:17408
	v_exp_f32_e32 v59, v59
	v_exp_f32_e32 v60, v60
	v_exp_f32_e32 v61, v61
	v_exp_f32_e32 v62, v62
	v_exp_f32_e32 v63, v63
	v_exp_f32_e32 v64, v64
	s_waitcnt lgkmcnt(0)
	v_mfma_f32_32x32x16_bf16 v[18:33], v[144:147], v[148:151], v[18:33]
	ds_read_b64_tr_b16 v[144:145], v143 offset:18432
	ds_read_b64_tr_b16 v[146:147], v143 offset:19456
	v_exp_f32_e32 v65, v65
	v_mfma_f32_32x32x16_bf16 v[34:49], v[82:85], v[148:151], v[34:49]
	v_cvt_pk_bf16_f32 v148, v58, v59
	v_cvt_pk_bf16_f32 v149, v60, v61
	v_cvt_pk_bf16_f32 v150, v62, v63
	v_cvt_pk_bf16_f32 v151, v64, v65
	s_nop 0
	s_nop 0
	s_waitcnt lgkmcnt(0)
	v_mfma_f32_32x32x16_bf16 v[2:17], v[144:147], v[148:151], v[2:17]
	ds_read_b64_tr_b16 v[144:145], v142 offset:18432
	ds_read_b64_tr_b16 v[146:147], v142 offset:19456
	s_waitcnt lgkmcnt(0)
	v_mfma_f32_32x32x16_bf16 v[18:33], v[144:147], v[148:151], v[18:33]
	v_max_f32_e32 v144, v66, v67
	v_max3_f32 v144, v144, v68, v69
	v_max3_f32 v144, v144, v70, v71
	v_max3_f32 v144, v144, v72, v73
	v_max3_f32 v144, v144, v74, v75
	v_max3_f32 v144, v144, v76, v77
	v_mfma_f32_32x32x16_bf16 v[34:49], v[82:85], v[148:151], v[34:49]
	v_max3_f32 v144, v144, v78, v79
	v_max3_f32 v144, v144, v80, v81
	v_mov_b32_e32 v145, v144
	s_nop 1
	v_permlane32_swap_b32_e32 v144, v145
	v_max_f32_e32 v144, v144, v145
	v_cmp_lt_f32_e32 vcc, s8, v144
	s_cbranch_vccz .LBB0_728
	v_max_f32_e32 v144, v144, v144
	v_max_f32_e32 v144, 0, v144
	v_exp_f32_e64 v146, -v144
	v_add_f32_e32 v137, v137, v144
	v_pk_add_f32 v[66:67], v[66:67], v[144:145] op_sel_hi:[1,0] neg_lo:[0,1] neg_hi:[0,1]
	v_pk_add_f32 v[68:69], v[68:69], v[144:145] op_sel_hi:[1,0] neg_lo:[0,1] neg_hi:[0,1]
	v_mul_f32_e32 v34, v34, v146
	v_pk_add_f32 v[70:71], v[70:71], v[144:145] op_sel_hi:[1,0] neg_lo:[0,1] neg_hi:[0,1]
	v_pk_add_f32 v[72:73], v[72:73], v[144:145] op_sel_hi:[1,0] neg_lo:[0,1] neg_hi:[0,1]
	v_pk_add_f32 v[74:75], v[74:75], v[144:145] op_sel_hi:[1,0] neg_lo:[0,1] neg_hi:[0,1]
	v_pk_add_f32 v[76:77], v[76:77], v[144:145] op_sel_hi:[1,0] neg_lo:[0,1] neg_hi:[0,1]
	v_pk_add_f32 v[78:79], v[78:79], v[144:145] op_sel_hi:[1,0] neg_lo:[0,1] neg_hi:[0,1]
	v_pk_add_f32 v[80:81], v[80:81], v[144:145] op_sel_hi:[1,0] neg_lo:[0,1] neg_hi:[0,1]
	v_pk_mul_f32 v[32:33], v[32:33], v[146:147] op_sel_hi:[1,0]
	v_pk_mul_f32 v[30:31], v[30:31], v[146:147] op_sel_hi:[1,0]
	v_pk_mul_f32 v[28:29], v[28:29], v[146:147] op_sel_hi:[1,0]
	v_pk_mul_f32 v[26:27], v[26:27], v[146:147] op_sel_hi:[1,0]
	v_pk_mul_f32 v[24:25], v[24:25], v[146:147] op_sel_hi:[1,0]
	v_pk_mul_f32 v[22:23], v[22:23], v[146:147] op_sel_hi:[1,0]
	v_pk_mul_f32 v[20:21], v[20:21], v[146:147] op_sel_hi:[1,0]
	v_pk_mul_f32 v[18:19], v[18:19], v[146:147] op_sel_hi:[1,0]
	v_pk_mul_f32 v[16:17], v[16:17], v[146:147] op_sel_hi:[1,0]
	v_pk_mul_f32 v[14:15], v[14:15], v[146:147] op_sel_hi:[1,0]
	v_pk_mul_f32 v[12:13], v[12:13], v[146:147] op_sel_hi:[1,0]
	v_pk_mul_f32 v[10:11], v[10:11], v[146:147] op_sel_hi:[1,0]
	v_pk_mul_f32 v[8:9], v[8:9], v[146:147] op_sel_hi:[1,0]
	v_pk_mul_f32 v[6:7], v[6:7], v[146:147] op_sel_hi:[1,0]
	v_pk_mul_f32 v[4:5], v[4:5], v[146:147] op_sel_hi:[1,0]
	v_pk_mul_f32 v[2:3], v[2:3], v[146:147] op_sel_hi:[1,0]

.LBB0_735:
	v_add_u32_e32 v0, s11, v127
	v_add_u32_e32 v138, v0, v128
	v_exp_f32_e32 v50, v50
	v_exp_f32_e32 v51, v51
	v_exp_f32_e32 v52, v52
	v_exp_f32_e32 v53, v53
	ds_read_b64_tr_b16 v[140:141], v138 offset:24576
	ds_read_b64_tr_b16 v[142:143], v138 offset:25600
	v_exp_f32_e32 v54, v54
	v_exp_f32_e32 v55, v55
	v_exp_f32_e32 v56, v56
	v_exp_f32_e32 v57, v57
	v_cvt_pk_bf16_f32 v144, v50, v51
	v_cvt_pk_bf16_f32 v145, v52, v53
	v_cvt_pk_bf16_f32 v146, v54, v55
	v_cvt_pk_bf16_f32 v147, v56, v57
	v_add_u32_e32 v0, v0, v129
	v_exp_f32_e32 v58, v58
	s_waitcnt lgkmcnt(0)
	v_mfma_f32_32x32x16_bf16 v[2:17], v[140:143], v[144:147], v[2:17]
	ds_read_b64_tr_b16 v[140:141], v0 offset:24576
	ds_read_b64_tr_b16 v[142:143], v0 offset:25600
	v_exp_f32_e32 v59, v59
	v_exp_f32_e32 v60, v60
	v_exp_f32_e32 v61, v61
	v_exp_f32_e32 v62, v62
	v_exp_f32_e32 v63, v63
	v_exp_f32_e32 v64, v64
	s_waitcnt lgkmcnt(0)
	v_mfma_f32_32x32x16_bf16 v[18:33], v[140:143], v[144:147], v[18:33]
	ds_read_b64_tr_b16 v[140:141], v138 offset:26624
	ds_read_b64_tr_b16 v[142:143], v138 offset:27648
	v_exp_f32_e32 v65, v65
	v_max_f32_e32 v139, v67, v67
	v_mfma_f32_32x32x16_bf16 v[34:49], v[82:85], v[144:147], v[34:49]
	v_cvt_pk_bf16_f32 v144, v58, v59
	v_cvt_pk_bf16_f32 v145, v60, v61
	v_cvt_pk_bf16_f32 v146, v62, v63
	v_cvt_pk_bf16_f32 v147, v64, v65
	s_nop 0
	s_nop 0
	s_waitcnt lgkmcnt(0)
	v_mfma_f32_32x32x16_bf16 v[2:17], v[140:143], v[144:147], v[2:17]
	ds_read_b64_tr_b16 v[140:141], v0 offset:26624
	ds_read_b64_tr_b16 v[142:143], v0 offset:27648
	s_waitcnt lgkmcnt(0)
	v_mfma_f32_32x32x16_bf16 v[18:33], v[140:143], v[144:147], v[18:33]
	v_max_f32_e32 v140, v66, v66
	v_max_f32_e32 v139, v140, v139
	v_max3_f32 v139, v139, v68, v69
	v_max3_f32 v139, v139, v70, v71
	v_max3_f32 v139, v139, v72, v73
	v_max3_f32 v139, v139, v74, v75
	v_max3_f32 v139, v139, v76, v77
	v_mfma_f32_32x32x16_bf16 v[34:49], v[82:85], v[144:147], v[34:49]
	v_max3_f32 v139, v139, v78, v79
	v_max3_f32 v139, v139, v80, v81
	v_mov_b32_e32 v140, v139
	s_nop 1
	v_permlane32_swap_b32_e32 v139, v140
	v_max_f32_e32 v139, v139, v140
	v_cmp_lt_f32_e32 vcc, s8, v139
	s_cbranch_vccz .LBB0_737
	v_max_f32_e32 v139, v139, v139
	v_max_f32_e32 v140, 0, v139
	v_exp_f32_e64 v142, -v140
	v_add_f32_e32 v137, v137, v140
	v_pk_add_f32 v[66:67], v[66:67], v[140:141] op_sel_hi:[1,0] neg_lo:[0,1] neg_hi:[0,1]
	v_pk_add_f32 v[68:69], v[68:69], v[140:141] op_sel_hi:[1,0] neg_lo:[0,1] neg_hi:[0,1]
	v_mul_f32_e32 v34, v34, v142
	v_pk_add_f32 v[70:71], v[70:71], v[140:141] op_sel_hi:[1,0] neg_lo:[0,1] neg_hi:[0,1]
	v_pk_add_f32 v[72:73], v[72:73], v[140:141] op_sel_hi:[1,0] neg_lo:[0,1] neg_hi:[0,1]
	v_pk_add_f32 v[74:75], v[74:75], v[140:141] op_sel_hi:[1,0] neg_lo:[0,1] neg_hi:[0,1]
	v_pk_add_f32 v[76:77], v[76:77], v[140:141] op_sel_hi:[1,0] neg_lo:[0,1] neg_hi:[0,1]
	v_pk_add_f32 v[78:79], v[78:79], v[140:141] op_sel_hi:[1,0] neg_lo:[0,1] neg_hi:[0,1]
	v_pk_add_f32 v[80:81], v[80:81], v[140:141] op_sel_hi:[1,0] neg_lo:[0,1] neg_hi:[0,1]
	v_pk_mul_f32 v[32:33], v[32:33], v[142:143] op_sel_hi:[1,0]
	v_pk_mul_f32 v[30:31], v[30:31], v[142:143] op_sel_hi:[1,0]
	v_pk_mul_f32 v[28:29], v[28:29], v[142:143] op_sel_hi:[1,0]
	v_pk_mul_f32 v[26:27], v[26:27], v[142:143] op_sel_hi:[1,0]
	v_pk_mul_f32 v[24:25], v[24:25], v[142:143] op_sel_hi:[1,0]
	v_pk_mul_f32 v[22:23], v[22:23], v[142:143] op_sel_hi:[1,0]
	v_pk_mul_f32 v[20:21], v[20:21], v[142:143] op_sel_hi:[1,0]
	v_pk_mul_f32 v[18:19], v[18:19], v[142:143] op_sel_hi:[1,0]
	v_pk_mul_f32 v[16:17], v[16:17], v[142:143] op_sel_hi:[1,0]
	v_pk_mul_f32 v[14:15], v[14:15], v[142:143] op_sel_hi:[1,0]
	v_pk_mul_f32 v[12:13], v[12:13], v[142:143] op_sel_hi:[1,0]
	v_pk_mul_f32 v[10:11], v[10:11], v[142:143] op_sel_hi:[1,0]
	v_pk_mul_f32 v[8:9], v[8:9], v[142:143] op_sel_hi:[1,0]
	v_pk_mul_f32 v[6:7], v[6:7], v[142:143] op_sel_hi:[1,0]
	v_pk_mul_f32 v[4:5], v[4:5], v[142:143] op_sel_hi:[1,0]
	v_pk_mul_f32 v[2:3], v[2:3], v[142:143] op_sel_hi:[1,0]

.LBB0_756:
	v_add_u32_e32 v121, s91, v129
	v_add_u32_e32 v122, v121, v130
	v_exp_f32_e32 v50, v50
	v_exp_f32_e32 v51, v51
	v_exp_f32_e32 v52, v52
	v_exp_f32_e32 v53, v53
	ds_read_b64_tr_b16 v[136:137], v122 offset:16384
	ds_read_b64_tr_b16 v[138:139], v122 offset:17408
	v_exp_f32_e32 v54, v54
	v_exp_f32_e32 v55, v55
	v_exp_f32_e32 v56, v56
	v_exp_f32_e32 v57, v57
	v_cvt_pk_bf16_f32 v140, v50, v51
	v_cvt_pk_bf16_f32 v141, v52, v53
	v_cvt_pk_bf16_f32 v142, v54, v55
	v_cvt_pk_bf16_f32 v143, v56, v57
	v_add_u32_e32 v121, v121, v131
	v_exp_f32_e32 v58, v58
	s_waitcnt lgkmcnt(0)
	v_mfma_f32_32x32x16_bf16 v[2:17], v[136:139], v[140:143], v[2:17]
	ds_read_b64_tr_b16 v[136:137], v121 offset:16384
	ds_read_b64_tr_b16 v[138:139], v121 offset:17408
	v_exp_f32_e32 v59, v59
	v_exp_f32_e32 v60, v60
	v_exp_f32_e32 v61, v61
	v_exp_f32_e32 v62, v62
	v_exp_f32_e32 v63, v63
	v_exp_f32_e32 v64, v64
	s_waitcnt lgkmcnt(0)
	v_mfma_f32_32x32x16_bf16 v[18:33], v[136:139], v[140:143], v[18:33]
	ds_read_b64_tr_b16 v[136:137], v122 offset:18432
	ds_read_b64_tr_b16 v[138:139], v122 offset:19456
	v_exp_f32_e32 v65, v65
	v_max_f32_e32 v123, v67, v67
	v_mfma_f32_32x32x16_bf16 v[34:49], v[84:87], v[140:143], v[34:49]
	v_cvt_pk_bf16_f32 v140, v58, v59
	v_cvt_pk_bf16_f32 v141, v60, v61
	v_cvt_pk_bf16_f32 v142, v62, v63
	v_cvt_pk_bf16_f32 v143, v64, v65
	s_nop 0
	s_nop 0
	s_waitcnt lgkmcnt(0)
	v_mfma_f32_32x32x16_bf16 v[2:17], v[136:139], v[140:143], v[2:17]
	ds_read_b64_tr_b16 v[136:137], v121 offset:18432
	ds_read_b64_tr_b16 v[138:139], v121 offset:19456
	s_waitcnt lgkmcnt(0)
	v_mfma_f32_32x32x16_bf16 v[18:33], v[136:139], v[140:143], v[18:33]
	v_max_f32_e32 v136, v66, v66
	v_max_f32_e32 v123, v136, v123
	v_max3_f32 v123, v123, v68, v69
	v_max3_f32 v123, v123, v70, v71
	v_max3_f32 v123, v123, v72, v73
	v_max3_f32 v123, v123, v74, v75
	v_max3_f32 v123, v123, v76, v77
	v_mfma_f32_32x32x16_bf16 v[34:49], v[84:87], v[140:143], v[34:49]
	v_max3_f32 v123, v123, v78, v79
	v_max3_f32 v123, v123, v80, v81
	v_mov_b32_e32 v136, v123
	s_nop 1
	v_permlane32_swap_b32_e32 v123, v136
	v_max_f32_e32 v123, v123, v136
	v_cmp_lt_f32_e32 vcc, s95, v123
	s_cbranch_vccz .LBB0_758
	v_max_f32_e32 v123, v123, v123
	v_max_f32_e32 v136, 0, v123
	v_exp_f32_e64 v138, -v136
	v_add_f32_e32 v116, v116, v136
	v_pk_add_f32 v[66:67], v[66:67], v[136:137] op_sel_hi:[1,0] neg_lo:[0,1] neg_hi:[0,1]
	v_pk_add_f32 v[68:69], v[68:69], v[136:137] op_sel_hi:[1,0] neg_lo:[0,1] neg_hi:[0,1]
	v_mul_f32_e32 v34, v34, v138
	v_pk_add_f32 v[70:71], v[70:71], v[136:137] op_sel_hi:[1,0] neg_lo:[0,1] neg_hi:[0,1]
	v_pk_add_f32 v[72:73], v[72:73], v[136:137] op_sel_hi:[1,0] neg_lo:[0,1] neg_hi:[0,1]
	v_pk_add_f32 v[74:75], v[74:75], v[136:137] op_sel_hi:[1,0] neg_lo:[0,1] neg_hi:[0,1]
	v_pk_add_f32 v[76:77], v[76:77], v[136:137] op_sel_hi:[1,0] neg_lo:[0,1] neg_hi:[0,1]
	v_pk_add_f32 v[78:79], v[78:79], v[136:137] op_sel_hi:[1,0] neg_lo:[0,1] neg_hi:[0,1]
	v_pk_add_f32 v[80:81], v[80:81], v[136:137] op_sel_hi:[1,0] neg_lo:[0,1] neg_hi:[0,1]
	v_pk_mul_f32 v[32:33], v[32:33], v[138:139] op_sel_hi:[1,0]
	v_pk_mul_f32 v[30:31], v[30:31], v[138:139] op_sel_hi:[1,0]
	v_pk_mul_f32 v[28:29], v[28:29], v[138:139] op_sel_hi:[1,0]
	v_pk_mul_f32 v[26:27], v[26:27], v[138:139] op_sel_hi:[1,0]
	v_pk_mul_f32 v[24:25], v[24:25], v[138:139] op_sel_hi:[1,0]
	v_pk_mul_f32 v[22:23], v[22:23], v[138:139] op_sel_hi:[1,0]
	v_pk_mul_f32 v[20:21], v[20:21], v[138:139] op_sel_hi:[1,0]
	v_pk_mul_f32 v[18:19], v[18:19], v[138:139] op_sel_hi:[1,0]
	v_pk_mul_f32 v[16:17], v[16:17], v[138:139] op_sel_hi:[1,0]
	v_pk_mul_f32 v[14:15], v[14:15], v[138:139] op_sel_hi:[1,0]
	v_pk_mul_f32 v[12:13], v[12:13], v[138:139] op_sel_hi:[1,0]
	v_pk_mul_f32 v[10:11], v[10:11], v[138:139] op_sel_hi:[1,0]
	v_pk_mul_f32 v[8:9], v[8:9], v[138:139] op_sel_hi:[1,0]
	v_pk_mul_f32 v[6:7], v[6:7], v[138:139] op_sel_hi:[1,0]
	v_pk_mul_f32 v[4:5], v[4:5], v[138:139] op_sel_hi:[1,0]
	v_pk_mul_f32 v[2:3], v[2:3], v[138:139] op_sel_hi:[1,0]

.LBB0_765:
	v_add_u32_e32 v0, s91, v129
	v_add_u32_e32 v117, v0, v130
	v_exp_f32_e32 v50, v50
	v_exp_f32_e32 v51, v51
	v_exp_f32_e32 v52, v52
	v_exp_f32_e32 v53, v53
	ds_read_b64_tr_b16 v[118:119], v117 offset:24576
	ds_read_b64_tr_b16 v[120:121], v117 offset:25600
	v_exp_f32_e32 v54, v54
	v_exp_f32_e32 v55, v55
	v_exp_f32_e32 v56, v56
	v_exp_f32_e32 v57, v57
	v_cvt_pk_bf16_f32 v136, v50, v51
	v_cvt_pk_bf16_f32 v137, v52, v53
	v_cvt_pk_bf16_f32 v138, v54, v55
	v_cvt_pk_bf16_f32 v139, v56, v57
	v_add_u32_e32 v0, v0, v131
	v_exp_f32_e32 v58, v58
	s_waitcnt lgkmcnt(0)
	v_mfma_f32_32x32x16_bf16 v[2:17], v[118:121], v[136:139], v[2:17]
	ds_read_b64_tr_b16 v[118:119], v0 offset:24576
	ds_read_b64_tr_b16 v[120:121], v0 offset:25600
	v_exp_f32_e32 v59, v59
	v_exp_f32_e32 v60, v60
	v_exp_f32_e32 v61, v61
	v_exp_f32_e32 v62, v62
	v_exp_f32_e32 v63, v63
	v_exp_f32_e32 v64, v64
	s_waitcnt lgkmcnt(0)
	v_mfma_f32_32x32x16_bf16 v[18:33], v[118:121], v[136:139], v[18:33]
	ds_read_b64_tr_b16 v[118:119], v117 offset:26624
	ds_read_b64_tr_b16 v[120:121], v117 offset:27648
	v_exp_f32_e32 v65, v65
	v_mfma_f32_32x32x16_bf16 v[34:49], v[84:87], v[136:139], v[34:49]
	v_cvt_pk_bf16_f32 v136, v58, v59
	v_cvt_pk_bf16_f32 v137, v60, v61
	v_cvt_pk_bf16_f32 v138, v62, v63
	v_cvt_pk_bf16_f32 v139, v64, v65
	s_nop 0
	s_nop 0
	s_waitcnt lgkmcnt(0)
	v_mfma_f32_32x32x16_bf16 v[2:17], v[118:121], v[136:139], v[2:17]
	ds_read_b64_tr_b16 v[118:119], v0 offset:26624
	ds_read_b64_tr_b16 v[120:121], v0 offset:27648
	s_waitcnt lgkmcnt(0)
	v_mfma_f32_32x32x16_bf16 v[18:33], v[118:121], v[136:139], v[18:33]
	v_max_f32_e32 v118, v66, v67
	v_max3_f32 v118, v118, v68, v69
	v_max3_f32 v118, v118, v70, v71
	v_max3_f32 v118, v118, v72, v73
	v_max3_f32 v118, v118, v74, v75
	v_max3_f32 v118, v118, v76, v77
	v_mfma_f32_32x32x16_bf16 v[34:49], v[84:87], v[136:139], v[34:49]
	v_max3_f32 v118, v118, v78, v79
	v_max3_f32 v118, v118, v80, v81
	v_mov_b32_e32 v119, v118
	s_nop 1
	v_permlane32_swap_b32_e32 v118, v119
	v_max_f32_e32 v118, v118, v119
	v_cmp_lt_f32_e32 vcc, s95, v118
	s_cbranch_vccz .LBB0_767
	v_max_f32_e32 v118, v118, v118
	v_max_f32_e32 v118, 0, v118
	v_exp_f32_e64 v120, -v118
	v_add_f32_e32 v116, v116, v118
	v_pk_add_f32 v[66:67], v[66:67], v[118:119] op_sel_hi:[1,0] neg_lo:[0,1] neg_hi:[0,1]
	v_pk_add_f32 v[68:69], v[68:69], v[118:119] op_sel_hi:[1,0] neg_lo:[0,1] neg_hi:[0,1]
	v_mul_f32_e32 v34, v34, v120
	v_pk_add_f32 v[70:71], v[70:71], v[118:119] op_sel_hi:[1,0] neg_lo:[0,1] neg_hi:[0,1]
	v_pk_add_f32 v[72:73], v[72:73], v[118:119] op_sel_hi:[1,0] neg_lo:[0,1] neg_hi:[0,1]
	v_pk_add_f32 v[74:75], v[74:75], v[118:119] op_sel_hi:[1,0] neg_lo:[0,1] neg_hi:[0,1]
	v_pk_add_f32 v[76:77], v[76:77], v[118:119] op_sel_hi:[1,0] neg_lo:[0,1] neg_hi:[0,1]
	v_pk_add_f32 v[78:79], v[78:79], v[118:119] op_sel_hi:[1,0] neg_lo:[0,1] neg_hi:[0,1]
	v_pk_add_f32 v[80:81], v[80:81], v[118:119] op_sel_hi:[1,0] neg_lo:[0,1] neg_hi:[0,1]
	v_pk_mul_f32 v[32:33], v[32:33], v[120:121] op_sel_hi:[1,0]
	v_pk_mul_f32 v[30:31], v[30:31], v[120:121] op_sel_hi:[1,0]
	v_pk_mul_f32 v[28:29], v[28:29], v[120:121] op_sel_hi:[1,0]
	v_pk_mul_f32 v[26:27], v[26:27], v[120:121] op_sel_hi:[1,0]
	v_pk_mul_f32 v[24:25], v[24:25], v[120:121] op_sel_hi:[1,0]
	v_pk_mul_f32 v[22:23], v[22:23], v[120:121] op_sel_hi:[1,0]
	v_pk_mul_f32 v[20:21], v[20:21], v[120:121] op_sel_hi:[1,0]
	v_pk_mul_f32 v[18:19], v[18:19], v[120:121] op_sel_hi:[1,0]
	v_pk_mul_f32 v[16:17], v[16:17], v[120:121] op_sel_hi:[1,0]
	v_pk_mul_f32 v[14:15], v[14:15], v[120:121] op_sel_hi:[1,0]
	v_pk_mul_f32 v[12:13], v[12:13], v[120:121] op_sel_hi:[1,0]
	v_pk_mul_f32 v[10:11], v[10:11], v[120:121] op_sel_hi:[1,0]
	v_pk_mul_f32 v[8:9], v[8:9], v[120:121] op_sel_hi:[1,0]
	v_pk_mul_f32 v[6:7], v[6:7], v[120:121] op_sel_hi:[1,0]
	v_pk_mul_f32 v[4:5], v[4:5], v[120:121] op_sel_hi:[1,0]
	v_pk_mul_f32 v[2:3], v[2:3], v[120:121] op_sel_hi:[1,0]

.LBB0_784:
	v_add_u32_e32 v142, s91, v129
	v_add_u32_e32 v143, v142, v130
	v_exp_f32_e32 v52, v52
	v_exp_f32_e32 v53, v53
	v_exp_f32_e32 v54, v54
	v_exp_f32_e32 v55, v55
	ds_read_b64_tr_b16 v[144:145], v143 offset:16384
	ds_read_b64_tr_b16 v[146:147], v143 offset:17408
	v_exp_f32_e32 v56, v56
	v_exp_f32_e32 v57, v57
	v_exp_f32_e32 v58, v58
	v_exp_f32_e32 v59, v59
	v_cvt_pk_bf16_f32 v148, v52, v53
	v_cvt_pk_bf16_f32 v149, v54, v55
	v_cvt_pk_bf16_f32 v150, v56, v57
	v_cvt_pk_bf16_f32 v151, v58, v59
	v_add_u32_e32 v142, v142, v131
	v_exp_f32_e32 v60, v60
	s_waitcnt lgkmcnt(0)
	v_mfma_f32_32x32x16_bf16 v[4:19], v[144:147], v[148:151], v[4:19]
	ds_read_b64_tr_b16 v[144:145], v142 offset:16384
	ds_read_b64_tr_b16 v[146:147], v142 offset:17408
	v_exp_f32_e32 v61, v61
	v_exp_f32_e32 v62, v62
	v_exp_f32_e32 v63, v63
	v_exp_f32_e32 v64, v64
	v_exp_f32_e32 v65, v65
	v_exp_f32_e32 v66, v66
	s_waitcnt lgkmcnt(0)
	v_mfma_f32_32x32x16_bf16 v[20:35], v[144:147], v[148:151], v[20:35]
	ds_read_b64_tr_b16 v[144:145], v143 offset:18432
	ds_read_b64_tr_b16 v[146:147], v143 offset:19456
	v_exp_f32_e32 v67, v67
	v_mfma_f32_32x32x16_bf16 v[36:51], v[84:87], v[148:151], v[36:51]
	v_cvt_pk_bf16_f32 v148, v60, v61
	v_cvt_pk_bf16_f32 v149, v62, v63
	v_cvt_pk_bf16_f32 v150, v64, v65
	v_cvt_pk_bf16_f32 v151, v66, v67
	s_nop 0
	s_nop 0
	s_waitcnt lgkmcnt(0)
	v_mfma_f32_32x32x16_bf16 v[4:19], v[144:147], v[148:151], v[4:19]
	ds_read_b64_tr_b16 v[144:145], v142 offset:18432
	ds_read_b64_tr_b16 v[146:147], v142 offset:19456
	s_waitcnt lgkmcnt(0)
	v_mfma_f32_32x32x16_bf16 v[20:35], v[144:147], v[148:151], v[20:35]
	v_max_f32_e32 v144, v68, v69
	v_max3_f32 v144, v144, v70, v71
	v_max3_f32 v144, v144, v72, v73
	v_max3_f32 v144, v144, v74, v75
	v_max3_f32 v144, v144, v76, v77
	v_max3_f32 v144, v144, v78, v79
	v_mfma_f32_32x32x16_bf16 v[36:51], v[84:87], v[148:151], v[36:51]
	v_max3_f32 v144, v144, v80, v81
	v_max3_f32 v144, v144, v82, v83
	v_mov_b32_e32 v145, v144
	s_nop 1
	v_permlane32_swap_b32_e32 v144, v145
	v_max_f32_e32 v144, v144, v145
	v_cmp_lt_f32_e32 vcc, s94, v144
	s_cbranch_vccz .LBB0_786
	v_max_f32_e32 v144, v144, v144
	v_max_f32_e32 v144, 0, v144
	v_exp_f32_e64 v146, -v144
	v_add_f32_e32 v137, v137, v144
	v_pk_add_f32 v[68:69], v[68:69], v[144:145] op_sel_hi:[1,0] neg_lo:[0,1] neg_hi:[0,1]
	v_pk_add_f32 v[70:71], v[70:71], v[144:145] op_sel_hi:[1,0] neg_lo:[0,1] neg_hi:[0,1]
	v_mul_f32_e32 v36, v36, v146
	v_pk_add_f32 v[72:73], v[72:73], v[144:145] op_sel_hi:[1,0] neg_lo:[0,1] neg_hi:[0,1]
	v_pk_add_f32 v[74:75], v[74:75], v[144:145] op_sel_hi:[1,0] neg_lo:[0,1] neg_hi:[0,1]
	v_pk_add_f32 v[76:77], v[76:77], v[144:145] op_sel_hi:[1,0] neg_lo:[0,1] neg_hi:[0,1]
	v_pk_add_f32 v[78:79], v[78:79], v[144:145] op_sel_hi:[1,0] neg_lo:[0,1] neg_hi:[0,1]
	v_pk_add_f32 v[80:81], v[80:81], v[144:145] op_sel_hi:[1,0] neg_lo:[0,1] neg_hi:[0,1]
	v_pk_add_f32 v[82:83], v[82:83], v[144:145] op_sel_hi:[1,0] neg_lo:[0,1] neg_hi:[0,1]
	v_pk_mul_f32 v[34:35], v[34:35], v[146:147] op_sel_hi:[1,0]
	v_pk_mul_f32 v[32:33], v[32:33], v[146:147] op_sel_hi:[1,0]
	v_pk_mul_f32 v[30:31], v[30:31], v[146:147] op_sel_hi:[1,0]
	v_pk_mul_f32 v[28:29], v[28:29], v[146:147] op_sel_hi:[1,0]
	v_pk_mul_f32 v[26:27], v[26:27], v[146:147] op_sel_hi:[1,0]
	v_pk_mul_f32 v[24:25], v[24:25], v[146:147] op_sel_hi:[1,0]
	v_pk_mul_f32 v[22:23], v[22:23], v[146:147] op_sel_hi:[1,0]
	v_pk_mul_f32 v[20:21], v[20:21], v[146:147] op_sel_hi:[1,0]
	v_pk_mul_f32 v[18:19], v[18:19], v[146:147] op_sel_hi:[1,0]
	v_pk_mul_f32 v[16:17], v[16:17], v[146:147] op_sel_hi:[1,0]
	v_pk_mul_f32 v[14:15], v[14:15], v[146:147] op_sel_hi:[1,0]
	v_pk_mul_f32 v[12:13], v[12:13], v[146:147] op_sel_hi:[1,0]
	v_pk_mul_f32 v[10:11], v[10:11], v[146:147] op_sel_hi:[1,0]
	v_pk_mul_f32 v[8:9], v[8:9], v[146:147] op_sel_hi:[1,0]
	v_pk_mul_f32 v[6:7], v[6:7], v[146:147] op_sel_hi:[1,0]
	v_pk_mul_f32 v[4:5], v[4:5], v[146:147] op_sel_hi:[1,0]

.LBB0_793:
	v_add_u32_e32 v2, s91, v129
	v_add_u32_e32 v138, v2, v130
	v_exp_f32_e32 v52, v52
	v_exp_f32_e32 v53, v53
	v_exp_f32_e32 v54, v54
	v_exp_f32_e32 v55, v55
	ds_read_b64_tr_b16 v[140:141], v138 offset:24576
	ds_read_b64_tr_b16 v[142:143], v138 offset:25600
	v_exp_f32_e32 v56, v56
	v_exp_f32_e32 v57, v57
	v_exp_f32_e32 v58, v58
	v_exp_f32_e32 v59, v59
	v_cvt_pk_bf16_f32 v144, v52, v53
	v_cvt_pk_bf16_f32 v145, v54, v55
	v_cvt_pk_bf16_f32 v146, v56, v57
	v_cvt_pk_bf16_f32 v147, v58, v59
	v_add_u32_e32 v2, v2, v131
	v_exp_f32_e32 v60, v60
	s_waitcnt lgkmcnt(0)
	v_mfma_f32_32x32x16_bf16 v[4:19], v[140:143], v[144:147], v[4:19]
	ds_read_b64_tr_b16 v[140:141], v2 offset:24576
	ds_read_b64_tr_b16 v[142:143], v2 offset:25600
	v_exp_f32_e32 v61, v61
	v_exp_f32_e32 v62, v62
	v_exp_f32_e32 v63, v63
	v_exp_f32_e32 v64, v64
	v_exp_f32_e32 v65, v65
	v_exp_f32_e32 v66, v66
	s_waitcnt lgkmcnt(0)
	v_mfma_f32_32x32x16_bf16 v[20:35], v[140:143], v[144:147], v[20:35]
	ds_read_b64_tr_b16 v[140:141], v138 offset:26624
	ds_read_b64_tr_b16 v[142:143], v138 offset:27648
	v_exp_f32_e32 v67, v67
	v_max_f32_e32 v139, v69, v69
	v_mfma_f32_32x32x16_bf16 v[36:51], v[84:87], v[144:147], v[36:51]
	v_cvt_pk_bf16_f32 v144, v60, v61
	v_cvt_pk_bf16_f32 v145, v62, v63
	v_cvt_pk_bf16_f32 v146, v64, v65
	v_cvt_pk_bf16_f32 v147, v66, v67
	s_nop 0
	s_nop 0
	s_waitcnt lgkmcnt(0)
	v_mfma_f32_32x32x16_bf16 v[4:19], v[140:143], v[144:147], v[4:19]
	ds_read_b64_tr_b16 v[140:141], v2 offset:26624
	ds_read_b64_tr_b16 v[142:143], v2 offset:27648
	s_waitcnt lgkmcnt(0)
	v_mfma_f32_32x32x16_bf16 v[20:35], v[140:143], v[144:147], v[20:35]
	v_max_f32_e32 v140, v68, v68
	v_max_f32_e32 v139, v140, v139
	v_max3_f32 v139, v139, v70, v71
	v_max3_f32 v139, v139, v72, v73
	v_max3_f32 v139, v139, v74, v75
	v_max3_f32 v139, v139, v76, v77
	v_max3_f32 v139, v139, v78, v79
	v_mfma_f32_32x32x16_bf16 v[36:51], v[84:87], v[144:147], v[36:51]
	v_max3_f32 v139, v139, v80, v81
	v_max3_f32 v139, v139, v82, v83
	v_mov_b32_e32 v140, v139
	s_nop 1
	v_permlane32_swap_b32_e32 v139, v140
	v_max_f32_e32 v139, v139, v140
	v_cmp_lt_f32_e32 vcc, s94, v139
	s_cbranch_vccz .LBB0_795
	v_max_f32_e32 v139, v139, v139
	v_max_f32_e32 v140, 0, v139
	v_exp_f32_e64 v142, -v140
	v_add_f32_e32 v137, v137, v140
	v_pk_add_f32 v[68:69], v[68:69], v[140:141] op_sel_hi:[1,0] neg_lo:[0,1] neg_hi:[0,1]
	v_pk_add_f32 v[70:71], v[70:71], v[140:141] op_sel_hi:[1,0] neg_lo:[0,1] neg_hi:[0,1]
	v_mul_f32_e32 v36, v36, v142
	v_pk_add_f32 v[72:73], v[72:73], v[140:141] op_sel_hi:[1,0] neg_lo:[0,1] neg_hi:[0,1]
	v_pk_add_f32 v[74:75], v[74:75], v[140:141] op_sel_hi:[1,0] neg_lo:[0,1] neg_hi:[0,1]
	v_pk_add_f32 v[76:77], v[76:77], v[140:141] op_sel_hi:[1,0] neg_lo:[0,1] neg_hi:[0,1]
	v_pk_add_f32 v[78:79], v[78:79], v[140:141] op_sel_hi:[1,0] neg_lo:[0,1] neg_hi:[0,1]
	v_pk_add_f32 v[80:81], v[80:81], v[140:141] op_sel_hi:[1,0] neg_lo:[0,1] neg_hi:[0,1]
	v_pk_add_f32 v[82:83], v[82:83], v[140:141] op_sel_hi:[1,0] neg_lo:[0,1] neg_hi:[0,1]
	v_pk_mul_f32 v[34:35], v[34:35], v[142:143] op_sel_hi:[1,0]
	v_pk_mul_f32 v[32:33], v[32:33], v[142:143] op_sel_hi:[1,0]
	v_pk_mul_f32 v[30:31], v[30:31], v[142:143] op_sel_hi:[1,0]
	v_pk_mul_f32 v[28:29], v[28:29], v[142:143] op_sel_hi:[1,0]
	v_pk_mul_f32 v[26:27], v[26:27], v[142:143] op_sel_hi:[1,0]
	v_pk_mul_f32 v[24:25], v[24:25], v[142:143] op_sel_hi:[1,0]
	v_pk_mul_f32 v[22:23], v[22:23], v[142:143] op_sel_hi:[1,0]
	v_pk_mul_f32 v[20:21], v[20:21], v[142:143] op_sel_hi:[1,0]
	v_pk_mul_f32 v[18:19], v[18:19], v[142:143] op_sel_hi:[1,0]
	v_pk_mul_f32 v[16:17], v[16:17], v[142:143] op_sel_hi:[1,0]
	v_pk_mul_f32 v[14:15], v[14:15], v[142:143] op_sel_hi:[1,0]
	v_pk_mul_f32 v[12:13], v[12:13], v[142:143] op_sel_hi:[1,0]
	v_pk_mul_f32 v[10:11], v[10:11], v[142:143] op_sel_hi:[1,0]
	v_pk_mul_f32 v[8:9], v[8:9], v[142:143] op_sel_hi:[1,0]
	v_pk_mul_f32 v[6:7], v[6:7], v[142:143] op_sel_hi:[1,0]
	v_pk_mul_f32 v[4:5], v[4:5], v[142:143] op_sel_hi:[1,0]

.LBB0_812:
	v_add_u32_e32 v142, s95, v129
	v_add_u32_e32 v143, v142, v130
	v_exp_f32_e32 v52, v52
	v_exp_f32_e32 v53, v53
	v_exp_f32_e32 v54, v54
	v_exp_f32_e32 v55, v55
	ds_read_b64_tr_b16 v[144:145], v143 offset:16384
	ds_read_b64_tr_b16 v[146:147], v143 offset:17408
	v_exp_f32_e32 v56, v56
	v_exp_f32_e32 v57, v57
	v_exp_f32_e32 v58, v58
	v_exp_f32_e32 v59, v59
	v_cvt_pk_bf16_f32 v148, v52, v53
	v_cvt_pk_bf16_f32 v149, v54, v55
	v_cvt_pk_bf16_f32 v150, v56, v57
	v_cvt_pk_bf16_f32 v151, v58, v59
	v_add_u32_e32 v142, v142, v131
	v_exp_f32_e32 v60, v60
	s_waitcnt lgkmcnt(0)
	v_mfma_f32_32x32x16_bf16 v[4:19], v[144:147], v[148:151], v[4:19]
	ds_read_b64_tr_b16 v[144:145], v142 offset:16384
	ds_read_b64_tr_b16 v[146:147], v142 offset:17408
	v_exp_f32_e32 v61, v61
	v_exp_f32_e32 v62, v62
	v_exp_f32_e32 v63, v63
	v_exp_f32_e32 v64, v64
	v_exp_f32_e32 v65, v65
	v_exp_f32_e32 v66, v66
	s_waitcnt lgkmcnt(0)
	v_mfma_f32_32x32x16_bf16 v[20:35], v[144:147], v[148:151], v[20:35]
	ds_read_b64_tr_b16 v[144:145], v143 offset:18432
	ds_read_b64_tr_b16 v[146:147], v143 offset:19456
	v_exp_f32_e32 v67, v67
	v_mfma_f32_32x32x16_bf16 v[36:51], v[84:87], v[148:151], v[36:51]
	v_cvt_pk_bf16_f32 v148, v60, v61
	v_cvt_pk_bf16_f32 v149, v62, v63
	v_cvt_pk_bf16_f32 v150, v64, v65
	v_cvt_pk_bf16_f32 v151, v66, v67
	s_nop 0
	s_nop 0
	s_waitcnt lgkmcnt(0)
	v_mfma_f32_32x32x16_bf16 v[4:19], v[144:147], v[148:151], v[4:19]
	ds_read_b64_tr_b16 v[144:145], v142 offset:18432
	ds_read_b64_tr_b16 v[146:147], v142 offset:19456
	s_waitcnt lgkmcnt(0)
	v_mfma_f32_32x32x16_bf16 v[20:35], v[144:147], v[148:151], v[20:35]
	v_max_f32_e32 v144, v68, v69
	v_max3_f32 v144, v144, v70, v71
	v_max3_f32 v144, v144, v72, v73
	v_max3_f32 v144, v144, v74, v75
	v_max3_f32 v144, v144, v76, v77
	v_max3_f32 v144, v144, v78, v79
	v_mfma_f32_32x32x16_bf16 v[36:51], v[84:87], v[148:151], v[36:51]
	v_max3_f32 v144, v144, v80, v81
	v_max3_f32 v144, v144, v82, v83
	v_mov_b32_e32 v145, v144
	s_nop 1
	v_permlane32_swap_b32_e32 v144, v145
	v_max_f32_e32 v144, v144, v145
	v_cmp_lt_f32_e32 vcc, s94, v144
	s_cbranch_vccz .LBB0_814
	v_max_f32_e32 v144, v144, v144
	v_max_f32_e32 v144, 0, v144
	v_exp_f32_e64 v146, -v144
	v_add_f32_e32 v137, v137, v144
	v_pk_add_f32 v[68:69], v[68:69], v[144:145] op_sel_hi:[1,0] neg_lo:[0,1] neg_hi:[0,1]
	v_pk_add_f32 v[70:71], v[70:71], v[144:145] op_sel_hi:[1,0] neg_lo:[0,1] neg_hi:[0,1]
	v_mul_f32_e32 v36, v36, v146
	v_pk_add_f32 v[72:73], v[72:73], v[144:145] op_sel_hi:[1,0] neg_lo:[0,1] neg_hi:[0,1]
	v_pk_add_f32 v[74:75], v[74:75], v[144:145] op_sel_hi:[1,0] neg_lo:[0,1] neg_hi:[0,1]
	v_pk_add_f32 v[76:77], v[76:77], v[144:145] op_sel_hi:[1,0] neg_lo:[0,1] neg_hi:[0,1]
	v_pk_add_f32 v[78:79], v[78:79], v[144:145] op_sel_hi:[1,0] neg_lo:[0,1] neg_hi:[0,1]
	v_pk_add_f32 v[80:81], v[80:81], v[144:145] op_sel_hi:[1,0] neg_lo:[0,1] neg_hi:[0,1]
	v_pk_add_f32 v[82:83], v[82:83], v[144:145] op_sel_hi:[1,0] neg_lo:[0,1] neg_hi:[0,1]
	v_pk_mul_f32 v[34:35], v[34:35], v[146:147] op_sel_hi:[1,0]
	v_pk_mul_f32 v[32:33], v[32:33], v[146:147] op_sel_hi:[1,0]
	v_pk_mul_f32 v[30:31], v[30:31], v[146:147] op_sel_hi:[1,0]
	v_pk_mul_f32 v[28:29], v[28:29], v[146:147] op_sel_hi:[1,0]
	v_pk_mul_f32 v[26:27], v[26:27], v[146:147] op_sel_hi:[1,0]
	v_pk_mul_f32 v[24:25], v[24:25], v[146:147] op_sel_hi:[1,0]
	v_pk_mul_f32 v[22:23], v[22:23], v[146:147] op_sel_hi:[1,0]
	v_pk_mul_f32 v[20:21], v[20:21], v[146:147] op_sel_hi:[1,0]
	v_pk_mul_f32 v[18:19], v[18:19], v[146:147] op_sel_hi:[1,0]
	v_pk_mul_f32 v[16:17], v[16:17], v[146:147] op_sel_hi:[1,0]
	v_pk_mul_f32 v[14:15], v[14:15], v[146:147] op_sel_hi:[1,0]
	v_pk_mul_f32 v[12:13], v[12:13], v[146:147] op_sel_hi:[1,0]
	v_pk_mul_f32 v[10:11], v[10:11], v[146:147] op_sel_hi:[1,0]
	v_pk_mul_f32 v[8:9], v[8:9], v[146:147] op_sel_hi:[1,0]
	v_pk_mul_f32 v[6:7], v[6:7], v[146:147] op_sel_hi:[1,0]
	v_pk_mul_f32 v[4:5], v[4:5], v[146:147] op_sel_hi:[1,0]

.LBB0_821:
	v_add_u32_e32 v2, s95, v129
	v_add_u32_e32 v138, v2, v130
	v_exp_f32_e32 v52, v52
	v_exp_f32_e32 v53, v53
	v_exp_f32_e32 v54, v54
	v_exp_f32_e32 v55, v55
	ds_read_b64_tr_b16 v[140:141], v138 offset:24576
	ds_read_b64_tr_b16 v[142:143], v138 offset:25600
	v_exp_f32_e32 v56, v56
	v_exp_f32_e32 v57, v57
	v_exp_f32_e32 v58, v58
	v_exp_f32_e32 v59, v59
	v_cvt_pk_bf16_f32 v144, v52, v53
	v_cvt_pk_bf16_f32 v145, v54, v55
	v_cvt_pk_bf16_f32 v146, v56, v57
	v_cvt_pk_bf16_f32 v147, v58, v59
	v_add_u32_e32 v2, v2, v131
	v_exp_f32_e32 v60, v60
	s_waitcnt lgkmcnt(0)
	v_mfma_f32_32x32x16_bf16 v[4:19], v[140:143], v[144:147], v[4:19]
	ds_read_b64_tr_b16 v[140:141], v2 offset:24576
	ds_read_b64_tr_b16 v[142:143], v2 offset:25600
	v_exp_f32_e32 v61, v61
	v_exp_f32_e32 v62, v62
	v_exp_f32_e32 v63, v63
	v_exp_f32_e32 v64, v64
	v_exp_f32_e32 v65, v65
	v_exp_f32_e32 v66, v66
	s_waitcnt lgkmcnt(0)
	v_mfma_f32_32x32x16_bf16 v[20:35], v[140:143], v[144:147], v[20:35]
	ds_read_b64_tr_b16 v[140:141], v138 offset:26624
	ds_read_b64_tr_b16 v[142:143], v138 offset:27648
	v_exp_f32_e32 v67, v67
	v_max_f32_e32 v139, v69, v69
	v_mfma_f32_32x32x16_bf16 v[36:51], v[84:87], v[144:147], v[36:51]
	v_cvt_pk_bf16_f32 v144, v60, v61
	v_cvt_pk_bf16_f32 v145, v62, v63
	v_cvt_pk_bf16_f32 v146, v64, v65
	v_cvt_pk_bf16_f32 v147, v66, v67
	s_nop 0
	s_nop 0
	s_waitcnt lgkmcnt(0)
	v_mfma_f32_32x32x16_bf16 v[4:19], v[140:143], v[144:147], v[4:19]
	ds_read_b64_tr_b16 v[140:141], v2 offset:26624
	ds_read_b64_tr_b16 v[142:143], v2 offset:27648
	s_waitcnt lgkmcnt(0)
	v_mfma_f32_32x32x16_bf16 v[20:35], v[140:143], v[144:147], v[20:35]
	v_max_f32_e32 v140, v68, v68
	v_max_f32_e32 v139, v140, v139
	v_max3_f32 v139, v139, v70, v71
	v_max3_f32 v139, v139, v72, v73
	v_max3_f32 v139, v139, v74, v75
	v_max3_f32 v139, v139, v76, v77
	v_max3_f32 v139, v139, v78, v79
	v_mfma_f32_32x32x16_bf16 v[36:51], v[84:87], v[144:147], v[36:51]
	v_max3_f32 v139, v139, v80, v81
	v_max3_f32 v139, v139, v82, v83
	v_mov_b32_e32 v140, v139
	s_nop 1
	v_permlane32_swap_b32_e32 v139, v140
	v_max_f32_e32 v139, v139, v140
	v_cmp_lt_f32_e32 vcc, s94, v139
	s_cbranch_vccz .LBB0_823
	v_max_f32_e32 v139, v139, v139
	v_max_f32_e32 v140, 0, v139
	v_exp_f32_e64 v142, -v140
	v_add_f32_e32 v137, v137, v140
	v_pk_add_f32 v[68:69], v[68:69], v[140:141] op_sel_hi:[1,0] neg_lo:[0,1] neg_hi:[0,1]
	v_pk_add_f32 v[70:71], v[70:71], v[140:141] op_sel_hi:[1,0] neg_lo:[0,1] neg_hi:[0,1]
	v_mul_f32_e32 v36, v36, v142
	v_pk_add_f32 v[72:73], v[72:73], v[140:141] op_sel_hi:[1,0] neg_lo:[0,1] neg_hi:[0,1]
	v_pk_add_f32 v[74:75], v[74:75], v[140:141] op_sel_hi:[1,0] neg_lo:[0,1] neg_hi:[0,1]
	v_pk_add_f32 v[76:77], v[76:77], v[140:141] op_sel_hi:[1,0] neg_lo:[0,1] neg_hi:[0,1]
	v_pk_add_f32 v[78:79], v[78:79], v[140:141] op_sel_hi:[1,0] neg_lo:[0,1] neg_hi:[0,1]
	v_pk_add_f32 v[80:81], v[80:81], v[140:141] op_sel_hi:[1,0] neg_lo:[0,1] neg_hi:[0,1]
	v_pk_add_f32 v[82:83], v[82:83], v[140:141] op_sel_hi:[1,0] neg_lo:[0,1] neg_hi:[0,1]
	v_pk_mul_f32 v[34:35], v[34:35], v[142:143] op_sel_hi:[1,0]
	v_pk_mul_f32 v[32:33], v[32:33], v[142:143] op_sel_hi:[1,0]
	v_pk_mul_f32 v[30:31], v[30:31], v[142:143] op_sel_hi:[1,0]
	v_pk_mul_f32 v[28:29], v[28:29], v[142:143] op_sel_hi:[1,0]
	v_pk_mul_f32 v[26:27], v[26:27], v[142:143] op_sel_hi:[1,0]
	v_pk_mul_f32 v[24:25], v[24:25], v[142:143] op_sel_hi:[1,0]
	v_pk_mul_f32 v[22:23], v[22:23], v[142:143] op_sel_hi:[1,0]
	v_pk_mul_f32 v[20:21], v[20:21], v[142:143] op_sel_hi:[1,0]
	v_pk_mul_f32 v[18:19], v[18:19], v[142:143] op_sel_hi:[1,0]
	v_pk_mul_f32 v[16:17], v[16:17], v[142:143] op_sel_hi:[1,0]
	v_pk_mul_f32 v[14:15], v[14:15], v[142:143] op_sel_hi:[1,0]
	v_pk_mul_f32 v[12:13], v[12:13], v[142:143] op_sel_hi:[1,0]
	v_pk_mul_f32 v[10:11], v[10:11], v[142:143] op_sel_hi:[1,0]
	v_pk_mul_f32 v[8:9], v[8:9], v[142:143] op_sel_hi:[1,0]
	v_pk_mul_f32 v[6:7], v[6:7], v[142:143] op_sel_hi:[1,0]
	v_pk_mul_f32 v[4:5], v[4:5], v[142:143] op_sel_hi:[1,0]

.LBB0_840:
	v_add_u32_e32 v142, s91, v129
	v_add_u32_e32 v143, v142, v130
	v_exp_f32_e32 v52, v52
	v_exp_f32_e32 v53, v53
	v_exp_f32_e32 v54, v54
	v_exp_f32_e32 v55, v55
	ds_read_b64_tr_b16 v[144:145], v143 offset:16384
	ds_read_b64_tr_b16 v[146:147], v143 offset:17408
	v_exp_f32_e32 v56, v56
	v_exp_f32_e32 v57, v57
	v_exp_f32_e32 v58, v58
	v_exp_f32_e32 v59, v59
	v_cvt_pk_bf16_f32 v148, v52, v53
	v_cvt_pk_bf16_f32 v149, v54, v55
	v_cvt_pk_bf16_f32 v150, v56, v57
	v_cvt_pk_bf16_f32 v151, v58, v59
	v_add_u32_e32 v142, v142, v131
	v_exp_f32_e32 v60, v60
	s_waitcnt lgkmcnt(0)
	v_mfma_f32_32x32x16_bf16 v[4:19], v[144:147], v[148:151], v[4:19]
	ds_read_b64_tr_b16 v[144:145], v142 offset:16384
	ds_read_b64_tr_b16 v[146:147], v142 offset:17408
	v_exp_f32_e32 v61, v61
	v_exp_f32_e32 v62, v62
	v_exp_f32_e32 v63, v63
	v_exp_f32_e32 v64, v64
	v_exp_f32_e32 v65, v65
	v_exp_f32_e32 v66, v66
	s_waitcnt lgkmcnt(0)
	v_mfma_f32_32x32x16_bf16 v[20:35], v[144:147], v[148:151], v[20:35]
	ds_read_b64_tr_b16 v[144:145], v143 offset:18432
	ds_read_b64_tr_b16 v[146:147], v143 offset:19456
	v_exp_f32_e32 v67, v67
	v_mfma_f32_32x32x16_bf16 v[36:51], v[84:87], v[148:151], v[36:51]
	v_cvt_pk_bf16_f32 v148, v60, v61
	v_cvt_pk_bf16_f32 v149, v62, v63
	v_cvt_pk_bf16_f32 v150, v64, v65
	v_cvt_pk_bf16_f32 v151, v66, v67
	s_nop 0
	s_nop 0
	s_waitcnt lgkmcnt(0)
	v_mfma_f32_32x32x16_bf16 v[4:19], v[144:147], v[148:151], v[4:19]
	ds_read_b64_tr_b16 v[144:145], v142 offset:18432
	ds_read_b64_tr_b16 v[146:147], v142 offset:19456
	s_waitcnt lgkmcnt(0)
	v_mfma_f32_32x32x16_bf16 v[20:35], v[144:147], v[148:151], v[20:35]
	v_max_f32_e32 v144, v68, v69
	v_max3_f32 v144, v144, v70, v71
	v_max3_f32 v144, v144, v72, v73
	v_max3_f32 v144, v144, v74, v75
	v_max3_f32 v144, v144, v76, v77
	v_max3_f32 v144, v144, v78, v79
	v_mfma_f32_32x32x16_bf16 v[36:51], v[84:87], v[148:151], v[36:51]
	v_max3_f32 v144, v144, v80, v81
	v_max3_f32 v144, v144, v82, v83
	v_mov_b32_e32 v145, v144
	s_nop 1
	v_permlane32_swap_b32_e32 v144, v145
	v_max_f32_e32 v144, v144, v145
	v_cmp_lt_f32_e32 vcc, s95, v144
	s_cbranch_vccz .LBB0_842
	v_max_f32_e32 v144, v144, v144
	v_max_f32_e32 v144, 0, v144
	v_exp_f32_e64 v146, -v144
	v_add_f32_e32 v137, v137, v144
	v_pk_add_f32 v[68:69], v[68:69], v[144:145] op_sel_hi:[1,0] neg_lo:[0,1] neg_hi:[0,1]
	v_pk_add_f32 v[70:71], v[70:71], v[144:145] op_sel_hi:[1,0] neg_lo:[0,1] neg_hi:[0,1]
	v_mul_f32_e32 v36, v36, v146
	v_pk_add_f32 v[72:73], v[72:73], v[144:145] op_sel_hi:[1,0] neg_lo:[0,1] neg_hi:[0,1]
	v_pk_add_f32 v[74:75], v[74:75], v[144:145] op_sel_hi:[1,0] neg_lo:[0,1] neg_hi:[0,1]
	v_pk_add_f32 v[76:77], v[76:77], v[144:145] op_sel_hi:[1,0] neg_lo:[0,1] neg_hi:[0,1]
	v_pk_add_f32 v[78:79], v[78:79], v[144:145] op_sel_hi:[1,0] neg_lo:[0,1] neg_hi:[0,1]
	v_pk_add_f32 v[80:81], v[80:81], v[144:145] op_sel_hi:[1,0] neg_lo:[0,1] neg_hi:[0,1]
	v_pk_add_f32 v[82:83], v[82:83], v[144:145] op_sel_hi:[1,0] neg_lo:[0,1] neg_hi:[0,1]
	v_pk_mul_f32 v[34:35], v[34:35], v[146:147] op_sel_hi:[1,0]
	v_pk_mul_f32 v[32:33], v[32:33], v[146:147] op_sel_hi:[1,0]
	v_pk_mul_f32 v[30:31], v[30:31], v[146:147] op_sel_hi:[1,0]
	v_pk_mul_f32 v[28:29], v[28:29], v[146:147] op_sel_hi:[1,0]
	v_pk_mul_f32 v[26:27], v[26:27], v[146:147] op_sel_hi:[1,0]
	v_pk_mul_f32 v[24:25], v[24:25], v[146:147] op_sel_hi:[1,0]
	v_pk_mul_f32 v[22:23], v[22:23], v[146:147] op_sel_hi:[1,0]
	v_pk_mul_f32 v[20:21], v[20:21], v[146:147] op_sel_hi:[1,0]
	v_pk_mul_f32 v[18:19], v[18:19], v[146:147] op_sel_hi:[1,0]
	v_pk_mul_f32 v[16:17], v[16:17], v[146:147] op_sel_hi:[1,0]
	v_pk_mul_f32 v[14:15], v[14:15], v[146:147] op_sel_hi:[1,0]
	v_pk_mul_f32 v[12:13], v[12:13], v[146:147] op_sel_hi:[1,0]
	v_pk_mul_f32 v[10:11], v[10:11], v[146:147] op_sel_hi:[1,0]
	v_pk_mul_f32 v[8:9], v[8:9], v[146:147] op_sel_hi:[1,0]
	v_pk_mul_f32 v[6:7], v[6:7], v[146:147] op_sel_hi:[1,0]
	v_pk_mul_f32 v[4:5], v[4:5], v[146:147] op_sel_hi:[1,0]

.LBB0_849:
	v_add_u32_e32 v2, s91, v129
	v_add_u32_e32 v138, v2, v130
	v_exp_f32_e32 v52, v52
	v_exp_f32_e32 v53, v53
	v_exp_f32_e32 v54, v54
	v_exp_f32_e32 v55, v55
	ds_read_b64_tr_b16 v[140:141], v138 offset:24576
	ds_read_b64_tr_b16 v[142:143], v138 offset:25600
	v_exp_f32_e32 v56, v56
	v_exp_f32_e32 v57, v57
	v_exp_f32_e32 v58, v58
	v_exp_f32_e32 v59, v59
	v_cvt_pk_bf16_f32 v144, v52, v53
	v_cvt_pk_bf16_f32 v145, v54, v55
	v_cvt_pk_bf16_f32 v146, v56, v57
	v_cvt_pk_bf16_f32 v147, v58, v59
	v_add_u32_e32 v2, v2, v131
	v_exp_f32_e32 v60, v60
	s_waitcnt lgkmcnt(0)
	v_mfma_f32_32x32x16_bf16 v[4:19], v[140:143], v[144:147], v[4:19]
	ds_read_b64_tr_b16 v[140:141], v2 offset:24576
	ds_read_b64_tr_b16 v[142:143], v2 offset:25600
	v_exp_f32_e32 v61, v61
	v_exp_f32_e32 v62, v62
	v_exp_f32_e32 v63, v63
	v_exp_f32_e32 v64, v64
	v_exp_f32_e32 v65, v65
	v_exp_f32_e32 v66, v66
	s_waitcnt lgkmcnt(0)
	v_mfma_f32_32x32x16_bf16 v[20:35], v[140:143], v[144:147], v[20:35]
	ds_read_b64_tr_b16 v[140:141], v138 offset:26624
	ds_read_b64_tr_b16 v[142:143], v138 offset:27648
	v_exp_f32_e32 v67, v67
	v_max_f32_e32 v139, v69, v69
	v_mfma_f32_32x32x16_bf16 v[36:51], v[84:87], v[144:147], v[36:51]
	v_cvt_pk_bf16_f32 v144, v60, v61
	v_cvt_pk_bf16_f32 v145, v62, v63
	v_cvt_pk_bf16_f32 v146, v64, v65
	v_cvt_pk_bf16_f32 v147, v66, v67
	s_nop 0
	s_nop 0
	s_waitcnt lgkmcnt(0)
	v_mfma_f32_32x32x16_bf16 v[4:19], v[140:143], v[144:147], v[4:19]
	ds_read_b64_tr_b16 v[140:141], v2 offset:26624
	ds_read_b64_tr_b16 v[142:143], v2 offset:27648
	s_waitcnt lgkmcnt(0)
	v_mfma_f32_32x32x16_bf16 v[20:35], v[140:143], v[144:147], v[20:35]
	v_max_f32_e32 v140, v68, v68
	v_max_f32_e32 v139, v140, v139
	v_max3_f32 v139, v139, v70, v71
	v_max3_f32 v139, v139, v72, v73
	v_max3_f32 v139, v139, v74, v75
	v_max3_f32 v139, v139, v76, v77
	v_max3_f32 v139, v139, v78, v79
	v_mfma_f32_32x32x16_bf16 v[36:51], v[84:87], v[144:147], v[36:51]
	v_max3_f32 v139, v139, v80, v81
	v_max3_f32 v139, v139, v82, v83
	v_mov_b32_e32 v140, v139
	s_nop 1
	v_permlane32_swap_b32_e32 v139, v140
	v_max_f32_e32 v139, v139, v140
	v_cmp_lt_f32_e32 vcc, s95, v139
	s_cbranch_vccz .LBB0_851
	v_max_f32_e32 v139, v139, v139
	v_max_f32_e32 v140, 0, v139
	v_exp_f32_e64 v142, -v140
	v_add_f32_e32 v137, v137, v140
	v_pk_add_f32 v[68:69], v[68:69], v[140:141] op_sel_hi:[1,0] neg_lo:[0,1] neg_hi:[0,1]
	v_pk_add_f32 v[70:71], v[70:71], v[140:141] op_sel_hi:[1,0] neg_lo:[0,1] neg_hi:[0,1]
	v_mul_f32_e32 v36, v36, v142
	v_pk_add_f32 v[72:73], v[72:73], v[140:141] op_sel_hi:[1,0] neg_lo:[0,1] neg_hi:[0,1]
	v_pk_add_f32 v[74:75], v[74:75], v[140:141] op_sel_hi:[1,0] neg_lo:[0,1] neg_hi:[0,1]
	v_pk_add_f32 v[76:77], v[76:77], v[140:141] op_sel_hi:[1,0] neg_lo:[0,1] neg_hi:[0,1]
	v_pk_add_f32 v[78:79], v[78:79], v[140:141] op_sel_hi:[1,0] neg_lo:[0,1] neg_hi:[0,1]
	v_pk_add_f32 v[80:81], v[80:81], v[140:141] op_sel_hi:[1,0] neg_lo:[0,1] neg_hi:[0,1]
	v_pk_add_f32 v[82:83], v[82:83], v[140:141] op_sel_hi:[1,0] neg_lo:[0,1] neg_hi:[0,1]
	v_pk_mul_f32 v[34:35], v[34:35], v[142:143] op_sel_hi:[1,0]
	v_pk_mul_f32 v[32:33], v[32:33], v[142:143] op_sel_hi:[1,0]
	v_pk_mul_f32 v[30:31], v[30:31], v[142:143] op_sel_hi:[1,0]
	v_pk_mul_f32 v[28:29], v[28:29], v[142:143] op_sel_hi:[1,0]
	v_pk_mul_f32 v[26:27], v[26:27], v[142:143] op_sel_hi:[1,0]
	v_pk_mul_f32 v[24:25], v[24:25], v[142:143] op_sel_hi:[1,0]
	v_pk_mul_f32 v[22:23], v[22:23], v[142:143] op_sel_hi:[1,0]
	v_pk_mul_f32 v[20:21], v[20:21], v[142:143] op_sel_hi:[1,0]
	v_pk_mul_f32 v[18:19], v[18:19], v[142:143] op_sel_hi:[1,0]
	v_pk_mul_f32 v[16:17], v[16:17], v[142:143] op_sel_hi:[1,0]
	v_pk_mul_f32 v[14:15], v[14:15], v[142:143] op_sel_hi:[1,0]
	v_pk_mul_f32 v[12:13], v[12:13], v[142:143] op_sel_hi:[1,0]
	v_pk_mul_f32 v[10:11], v[10:11], v[142:143] op_sel_hi:[1,0]
	v_pk_mul_f32 v[8:9], v[8:9], v[142:143] op_sel_hi:[1,0]
	v_pk_mul_f32 v[6:7], v[6:7], v[142:143] op_sel_hi:[1,0]
	v_pk_mul_f32 v[4:5], v[4:5], v[142:143] op_sel_hi:[1,0]

.LBB0_1759:
	s_setprio 0
	v_readfirstlane_b32 s12, v222
	s_and_b32 s6, s12, 0xffffffc0
	v_or_b32_e32 v0, s6, v145
	v_mul_hi_i32 v1, v0, s16
	v_lshrrev_b32_e32 v2, 31, v1
	v_ashrrev_i32_e32 v1, 2, v1
	v_add_u32_e32 v2, v1, v2
	s_ashr_i32 s10, s21, 9
	v_lshrrev_b32_e32 v163, 1, v2
	s_ashr_i32 s11, s10, 31
	v_mad_u64_u32 v[164:165], s[8:9], v2, s17, v[0:1]
	v_xor_b32_e32 v1, v163, v222
	s_lshl_b64 s[2:3], s[10:11], 13
	v_bfi_b32 v1, -8, v164, v1
	v_cmp_lt_i32_e32 vcc, 15, v1
	v_add_u32_e32 v2, s2, v2
	s_and_saveexec_b64 s[8:9], vcc
	s_xor_b64 s[8:9], exec, s[8:9]
	v_lshl_add_u32 v159, v2, 6, v187
	s_or_saveexec_b64 s[8:9], s[8:9]
	s_bfe_u32 s6, s21, 0x40005
	s_lshl_b32 s13, s6, 7
	v_mov_b32_e32 v153, 0x1000
	s_xor_b64 exec, exec, s[8:9]
	v_lshl_or_b32 v2, v2, 11, s13
	v_add_u32_e32 v159, 0x8000000, v2
	v_mov_b32_e32 v153, 0x20000
	s_or_b64 exec, exec, s[8:9]
	v_add_u32_e32 v2, 0x200, v0
	v_mul_hi_i32 v3, v2, s16
	v_lshrrev_b32_e32 v4, 31, v3
	v_ashrrev_i32_e32 v3, 2, v3
	v_add_u32_e32 v4, v3, v4
	v_mad_u64_u32 v[166:167], s[8:9], v4, s17, v[2:3]
	v_lshrrev_b32_e32 v167, 1, v4
	v_xor_b32_e32 v3, v167, v222
	v_bfi_b32 v3, -8, v166, v3
	v_cmp_lt_i32_e32 vcc, 15, v3
	v_add_u32_e32 v4, s2, v4
	s_and_saveexec_b64 s[8:9], vcc
	s_xor_b64 s[8:9], exec, s[8:9]
	v_lshl_add_u32 v161, v4, 6, v187
	s_or_saveexec_b64 s[8:9], s[8:9]
	v_mov_b32_e32 v155, 0x1000
	s_xor_b64 exec, exec, s[8:9]
	v_lshl_or_b32 v4, v4, 11, s13
	v_add_u32_e32 v161, 0x8000000, v4
	v_mov_b32_e32 v155, 0x20000
	s_or_b64 exec, exec, s[8:9]
	v_add_u32_e32 v4, 0x400, v0
	v_mul_hi_i32 v5, v4, s16
	v_lshrrev_b32_e32 v6, 31, v5
	v_ashrrev_i32_e32 v5, 2, v5
	v_add_u32_e32 v5, v5, v6
	v_mad_u64_u32 v[168:169], s[8:9], v5, s17, v[4:5]
	v_lshrrev_b32_e32 v169, 1, v5
	v_xor_b32_e32 v4, v169, v222
	v_bfi_b32 v4, -8, v168, v4
	v_cmp_lt_i32_e32 vcc, 15, v4
	v_add_u32_e32 v5, s2, v5
	s_and_saveexec_b64 s[8:9], vcc
	s_xor_b64 s[8:9], exec, s[8:9]
	v_lshl_add_u32 v165, v5, 6, v187
	s_or_saveexec_b64 s[8:9], s[8:9]
	v_mov_b32_e32 v157, 0x1000
	s_xor_b64 exec, exec, s[8:9]
	v_lshl_or_b32 v5, v5, 11, s13
	v_add_u32_e32 v165, 0x8000000, v5
	v_mov_b32_e32 v157, 0x20000
	s_or_b64 exec, exec, s[8:9]
	s_not_b32 s8, s21
	s_lshl_b32 s8, s8, 8
	s_lshr_b32 s24, s12, 6
	s_and_b32 s11, s8, 0x1f00
	s_lshl_b32 s26, s24, 5
	s_or_b32 s13, s13, 0xc000000
	s_or_b32 s8, s2, s11
	s_add_u32 s22, s8, s26
	v_or_b32_e32 v5, s22, v144
	v_mov_b64_e32 v[6:7], s[4:5]
	s_addc_u32 s23, s3, 0
	v_mad_u64_u32 v[6:7], s[8:9], v5, s18, v[6:7]
	s_mulk_i32 s6, 0xc0
	v_mad_i32_i24 v7, s23, v188, v7
	s_lshl_b32 s6, s6, 1
	v_lshl_add_u64 v[6:7], v[6:7], 0, s[6:7]
	v_mov_b32_e32 v151, v147
	v_lshl_add_u64 v[6:7], v[6:7], 0, v[150:151]
	v_ashrrev_i32_e32 v8, 31, v0
	v_ashrrev_i32_e32 v9, 31, v2
	global_load_dwordx4 v[96:99], v[6:7], off
	global_load_dwordx4 v[100:103], v[6:7], off offset:32
	global_load_dwordx4 v[104:107], v[6:7], off offset:64
	global_load_dwordx4 v[108:111], v[6:7], off offset:96
	global_load_dwordx4 v[112:115], v[6:7], off offset:128
	global_load_dwordx4 v[116:119], v[6:7], off offset:160
	global_load_dwordx4 v[120:123], v[6:7], off offset:192
	global_load_dwordx4 v[124:127], v[6:7], off offset:224
	global_load_dwordx4 v[128:131], v[6:7], off offset:256
	global_load_dwordx4 v[132:135], v[6:7], off offset:288
	global_load_dwordx4 v[136:139], v[6:7], off offset:320
	global_load_dwordx4 v[140:143], v[6:7], off offset:352
	v_lshl_add_u32 v6, v3, 3, v161
	v_lshl_add_u32 v4, v4, 3, v165
	v_mov_b32_e32 v7, v147
	v_mov_b32_e32 v5, v147
	v_lshrrev_b32_e32 v14, 28, v8
	v_lshrrev_b32_e32 v15, 28, v9
	v_lshl_add_u64 v[10:11], v[6:7], 1, s[84:85]
	v_lshl_add_u64 v[12:13], v[4:5], 1, s[84:85]
	v_add_u32_e32 v5, v0, v14
	v_add_u32_e32 v7, v2, v15
	v_ashrrev_i32_e32 v170, 4, v5
	v_and_b32_e32 v5, 0x1ffffff0, v5
	v_ashrrev_i32_e32 v171, 4, v7
	v_sub_u32_e32 v0, v0, v5
	v_lshlrev_b32_e32 v5, 2, v170
	v_add_lshl_u32 v15, v170, s2, 11
	v_add_lshl_u32 v17, v171, s2, 11
	s_lshl_b32 s2, s24, 10
	v_lshl_add_u32 v146, v1, 3, v159
	v_bfe_u32 v14, v170, 2, 2
	v_and_b32_e32 v5, 12, v5
	s_add_i32 s25, s2, 0
	v_lshl_add_u64 v[8:9], v[146:147], 1, s[84:85]
	v_and_b32_e32 v7, 0x1ffffff0, v7
	v_bitop3_b32 v0, v5, v0, v14 bitop3:0x36
	s_mov_b32 m0, s25
	v_sub_u32_e32 v2, v2, v7
	v_lshlrev_b32_e32 v7, 2, v171
	v_lshlrev_b32_e32 v189, 3, v0
	global_load_lds_dwordx4 v[8:9], off
	s_add_i32 m0, s25, 0x2000
	v_mov_b32_e32 v1, v147
	v_bfe_u32 v16, v171, 2, 2
	v_and_b32_e32 v7, 12, v7
	v_add3_u32 v0, s13, v15, v189
	global_load_lds_dwordx4 v[10:11], off
	s_add_i32 m0, s25, 0x4000
	v_bitop3_b32 v2, v7, v2, v16 bitop3:0x36
	v_lshl_add_u64 v[8:9], v[0:1], 1, s[84:85]
	global_load_lds_dwordx4 v[12:13], off
	s_add_i32 m0, s25, 0x6000
	v_lshlrev_b32_e32 v190, 3, v2
	global_load_lds_dwordx4 v[8:9], off
	s_add_i32 m0, s25, 0x8000
	v_mov_b32_e32 v3, v147
	v_add3_u32 v2, s13, v17, v190
	s_cmpk_gt_u32 s12, 0xff
	v_lshl_add_u64 v[10:11], v[2:3], 1, s[84:85]
	s_cselect_b64 s[8:9], -1, 0
	s_cmpk_lt_u32 s12, 0x100
	v_add_u32_e32 v146, v146, v153
	global_load_lds_dwordx4 v[10:11], off
	s_cselect_b64 s[12:13], -1, 0
	s_add_i32 m0, s25, 0xa000
	v_lshl_add_u64 v[8:9], v[146:147], 1, s[84:85]
	v_add_u32_e32 v146, v6, v155
	s_waitcnt vmcnt(0) lgkmcnt(0)
	s_barrier
	s_waitcnt vmcnt(0)
	global_load_lds_dwordx4 v[8:9], off
	v_lshl_add_u64 v[6:7], v[146:147], 1, s[84:85]
	s_add_i32 m0, s25, 0xc000
	v_add_u32_e32 v146, v4, v157
	global_load_lds_dwordx4 v[6:7], off
	v_lshl_add_u64 v[4:5], v[146:147], 1, s[84:85]
	s_add_i32 m0, s25, 0xe000
	v_add_u32_e32 v146, 0x20000, v0
	global_load_lds_dwordx4 v[4:5], off
	s_add_i32 m0, s25, 0x10000
	v_lshl_add_u64 v[0:1], v[146:147], 1, s[84:85]
	v_add_u32_e32 v146, 0x20000, v2
	global_load_lds_dwordx4 v[0:1], off
	v_lshl_add_u64 v[0:1], v[146:147], 1, s[84:85]
	s_add_i32 m0, s25, 0x12000
	v_add_u32_e32 v36, 0, v149
	global_load_lds_dwordx4 v[0:1], off
	ds_read_b128 v[0:3], v36
	v_add_u32_e32 v40, 0, v172
	ds_read_b128 v[4:7], v40
	v_add_u32_e32 v44, 0, v173
	v_add_u32_e32 v64, 0, v174
	ds_read_b128 v[8:11], v44
	ds_read_b128 v[12:15], v64
	s_waitcnt lgkmcnt(3)
	v_mfma_f32_32x32x16_bf16 v[48:63], v[0:3], v[96:99], 0
	ds_read_b128 v[0:3], v36 offset:128
	s_and_b64 vcc, exec, s[12:13]
	s_waitcnt lgkmcnt(3)
	v_mfma_f32_32x32x16_bf16 v[48:63], v[4:7], v[100:103], v[48:63]
	ds_read_b128 v[4:7], v40 offset:128
	s_waitcnt lgkmcnt(3)
	v_mfma_f32_32x32x16_bf16 v[48:63], v[8:11], v[104:107], v[48:63]
	ds_read_b128 v[8:11], v44 offset:128
	s_waitcnt lgkmcnt(3)
	v_mfma_f32_32x32x16_bf16 v[48:63], v[12:15], v[108:111], v[48:63]
	ds_read_b128 v[12:15], v64 offset:128
	s_waitcnt lgkmcnt(3)
	v_mfma_f32_32x32x16_bf16 v[48:63], v[0:3], v[112:115], v[48:63]
	ds_read_b128 v[0:3], v36 offset:256
	s_waitcnt lgkmcnt(3)
	v_mfma_f32_32x32x16_bf16 v[48:63], v[4:7], v[116:119], v[48:63]
	ds_read_b128 v[4:7], v40 offset:256
	s_waitcnt lgkmcnt(3)
	v_mfma_f32_32x32x16_bf16 v[48:63], v[8:11], v[120:123], v[48:63]
	ds_read_b128 v[8:11], v44 offset:256
	s_waitcnt lgkmcnt(3)
	v_mfma_f32_32x32x16_bf16 v[48:63], v[12:15], v[124:127], v[48:63]
	ds_read_b128 v[12:15], v64 offset:256
	s_waitcnt lgkmcnt(3)
	v_mfma_f32_32x32x16_bf16 v[48:63], v[0:3], v[128:131], v[48:63]
	ds_read_b128 v[0:3], v36 offset:12288
	s_waitcnt lgkmcnt(3)
	v_mfma_f32_32x32x16_bf16 v[48:63], v[4:7], v[132:135], v[48:63]
	ds_read_b128 v[4:7], v40 offset:12288
	s_waitcnt lgkmcnt(3)
	v_mfma_f32_32x32x16_bf16 v[48:63], v[8:11], v[136:139], v[48:63]
	ds_read_b128 v[8:11], v44 offset:12288
	s_waitcnt lgkmcnt(2)
	v_mfma_f32_32x32x16_bf16 v[80:95], v[0:3], v[96:99], 0
	ds_read_b128 v[16:19], v64 offset:12288
	s_waitcnt lgkmcnt(2)
	v_mfma_f32_32x32x16_bf16 v[80:95], v[4:7], v[100:103], v[80:95]
	ds_read_b128 v[20:23], v36 offset:12416
	s_waitcnt lgkmcnt(2)
	v_mfma_f32_32x32x16_bf16 v[80:95], v[8:11], v[104:107], v[80:95]
	ds_read_b128 v[24:27], v40 offset:12416
	s_waitcnt lgkmcnt(2)
	v_mfma_f32_32x32x16_bf16 v[80:95], v[16:19], v[108:111], v[80:95]
	ds_read_b128 v[28:31], v44 offset:12416
	s_waitcnt lgkmcnt(2)
	v_mfma_f32_32x32x16_bf16 v[80:95], v[20:23], v[112:115], v[80:95]
	ds_read_b128 v[32:35], v64 offset:12416
	s_waitcnt lgkmcnt(2)
	v_mfma_f32_32x32x16_bf16 v[80:95], v[24:27], v[116:119], v[80:95]
	ds_read_b128 v[36:39], v36 offset:12544
	s_waitcnt lgkmcnt(2)
	v_mfma_f32_32x32x16_bf16 v[80:95], v[28:31], v[120:123], v[80:95]
	ds_read_b128 v[40:43], v40 offset:12544
	s_waitcnt lgkmcnt(2)
	v_mfma_f32_32x32x16_bf16 v[80:95], v[32:35], v[124:127], v[80:95]
	ds_read_b128 v[44:47], v44 offset:12544
	s_waitcnt lgkmcnt(2)
	v_mfma_f32_32x32x16_bf16 v[80:95], v[36:39], v[128:131], v[80:95]
	ds_read_b128 v[64:67], v64 offset:12544
	s_waitcnt lgkmcnt(2)
	v_mfma_f32_32x32x16_bf16 v[80:95], v[40:43], v[132:135], v[80:95]
	s_waitcnt lgkmcnt(1)
	v_mfma_f32_32x32x16_bf16 v[80:95], v[44:47], v[136:139], v[80:95]
	s_waitcnt lgkmcnt(0)
	v_mfma_f32_32x32x16_bf16 v[80:95], v[64:67], v[140:143], v[80:95]
	v_mfma_f32_32x32x16_bf16 v[48:63], v[12:15], v[140:143], v[48:63]
	s_cbranch_vccnz .LBB0_1773
	s_waitcnt vmcnt(0) lgkmcnt(0)
	s_barrier
.LBB0_1773:
	s_nop 10
	v_max_f32_e32 v0, v48, v49
	v_max3_f32 v0, v0, v50, v51
	v_max3_f32 v0, v0, v52, v53
	v_max3_f32 v0, v0, v54, v55
	v_max3_f32 v0, v0, v56, v57
	v_max3_f32 v0, v0, v58, v59
	v_max3_f32 v0, v0, v60, v61
	v_max3_f32 v0, v0, v62, v63
	v_mov_b32_e32 v1, v0
	s_nop 1
	v_permlane32_swap_b32_e32 v0, v1
	v_max_f32_e32 v0, v0, v1
	s_cmp_lg_u64 exec, 0
	v_add_f32_e32 v0, 0, v0
	s_cselect_b64 vcc, -1, 0
	v_cndmask_b32_e32 v151, 0, v0, vcc
	v_sub_f32_e32 v0, v48, v151
	v_exp_f32_e32 v48, v0
	v_sub_f32_e32 v0, v49, v151
	v_exp_f32_e32 v49, v0
	v_sub_f32_e32 v0, v50, v151
	v_exp_f32_e32 v50, v0
	v_sub_f32_e32 v0, v51, v151
	v_exp_f32_e32 v51, v0
	v_sub_f32_e32 v0, v52, v151
	v_exp_f32_e32 v52, v0
	v_sub_f32_e32 v0, v53, v151
	v_exp_f32_e32 v53, v0
	v_sub_f32_e32 v0, v54, v151
	v_exp_f32_e32 v54, v0
	v_sub_f32_e32 v0, v55, v151
	v_add_u32_e32 v191, v182, v178
	v_exp_f32_e32 v55, v0
	v_add_u32_e32 v193, v183, v178
	ds_read_b64_tr_b16 v[4:5], v191 offset:24576
	ds_read_b64_tr_b16 v[6:7], v193 offset:26624
	v_sub_f32_e32 v0, v56, v151
	v_exp_f32_e32 v56, v0
	v_sub_f32_e32 v0, v57, v151
	v_exp_f32_e32 v57, v0
	v_sub_f32_e32 v0, v58, v151
	v_exp_f32_e32 v58, v0
	v_cvt_pk_bf16_f32 v0, v48, v49
	v_cvt_pk_bf16_f32 v1, v50, v51
	v_cvt_pk_bf16_f32 v2, v52, v53
	v_cvt_pk_bf16_f32 v3, v54, v55
	v_add_u32_e32 v146, v182, v179
	v_add_u32_e32 v195, v182, v180
	v_add_u32_e32 v192, v183, v179
	ds_read_b64_tr_b16 v[8:9], v146 offset:24576
	ds_read_b64_tr_b16 v[10:11], v192 offset:26624
	ds_read_b64_tr_b16 v[202:203], v193 offset:30720
	ds_read_b64_tr_b16 v[200:201], v191 offset:28672
	s_waitcnt lgkmcnt(4)
	v_mfma_f32_32x32x16_bf16 v[64:79], v[4:7], v[0:3], 0
	v_add_u32_e32 v197, v183, v180
	ds_read_b64_tr_b16 v[4:5], v195 offset:24576
	ds_read_b64_tr_b16 v[6:7], v197 offset:26624
	ds_read_b64_tr_b16 v[206:207], v192 offset:30720
	ds_read_b64_tr_b16 v[204:205], v146 offset:28672
	v_sub_f32_e32 v12, v59, v151
	v_sub_f32_e32 v62, v62, v151
	v_sub_f32_e32 v63, v63, v151
	v_exp_f32_e32 v59, v12
	v_add_u32_e32 v196, v182, v181
	s_waitcnt lgkmcnt(2)
	v_mfma_f32_32x32x16_bf16 v[16:31], v[4:7], v[0:3], 0
	v_sub_f32_e32 v4, v60, v151
	v_exp_f32_e32 v60, v4
	v_sub_f32_e32 v4, v61, v151
	v_exp_f32_e32 v61, v4
	v_exp_f32_e32 v62, v62
	v_exp_f32_e32 v63, v63
	v_add_u32_e32 v198, v183, v181
	v_mfma_f32_32x32x16_bf16 v[32:47], v[8:11], v[0:3], 0
	ds_read_b64_tr_b16 v[8:9], v196 offset:24576
	ds_read_b64_tr_b16 v[10:11], v198 offset:26624
	ds_read_b64_tr_b16 v[210:211], v197 offset:30720
	ds_read_b64_tr_b16 v[208:209], v195 offset:28672
	v_add_f32_e32 v194, 0, v48
	v_cvt_pk_bf16_f32 v216, v56, v57
	v_cvt_pk_bf16_f32 v217, v58, v59
	v_cvt_pk_bf16_f32 v218, v60, v61
	v_cvt_pk_bf16_f32 v219, v62, v63
	v_add_f32_e32 v194, v49, v194
	s_waitcnt lgkmcnt(2)
	v_mfma_f32_32x32x16_bf16 v[0:15], v[8:11], v[0:3], 0
	v_add_f32_e32 v194, v50, v194
	v_max_f32_e32 v199, v81, v81
	v_add_f32_e32 v194, v51, v194
	ds_read_b64_tr_b16 v[214:215], v198 offset:30720
	ds_read_b64_tr_b16 v[212:213], v196 offset:28672
	v_add_f32_e32 v194, v52, v194
	v_add_f32_e32 v194, v53, v194
	v_add_f32_e32 v194, v54, v194
	v_mfma_f32_32x32x16_bf16 v[64:79], v[200:203], v[216:219], v[64:79]
	v_max_f32_e32 v200, v80, v80
	v_max_f32_e32 v199, v200, v199
	v_max3_f32 v199, v199, v82, v83
	v_max3_f32 v199, v199, v84, v85
	v_max3_f32 v199, v199, v86, v87
	v_add_f32_e32 v194, v55, v194
	v_max3_f32 v199, v199, v88, v89
	v_add_f32_e32 v194, v56, v194
	v_max3_f32 v199, v199, v90, v91
	v_mfma_f32_32x32x16_bf16 v[32:47], v[204:207], v[216:219], v[32:47]
	v_add_f32_e32 v194, v57, v194
	v_max3_f32 v199, v199, v92, v93
	v_add_f32_e32 v194, v58, v194
	v_max3_f32 v199, v199, v94, v95
	v_add_f32_e32 v194, v59, v194
	v_mov_b32_e32 v200, v199
	v_add_f32_e32 v194, v60, v194
	s_waitcnt lgkmcnt(2)
	v_mfma_f32_32x32x16_bf16 v[16:31], v[208:211], v[216:219], v[16:31]
	v_permlane32_swap_b32_e32 v199, v200
	v_add_f32_e32 v194, v61, v194
	v_max_f32_e32 v200, v200, v200
	v_max_f32_e32 v199, v199, v199
	v_add_f32_e32 v194, v62, v194
	v_max_f32_e32 v199, v199, v200
	s_waitcnt lgkmcnt(0)
	v_mfma_f32_32x32x16_bf16 v[0:15], v[212:215], v[216:219], v[0:15]
	v_add_f32_e32 v194, v63, v194
	v_sub_f32_e32 v199, v199, v151
	v_add_f32_e32 v194, 0, v194
	v_cmp_lt_f32_e32 vcc, s20, v199
	s_cbranch_vccz .LBB0_1775
	v_max_f32_e32 v199, v199, v199
	v_max_f32_e32 v199, 0, v199
	v_exp_f32_e64 v200, -v199
	v_add_f32_e32 v151, v151, v199
	v_pk_mul_f32 v[78:79], v[78:79], v[200:201] op_sel_hi:[1,0]
	v_pk_mul_f32 v[76:77], v[76:77], v[200:201] op_sel_hi:[1,0]
	v_pk_mul_f32 v[74:75], v[74:75], v[200:201] op_sel_hi:[1,0]
	v_pk_mul_f32 v[72:73], v[72:73], v[200:201] op_sel_hi:[1,0]
	v_pk_mul_f32 v[70:71], v[70:71], v[200:201] op_sel_hi:[1,0]
	v_pk_mul_f32 v[68:69], v[68:69], v[200:201] op_sel_hi:[1,0]
	v_pk_mul_f32 v[66:67], v[66:67], v[200:201] op_sel_hi:[1,0]
	v_pk_mul_f32 v[64:65], v[64:65], v[200:201] op_sel_hi:[1,0]
	v_pk_mul_f32 v[46:47], v[46:47], v[200:201] op_sel_hi:[1,0]
	v_pk_mul_f32 v[44:45], v[44:45], v[200:201] op_sel_hi:[1,0]
	v_pk_mul_f32 v[42:43], v[42:43], v[200:201] op_sel_hi:[1,0]
	v_pk_mul_f32 v[40:41], v[40:41], v[200:201] op_sel_hi:[1,0]
	v_pk_mul_f32 v[38:39], v[38:39], v[200:201] op_sel_hi:[1,0]
	v_pk_mul_f32 v[36:37], v[36:37], v[200:201] op_sel_hi:[1,0]
	v_pk_mul_f32 v[34:35], v[34:35], v[200:201] op_sel_hi:[1,0]
	v_pk_mul_f32 v[32:33], v[32:33], v[200:201] op_sel_hi:[1,0]
	v_pk_mul_f32 v[30:31], v[30:31], v[200:201] op_sel_hi:[1,0]
	v_pk_mul_f32 v[28:29], v[28:29], v[200:201] op_sel_hi:[1,0]
	v_pk_mul_f32 v[26:27], v[26:27], v[200:201] op_sel_hi:[1,0]
	v_pk_mul_f32 v[24:25], v[24:25], v[200:201] op_sel_hi:[1,0]
	v_pk_mul_f32 v[22:23], v[22:23], v[200:201] op_sel_hi:[1,0]
	v_pk_mul_f32 v[20:21], v[20:21], v[200:201] op_sel_hi:[1,0]
	v_pk_mul_f32 v[18:19], v[18:19], v[200:201] op_sel_hi:[1,0]
	v_pk_mul_f32 v[16:17], v[16:17], v[200:201] op_sel_hi:[1,0]
	v_pk_mul_f32 v[14:15], v[14:15], v[200:201] op_sel_hi:[1,0]
	v_pk_mul_f32 v[12:13], v[12:13], v[200:201] op_sel_hi:[1,0]
	v_pk_mul_f32 v[10:11], v[10:11], v[200:201] op_sel_hi:[1,0]
	v_pk_mul_f32 v[8:9], v[8:9], v[200:201] op_sel_hi:[1,0]
	v_pk_mul_f32 v[6:7], v[6:7], v[200:201] op_sel_hi:[1,0]
	v_pk_mul_f32 v[4:5], v[4:5], v[200:201] op_sel_hi:[1,0]
	v_pk_mul_f32 v[2:3], v[2:3], v[200:201] op_sel_hi:[1,0]
	v_pk_mul_f32 v[0:1], v[0:1], v[200:201] op_sel_hi:[1,0]
	v_mul_f32_e32 v194, v194, v200

.LBB0_1786:
	s_setprio 0
	v_add_u32_e32 v159, s28, v149
	ds_read_b128 v[48:51], v159
	v_add_u32_e32 v161, s28, v172
	v_add_u32_e32 v165, s28, v173
	v_add_u32_e32 v167, s28, v174
	ds_read_b128 v[80:83], v161
	ds_read_b128 v[84:87], v165
	ds_read_b128 v[88:91], v167
	s_waitcnt lgkmcnt(3)
	v_mfma_f32_32x32x16_bf16 v[48:63], v[48:51], v[96:99], 0
	ds_read_b128 v[92:95], v159 offset:128
	s_waitcnt lgkmcnt(3)
	v_mfma_f32_32x32x16_bf16 v[48:63], v[80:83], v[100:103], v[48:63]
	ds_read_b128 v[80:83], v161 offset:128
	s_waitcnt lgkmcnt(3)
	v_mfma_f32_32x32x16_bf16 v[48:63], v[84:87], v[104:107], v[48:63]
	ds_read_b128 v[84:87], v165 offset:128
	s_waitcnt lgkmcnt(3)
	v_mfma_f32_32x32x16_bf16 v[48:63], v[88:91], v[108:111], v[48:63]
	ds_read_b128 v[88:91], v167 offset:128
	s_waitcnt lgkmcnt(3)
	v_mfma_f32_32x32x16_bf16 v[48:63], v[92:95], v[112:115], v[48:63]
	ds_read_b128 v[92:95], v159 offset:256
	s_waitcnt lgkmcnt(3)
	v_mfma_f32_32x32x16_bf16 v[48:63], v[80:83], v[116:119], v[48:63]
	ds_read_b128 v[80:83], v161 offset:256
	s_waitcnt lgkmcnt(3)
	v_mfma_f32_32x32x16_bf16 v[48:63], v[84:87], v[120:123], v[48:63]
	ds_read_b128 v[84:87], v165 offset:256
	s_waitcnt lgkmcnt(3)
	v_mfma_f32_32x32x16_bf16 v[48:63], v[88:91], v[124:127], v[48:63]
	ds_read_b128 v[190:193], v167 offset:256
	s_waitcnt lgkmcnt(3)
	v_mfma_f32_32x32x16_bf16 v[48:63], v[92:95], v[128:131], v[48:63]
	ds_read_b128 v[88:91], v159 offset:12288
	s_waitcnt lgkmcnt(3)
	v_mfma_f32_32x32x16_bf16 v[48:63], v[80:83], v[132:135], v[48:63]
	ds_read_b128 v[194:197], v161 offset:12288
	s_waitcnt lgkmcnt(3)
	v_mfma_f32_32x32x16_bf16 v[48:63], v[84:87], v[136:139], v[48:63]
	ds_read_b128 v[198:201], v165 offset:12288
	s_waitcnt lgkmcnt(2)
	v_mfma_f32_32x32x16_bf16 v[80:95], v[88:91], v[96:99], 0
	ds_read_b128 v[202:205], v167 offset:12288
	s_waitcnt lgkmcnt(2)
	v_mfma_f32_32x32x16_bf16 v[80:95], v[194:197], v[100:103], v[80:95]
	ds_read_b128 v[206:209], v159 offset:12416
	s_waitcnt lgkmcnt(2)
	v_mfma_f32_32x32x16_bf16 v[80:95], v[198:201], v[104:107], v[80:95]
	ds_read_b128 v[210:213], v161 offset:12416
	s_waitcnt lgkmcnt(2)
	v_mfma_f32_32x32x16_bf16 v[80:95], v[202:205], v[108:111], v[80:95]
	ds_read_b128 v[214:217], v165 offset:12416
	s_waitcnt lgkmcnt(2)
	v_mfma_f32_32x32x16_bf16 v[80:95], v[206:209], v[112:115], v[80:95]
	ds_read_b128 v[218:221], v167 offset:12416
	s_waitcnt lgkmcnt(2)
	v_mfma_f32_32x32x16_bf16 v[80:95], v[210:213], v[116:119], v[80:95]
	ds_read_b128 v[224:227], v159 offset:12544
	s_waitcnt lgkmcnt(2)
	v_mfma_f32_32x32x16_bf16 v[80:95], v[214:217], v[120:123], v[80:95]
	ds_read_b128 v[228:231], v161 offset:12544
	s_waitcnt lgkmcnt(2)
	v_mfma_f32_32x32x16_bf16 v[80:95], v[218:221], v[124:127], v[80:95]
	ds_read_b128 v[232:235], v165 offset:12544
	s_waitcnt lgkmcnt(2)
	v_mfma_f32_32x32x16_bf16 v[80:95], v[224:227], v[128:131], v[80:95]
	ds_read_b128 v[236:239], v167 offset:12544
	s_waitcnt lgkmcnt(2)
	v_mfma_f32_32x32x16_bf16 v[80:95], v[228:231], v[132:135], v[80:95]
	s_waitcnt lgkmcnt(1)
	v_mfma_f32_32x32x16_bf16 v[80:95], v[232:235], v[136:139], v[80:95]
	s_waitcnt lgkmcnt(0)
	v_mfma_f32_32x32x16_bf16 v[80:95], v[236:239], v[140:143], v[80:95]
	v_mfma_f32_32x32x16_bf16 v[48:63], v[190:193], v[140:143], v[48:63]
	s_andn2_b64 vcc, exec, s[8:9]
	s_cbranch_vccnz .LBB0_1781

.LBB0_1790:
	v_add_u32_e32 v171, s28, v175
	v_add_u32_e32 v190, s28, v177
	v_sub_f32_e32 v48, v48, v151
	v_sub_f32_e32 v49, v49, v151
	v_sub_f32_e32 v50, v50, v151
	v_sub_f32_e32 v51, v51, v151
	v_sub_f32_e32 v52, v52, v151
	v_sub_f32_e32 v53, v53, v151
	v_sub_f32_e32 v54, v54, v151
	v_sub_f32_e32 v55, v55, v151
	v_add_u32_e32 v161, v171, v178
	v_exp_f32_e32 v48, v48
	v_exp_f32_e32 v49, v49
	v_exp_f32_e32 v50, v50
	v_exp_f32_e32 v51, v51
	v_exp_f32_e32 v52, v52
	v_exp_f32_e32 v53, v53
	v_exp_f32_e32 v54, v54
	v_exp_f32_e32 v55, v55
	v_add_u32_e32 v167, v190, v178
	ds_read_b64_tr_b16 v[196:197], v161 offset:24576
	ds_read_b64_tr_b16 v[198:199], v167 offset:26624
	v_add_u32_e32 v159, v171, v179
	v_add_u32_e32 v165, v190, v179
	ds_read_b64_tr_b16 v[200:201], v159 offset:24576
	ds_read_b64_tr_b16 v[202:203], v165 offset:26624
	ds_read_b64_tr_b16 v[206:207], v167 offset:30720
	ds_read_b64_tr_b16 v[204:205], v161 offset:28672
	v_cvt_pk_bf16_f32 v192, v48, v49
	v_cvt_pk_bf16_f32 v193, v50, v51
	v_cvt_pk_bf16_f32 v194, v52, v53
	v_cvt_pk_bf16_f32 v195, v54, v55
	v_add_u32_e32 v169, v171, v180
	v_add_u32_e32 v171, v171, v181
	s_waitcnt lgkmcnt(4)
	v_mfma_f32_32x32x16_bf16 v[64:79], v[196:199], v[192:195], v[64:79]
	v_add_u32_e32 v189, v190, v180
	ds_read_b64_tr_b16 v[196:197], v169 offset:24576
	ds_read_b64_tr_b16 v[198:199], v189 offset:26624
	ds_read_b64_tr_b16 v[210:211], v165 offset:30720
	ds_read_b64_tr_b16 v[208:209], v159 offset:28672
	v_add_u32_e32 v190, v190, v181
	v_add_f32_e32 v191, 0, v48
	v_sub_f32_e32 v56, v56, v151
	v_sub_f32_e32 v57, v57, v151
	v_sub_f32_e32 v58, v58, v151
	s_waitcnt lgkmcnt(6)
	v_mfma_f32_32x32x16_bf16 v[32:47], v[200:203], v[192:195], v[32:47]
	ds_read_b64_tr_b16 v[200:201], v171 offset:24576
	ds_read_b64_tr_b16 v[202:203], v190 offset:26624
	ds_read_b64_tr_b16 v[214:215], v189 offset:30720
	ds_read_b64_tr_b16 v[212:213], v169 offset:28672
	v_sub_f32_e32 v59, v59, v151
	v_sub_f32_e32 v60, v60, v151
	v_sub_f32_e32 v61, v61, v151
	v_sub_f32_e32 v62, v62, v151
	v_sub_f32_e32 v63, v63, v151
	v_add_f32_e32 v191, v49, v191
	s_waitcnt lgkmcnt(6)
	v_mfma_f32_32x32x16_bf16 v[16:31], v[196:199], v[192:195], v[16:31]
	v_exp_f32_e32 v56, v56
	v_exp_f32_e32 v57, v57
	v_exp_f32_e32 v58, v58
	v_exp_f32_e32 v59, v59
	v_exp_f32_e32 v60, v60
	v_exp_f32_e32 v61, v61
	ds_read_b64_tr_b16 v[198:199], v190 offset:30720
	ds_read_b64_tr_b16 v[196:197], v171 offset:28672
	s_waitcnt lgkmcnt(4)
	v_mfma_f32_32x32x16_bf16 v[0:15], v[200:203], v[192:195], v[0:15]
	v_exp_f32_e32 v62, v62
	v_exp_f32_e32 v63, v63
	v_add_f32_e32 v191, v50, v191
	v_add_f32_e32 v191, v51, v191
	v_add_f32_e32 v191, v52, v191
	v_add_f32_e32 v191, v53, v191
	v_cvt_pk_bf16_f32 v192, v56, v57
	v_cvt_pk_bf16_f32 v193, v58, v59
	v_cvt_pk_bf16_f32 v194, v60, v61
	v_cvt_pk_bf16_f32 v195, v62, v63
	v_add_f32_e32 v191, v54, v191
	v_add_f32_e32 v191, v55, v191
	v_mfma_f32_32x32x16_bf16 v[64:79], v[204:207], v[192:195], v[64:79]
	v_add_f32_e32 v191, v56, v191
	v_add_f32_e32 v191, v57, v191
	v_add_f32_e32 v191, v58, v191
	v_add_f32_e32 v191, v59, v191
	v_add_f32_e32 v191, v60, v191
	v_add_f32_e32 v191, v61, v191
	v_add_f32_e32 v191, v62, v191
	v_mfma_f32_32x32x16_bf16 v[32:47], v[208:211], v[192:195], v[32:47]
	v_add_f32_e32 v191, v63, v191
	v_add_f32_e32 v163, v163, v191
	s_waitcnt lgkmcnt(2)
	v_mfma_f32_32x32x16_bf16 v[16:31], v[212:215], v[192:195], v[16:31]
	s_waitcnt lgkmcnt(0)
	v_mfma_f32_32x32x16_bf16 v[0:15], v[196:199], v[192:195], v[0:15]
	v_max_f32_e32 v192, v81, v81
	v_max_f32_e32 v193, v80, v80
	v_max_f32_e32 v192, v193, v192
	v_max3_f32 v192, v192, v82, v83
	v_max3_f32 v192, v192, v84, v85
	v_max3_f32 v192, v192, v86, v87
	v_max3_f32 v192, v192, v88, v89
	v_max3_f32 v192, v192, v90, v91
	v_max3_f32 v192, v192, v92, v93
	v_max3_f32 v192, v192, v94, v95
	v_mov_b32_e32 v191, v192
	s_nop 1
	v_permlane32_swap_b32_e32 v192, v191
	v_max_f32_e32 v191, v192, v191
	v_sub_f32_e32 v191, v191, v151
	v_cmp_lt_f32_e32 vcc, s20, v191
	s_cbranch_vccz .LBB0_1792
	v_max_f32_e32 v191, v191, v191
	v_max_f32_e32 v191, 0, v191
	v_exp_f32_e64 v192, -v191
	v_add_f32_e32 v151, v151, v191
	v_pk_mul_f32 v[78:79], v[78:79], v[192:193] op_sel_hi:[1,0]
	v_pk_mul_f32 v[76:77], v[76:77], v[192:193] op_sel_hi:[1,0]
	v_pk_mul_f32 v[74:75], v[74:75], v[192:193] op_sel_hi:[1,0]
	v_pk_mul_f32 v[72:73], v[72:73], v[192:193] op_sel_hi:[1,0]
	v_pk_mul_f32 v[70:71], v[70:71], v[192:193] op_sel_hi:[1,0]
	v_pk_mul_f32 v[68:69], v[68:69], v[192:193] op_sel_hi:[1,0]
	v_pk_mul_f32 v[66:67], v[66:67], v[192:193] op_sel_hi:[1,0]
	v_pk_mul_f32 v[64:65], v[64:65], v[192:193] op_sel_hi:[1,0]
	v_pk_mul_f32 v[46:47], v[46:47], v[192:193] op_sel_hi:[1,0]
	v_pk_mul_f32 v[44:45], v[44:45], v[192:193] op_sel_hi:[1,0]
	v_pk_mul_f32 v[42:43], v[42:43], v[192:193] op_sel_hi:[1,0]
	v_pk_mul_f32 v[40:41], v[40:41], v[192:193] op_sel_hi:[1,0]
	v_pk_mul_f32 v[38:39], v[38:39], v[192:193] op_sel_hi:[1,0]
	v_pk_mul_f32 v[36:37], v[36:37], v[192:193] op_sel_hi:[1,0]
	v_pk_mul_f32 v[34:35], v[34:35], v[192:193] op_sel_hi:[1,0]
	v_pk_mul_f32 v[32:33], v[32:33], v[192:193] op_sel_hi:[1,0]
	v_pk_mul_f32 v[30:31], v[30:31], v[192:193] op_sel_hi:[1,0]
	v_pk_mul_f32 v[28:29], v[28:29], v[192:193] op_sel_hi:[1,0]
	v_pk_mul_f32 v[26:27], v[26:27], v[192:193] op_sel_hi:[1,0]
	v_pk_mul_f32 v[24:25], v[24:25], v[192:193] op_sel_hi:[1,0]
	v_pk_mul_f32 v[22:23], v[22:23], v[192:193] op_sel_hi:[1,0]
	v_pk_mul_f32 v[20:21], v[20:21], v[192:193] op_sel_hi:[1,0]
	v_pk_mul_f32 v[18:19], v[18:19], v[192:193] op_sel_hi:[1,0]
	v_pk_mul_f32 v[16:17], v[16:17], v[192:193] op_sel_hi:[1,0]
	v_pk_mul_f32 v[14:15], v[14:15], v[192:193] op_sel_hi:[1,0]
	v_pk_mul_f32 v[12:13], v[12:13], v[192:193] op_sel_hi:[1,0]
	v_pk_mul_f32 v[10:11], v[10:11], v[192:193] op_sel_hi:[1,0]
	v_pk_mul_f32 v[8:9], v[8:9], v[192:193] op_sel_hi:[1,0]
	v_pk_mul_f32 v[6:7], v[6:7], v[192:193] op_sel_hi:[1,0]
	v_pk_mul_f32 v[4:5], v[4:5], v[192:193] op_sel_hi:[1,0]
	v_pk_mul_f32 v[2:3], v[2:3], v[192:193] op_sel_hi:[1,0]
	v_pk_mul_f32 v[0:1], v[0:1], v[192:193] op_sel_hi:[1,0]
	v_mul_f32_e32 v163, v163, v192

.LBB0_1809:
	v_bfe_u32 v2, v222, 2, 2
	v_lshrrev_b32_e32 v5, 3, v222
	v_lshlrev_b32_e32 v6, 3, v222
	v_lshlrev_b32_e32 v3, 10, v161
	v_lshlrev_b32_e32 v4, 8, v2
	v_and_b32_e32 v5, 2, v5
	v_and_b32_e32 v0, 1, v0
	v_and_b32_e32 v6, 8, v6
	v_or3_b32 v3, v4, v6, v3
	v_bitop3_b32 v4, v5, v161, v0 bitop3:0x36
	v_bitop3_b32 v0, v1, v5, v0 bitop3:0x1e
	v_lshl_or_b32 v175, v0, 4, v3
	v_max_f32_e32 v0, v48, v49
	v_max3_f32 v0, v0, v50, v51
	v_max3_f32 v0, v0, v52, v53
	v_max3_f32 v0, v0, v54, v55
	v_max3_f32 v0, v0, v56, v57
	v_max3_f32 v0, v0, v58, v59
	v_max3_f32 v0, v0, v60, v61
	v_max3_f32 v0, v0, v62, v63
	v_mov_b32_e32 v1, v0
	s_nop 1
	v_permlane32_swap_b32_e32 v0, v1
	v_max_f32_e32 v0, v0, v1
	s_cmp_lg_u64 exec, 0
	v_add_f32_e32 v0, 0, v0
	s_cselect_b64 vcc, -1, 0
	v_cndmask_b32_e32 v157, 0, v0, vcc
	v_sub_f32_e32 v0, v48, v157
	v_exp_f32_e32 v48, v0
	v_sub_f32_e32 v0, v49, v157
	v_exp_f32_e32 v49, v0
	v_sub_f32_e32 v0, v50, v157
	v_exp_f32_e32 v50, v0
	v_sub_f32_e32 v0, v51, v157
	v_exp_f32_e32 v51, v0
	v_sub_f32_e32 v0, v52, v157
	v_lshl_or_b32 v174, v4, 4, v3
	v_exp_f32_e32 v52, v0
	v_sub_f32_e32 v0, v53, v157
	v_lshlrev_b32_e32 v177, 6, v2
	v_add_u32_e32 v12, 0, v174
	v_exp_f32_e32 v53, v0
	v_sub_f32_e32 v0, v54, v157
	v_add_u32_e32 v13, 0, v175
	v_exp_f32_e32 v54, v0
	v_sub_f32_e32 v0, v55, v157
	v_add_u32_e32 v183, v12, v177
	v_exp_f32_e32 v55, v0
	v_add_u32_e32 v185, v13, v177
	ds_read_b64_tr_b16 v[4:5], v183 offset:24576
	ds_read_b64_tr_b16 v[6:7], v185 offset:26624
	v_sub_f32_e32 v0, v56, v157
	v_exp_f32_e32 v56, v0
	v_sub_f32_e32 v0, v57, v157
	v_xor_b32_e32 v178, 64, v177
	v_xor_b32_e32 v179, 0x80, v177
	v_exp_f32_e32 v57, v0
	v_sub_f32_e32 v0, v58, v157
	v_exp_f32_e32 v58, v0
	v_cvt_pk_bf16_f32 v0, v48, v49
	v_cvt_pk_bf16_f32 v1, v50, v51
	v_cvt_pk_bf16_f32 v2, v52, v53
	v_cvt_pk_bf16_f32 v3, v54, v55
	v_add_u32_e32 v182, v12, v178
	v_add_u32_e32 v186, v12, v179
	v_add_u32_e32 v184, v13, v178
	ds_read_b64_tr_b16 v[8:9], v182 offset:24576
	ds_read_b64_tr_b16 v[10:11], v184 offset:26624
	ds_read_b64_tr_b16 v[164:165], v185 offset:30720
	ds_read_b64_tr_b16 v[162:163], v183 offset:28672
	s_waitcnt lgkmcnt(4)
	v_mfma_f32_32x32x16_bf16 v[64:79], v[4:7], v[0:3], 0
	v_add_u32_e32 v188, v13, v179
	ds_read_b64_tr_b16 v[4:5], v186 offset:24576
	ds_read_b64_tr_b16 v[6:7], v188 offset:26624
	ds_read_b64_tr_b16 v[168:169], v184 offset:30720
	ds_read_b64_tr_b16 v[166:167], v182 offset:28672
	v_sub_f32_e32 v14, v59, v157
	v_sub_f32_e32 v62, v62, v157
	v_sub_f32_e32 v63, v63, v157
	v_exp_f32_e32 v59, v14
	v_exp_f32_e32 v62, v62
	s_waitcnt lgkmcnt(2)
	v_mfma_f32_32x32x16_bf16 v[16:31], v[4:7], v[0:3], 0
	v_sub_f32_e32 v4, v60, v157
	v_exp_f32_e32 v60, v4
	v_sub_f32_e32 v4, v61, v157
	v_exp_f32_e32 v61, v4
	v_exp_f32_e32 v63, v63
	v_xor_b32_e32 v180, 0xc0, v177
	v_add_u32_e32 v187, v12, v180
	v_mfma_f32_32x32x16_bf16 v[32:47], v[8:11], v[0:3], 0
	v_add_u32_e32 v189, v13, v180
	ds_read_b64_tr_b16 v[8:9], v187 offset:24576
	ds_read_b64_tr_b16 v[10:11], v189 offset:26624
	ds_read_b64_tr_b16 v[200:201], v188 offset:30720
	ds_read_b64_tr_b16 v[198:199], v186 offset:28672
	v_cvt_pk_bf16_f32 v206, v56, v57
	v_cvt_pk_bf16_f32 v207, v58, v59
	v_cvt_pk_bf16_f32 v208, v60, v61
	v_cvt_pk_bf16_f32 v209, v62, v63
	ds_read_b64_tr_b16 v[204:205], v189 offset:30720
	ds_read_b64_tr_b16 v[202:203], v187 offset:28672
	v_mfma_f32_32x32x16_bf16 v[64:79], v[162:165], v[206:209], v[64:79]
	v_add_f32_e32 v162, 0, v48
	v_add_f32_e32 v162, v49, v162
	v_add_f32_e32 v162, v50, v162
	v_max_f32_e32 v163, v81, v81
	v_max_f32_e32 v164, v80, v80
	v_add_f32_e32 v162, v51, v162
	v_max_f32_e32 v163, v164, v163
	s_waitcnt lgkmcnt(4)
	v_mfma_f32_32x32x16_bf16 v[0:15], v[8:11], v[0:3], 0
	v_add_f32_e32 v162, v52, v162
	v_max3_f32 v163, v163, v82, v83
	v_add_f32_e32 v162, v53, v162
	v_max3_f32 v163, v163, v84, v85
	v_add_f32_e32 v162, v54, v162
	v_max3_f32 v163, v163, v86, v87
	v_add_f32_e32 v162, v55, v162
	v_max3_f32 v163, v163, v88, v89
	v_add_f32_e32 v162, v56, v162
	v_max3_f32 v163, v163, v90, v91
	v_mfma_f32_32x32x16_bf16 v[32:47], v[166:169], v[206:209], v[32:47]
	v_add_f32_e32 v162, v57, v162
	v_max3_f32 v163, v163, v92, v93
	v_add_f32_e32 v162, v58, v162
	v_max3_f32 v163, v163, v94, v95
	v_add_f32_e32 v162, v59, v162
	v_mov_b32_e32 v164, v163
	v_add_f32_e32 v162, v60, v162
	s_waitcnt lgkmcnt(2)
	v_mfma_f32_32x32x16_bf16 v[16:31], v[198:201], v[206:209], v[16:31]
	v_permlane32_swap_b32_e32 v163, v164
	v_add_f32_e32 v162, v61, v162
	v_max_f32_e32 v164, v164, v164
	v_max_f32_e32 v163, v163, v163
	v_add_f32_e32 v162, v62, v162
	v_max_f32_e32 v163, v163, v164
	s_waitcnt lgkmcnt(0)
	v_mfma_f32_32x32x16_bf16 v[0:15], v[202:205], v[206:209], v[0:15]
	v_add_f32_e32 v162, v63, v162
	v_sub_f32_e32 v163, v163, v157
	s_mov_b32 s2, 0x41000000
	v_add_f32_e32 v162, 0, v162
	v_cmp_lt_f32_e32 vcc, s2, v163
	s_cbranch_vccz .LBB0_1811
	v_max_f32_e32 v163, v163, v163
	v_max_f32_e32 v163, 0, v163
	v_exp_f32_e64 v164, -v163
	v_add_f32_e32 v157, v157, v163
	v_pk_mul_f32 v[78:79], v[78:79], v[164:165] op_sel_hi:[1,0]
	v_pk_mul_f32 v[76:77], v[76:77], v[164:165] op_sel_hi:[1,0]
	v_pk_mul_f32 v[74:75], v[74:75], v[164:165] op_sel_hi:[1,0]
	v_pk_mul_f32 v[72:73], v[72:73], v[164:165] op_sel_hi:[1,0]
	v_pk_mul_f32 v[70:71], v[70:71], v[164:165] op_sel_hi:[1,0]
	v_pk_mul_f32 v[68:69], v[68:69], v[164:165] op_sel_hi:[1,0]
	v_pk_mul_f32 v[66:67], v[66:67], v[164:165] op_sel_hi:[1,0]
	v_pk_mul_f32 v[64:65], v[64:65], v[164:165] op_sel_hi:[1,0]
	v_pk_mul_f32 v[46:47], v[46:47], v[164:165] op_sel_hi:[1,0]
	v_pk_mul_f32 v[44:45], v[44:45], v[164:165] op_sel_hi:[1,0]
	v_pk_mul_f32 v[42:43], v[42:43], v[164:165] op_sel_hi:[1,0]
	v_pk_mul_f32 v[40:41], v[40:41], v[164:165] op_sel_hi:[1,0]
	v_pk_mul_f32 v[38:39], v[38:39], v[164:165] op_sel_hi:[1,0]
	v_pk_mul_f32 v[36:37], v[36:37], v[164:165] op_sel_hi:[1,0]
	v_pk_mul_f32 v[34:35], v[34:35], v[164:165] op_sel_hi:[1,0]
	v_pk_mul_f32 v[32:33], v[32:33], v[164:165] op_sel_hi:[1,0]
	v_pk_mul_f32 v[30:31], v[30:31], v[164:165] op_sel_hi:[1,0]
	v_pk_mul_f32 v[28:29], v[28:29], v[164:165] op_sel_hi:[1,0]
	v_pk_mul_f32 v[26:27], v[26:27], v[164:165] op_sel_hi:[1,0]
	v_pk_mul_f32 v[24:25], v[24:25], v[164:165] op_sel_hi:[1,0]
	v_pk_mul_f32 v[22:23], v[22:23], v[164:165] op_sel_hi:[1,0]
	v_pk_mul_f32 v[20:21], v[20:21], v[164:165] op_sel_hi:[1,0]
	v_pk_mul_f32 v[18:19], v[18:19], v[164:165] op_sel_hi:[1,0]
	v_pk_mul_f32 v[16:17], v[16:17], v[164:165] op_sel_hi:[1,0]
	v_pk_mul_f32 v[14:15], v[14:15], v[164:165] op_sel_hi:[1,0]
	v_pk_mul_f32 v[12:13], v[12:13], v[164:165] op_sel_hi:[1,0]
	v_pk_mul_f32 v[10:11], v[10:11], v[164:165] op_sel_hi:[1,0]
	v_pk_mul_f32 v[8:9], v[8:9], v[164:165] op_sel_hi:[1,0]
	v_pk_mul_f32 v[6:7], v[6:7], v[164:165] op_sel_hi:[1,0]
	v_pk_mul_f32 v[4:5], v[4:5], v[164:165] op_sel_hi:[1,0]
	v_pk_mul_f32 v[2:3], v[2:3], v[164:165] op_sel_hi:[1,0]
	v_pk_mul_f32 v[0:1], v[0:1], v[164:165] op_sel_hi:[1,0]
	v_mul_f32_e32 v162, v162, v164

.LBB0_1822:
	s_setprio 0
	v_add_u32_e32 v147, s26, v170
	ds_read_b128 v[48:51], v147
	v_add_u32_e32 v149, s26, v171
	v_add_u32_e32 v151, s26, v172
	v_add_u32_e32 v153, s26, v173
	ds_read_b128 v[80:83], v149
	ds_read_b128 v[84:87], v151
	ds_read_b128 v[88:91], v153
	s_waitcnt lgkmcnt(3)
	v_mfma_f32_32x32x16_bf16 v[48:63], v[48:51], v[96:99], 0
	ds_read_b128 v[92:95], v147 offset:128
	s_waitcnt lgkmcnt(3)
	v_mfma_f32_32x32x16_bf16 v[48:63], v[80:83], v[100:103], v[48:63]
	ds_read_b128 v[80:83], v149 offset:128
	s_waitcnt lgkmcnt(3)
	v_mfma_f32_32x32x16_bf16 v[48:63], v[84:87], v[104:107], v[48:63]
	ds_read_b128 v[84:87], v151 offset:128
	s_waitcnt lgkmcnt(3)
	v_mfma_f32_32x32x16_bf16 v[48:63], v[88:91], v[108:111], v[48:63]
	ds_read_b128 v[88:91], v153 offset:128
	s_waitcnt lgkmcnt(3)
	v_mfma_f32_32x32x16_bf16 v[48:63], v[92:95], v[112:115], v[48:63]
	ds_read_b128 v[92:95], v147 offset:256
	s_waitcnt lgkmcnt(3)
	v_mfma_f32_32x32x16_bf16 v[48:63], v[80:83], v[116:119], v[48:63]
	ds_read_b128 v[80:83], v149 offset:256
	s_waitcnt lgkmcnt(3)
	v_mfma_f32_32x32x16_bf16 v[48:63], v[84:87], v[120:123], v[48:63]
	ds_read_b128 v[84:87], v151 offset:256
	s_waitcnt lgkmcnt(3)
	v_mfma_f32_32x32x16_bf16 v[48:63], v[88:91], v[124:127], v[48:63]
	ds_read_b128 v[162:165], v153 offset:256
	s_waitcnt lgkmcnt(3)
	v_mfma_f32_32x32x16_bf16 v[48:63], v[92:95], v[128:131], v[48:63]
	ds_read_b128 v[88:91], v147 offset:12288
	s_waitcnt lgkmcnt(3)
	v_mfma_f32_32x32x16_bf16 v[48:63], v[80:83], v[132:135], v[48:63]
	ds_read_b128 v[166:169], v149 offset:12288
	s_waitcnt lgkmcnt(3)
	v_mfma_f32_32x32x16_bf16 v[48:63], v[84:87], v[136:139], v[48:63]
	ds_read_b128 v[198:201], v151 offset:12288
	s_waitcnt lgkmcnt(2)
	v_mfma_f32_32x32x16_bf16 v[80:95], v[88:91], v[96:99], 0
	ds_read_b128 v[202:205], v153 offset:12288
	s_waitcnt lgkmcnt(2)
	v_mfma_f32_32x32x16_bf16 v[80:95], v[166:169], v[100:103], v[80:95]
	ds_read_b128 v[206:209], v147 offset:12416
	s_waitcnt lgkmcnt(2)
	v_mfma_f32_32x32x16_bf16 v[80:95], v[198:201], v[104:107], v[80:95]
	ds_read_b128 v[210:213], v149 offset:12416
	s_waitcnt lgkmcnt(2)
	v_mfma_f32_32x32x16_bf16 v[80:95], v[202:205], v[108:111], v[80:95]
	ds_read_b128 v[214:217], v151 offset:12416
	s_waitcnt lgkmcnt(2)
	v_mfma_f32_32x32x16_bf16 v[80:95], v[206:209], v[112:115], v[80:95]
	ds_read_b128 v[218:221], v153 offset:12416
	s_waitcnt lgkmcnt(2)
	v_mfma_f32_32x32x16_bf16 v[80:95], v[210:213], v[116:119], v[80:95]
	ds_read_b128 v[224:227], v147 offset:12544
	s_waitcnt lgkmcnt(2)
	v_mfma_f32_32x32x16_bf16 v[80:95], v[214:217], v[120:123], v[80:95]
	ds_read_b128 v[228:231], v149 offset:12544
	s_waitcnt lgkmcnt(2)
	v_mfma_f32_32x32x16_bf16 v[80:95], v[218:221], v[124:127], v[80:95]
	ds_read_b128 v[232:235], v151 offset:12544
	s_waitcnt lgkmcnt(2)
	v_mfma_f32_32x32x16_bf16 v[80:95], v[224:227], v[128:131], v[80:95]
	ds_read_b128 v[236:239], v153 offset:12544
	s_waitcnt lgkmcnt(2)
	v_mfma_f32_32x32x16_bf16 v[80:95], v[228:231], v[132:135], v[80:95]
	s_waitcnt lgkmcnt(1)
	v_mfma_f32_32x32x16_bf16 v[80:95], v[232:235], v[136:139], v[80:95]
	s_waitcnt lgkmcnt(0)
	v_mfma_f32_32x32x16_bf16 v[80:95], v[236:239], v[140:143], v[80:95]
	v_mfma_f32_32x32x16_bf16 v[48:63], v[162:165], v[140:143], v[48:63]
	s_andn2_b64 vcc, exec, s[10:11]
	s_cbranch_vccnz .LBB0_1817

.LBB0_1826:
	v_add_u32_e32 v159, s26, v174
	v_add_u32_e32 v162, s26, v175
	v_sub_f32_e32 v48, v48, v157
	v_sub_f32_e32 v49, v49, v157
	v_sub_f32_e32 v50, v50, v157
	v_sub_f32_e32 v51, v51, v157
	v_sub_f32_e32 v52, v52, v157
	v_sub_f32_e32 v53, v53, v157
	v_sub_f32_e32 v54, v54, v157
	v_sub_f32_e32 v55, v55, v157
	v_add_u32_e32 v149, v159, v177
	v_exp_f32_e32 v48, v48
	v_exp_f32_e32 v49, v49
	v_exp_f32_e32 v50, v50
	v_exp_f32_e32 v51, v51
	v_exp_f32_e32 v52, v52
	v_exp_f32_e32 v53, v53
	v_exp_f32_e32 v54, v54
	v_exp_f32_e32 v55, v55
	v_add_u32_e32 v153, v162, v177
	ds_read_b64_tr_b16 v[198:199], v149 offset:24576
	ds_read_b64_tr_b16 v[200:201], v153 offset:26624
	v_add_u32_e32 v147, v159, v178
	v_add_u32_e32 v151, v162, v178
	ds_read_b64_tr_b16 v[202:203], v147 offset:24576
	ds_read_b64_tr_b16 v[204:205], v151 offset:26624
	ds_read_b64_tr_b16 v[208:209], v153 offset:30720
	ds_read_b64_tr_b16 v[206:207], v149 offset:28672
	v_cvt_pk_bf16_f32 v164, v48, v49
	v_cvt_pk_bf16_f32 v165, v50, v51
	v_cvt_pk_bf16_f32 v166, v52, v53
	v_cvt_pk_bf16_f32 v167, v54, v55
	v_add_u32_e32 v158, v159, v179
	v_add_u32_e32 v159, v159, v180
	s_waitcnt lgkmcnt(4)
	v_mfma_f32_32x32x16_bf16 v[64:79], v[198:201], v[164:167], v[64:79]
	v_add_u32_e32 v160, v162, v179
	ds_read_b64_tr_b16 v[198:199], v158 offset:24576
	ds_read_b64_tr_b16 v[200:201], v160 offset:26624
	ds_read_b64_tr_b16 v[212:213], v151 offset:30720
	ds_read_b64_tr_b16 v[210:211], v147 offset:28672
	v_add_u32_e32 v162, v162, v180
	v_add_f32_e32 v163, 0, v48
	v_sub_f32_e32 v56, v56, v157
	v_sub_f32_e32 v57, v57, v157
	v_sub_f32_e32 v58, v58, v157
	s_waitcnt lgkmcnt(6)
	v_mfma_f32_32x32x16_bf16 v[32:47], v[202:205], v[164:167], v[32:47]
	ds_read_b64_tr_b16 v[202:203], v159 offset:24576
	ds_read_b64_tr_b16 v[204:205], v162 offset:26624
	ds_read_b64_tr_b16 v[216:217], v160 offset:30720
	ds_read_b64_tr_b16 v[214:215], v158 offset:28672
	v_sub_f32_e32 v59, v59, v157
	v_sub_f32_e32 v60, v60, v157
	v_sub_f32_e32 v61, v61, v157
	v_sub_f32_e32 v62, v62, v157
	v_sub_f32_e32 v63, v63, v157
	v_add_f32_e32 v163, v49, v163
	s_waitcnt lgkmcnt(6)
	v_mfma_f32_32x32x16_bf16 v[16:31], v[198:201], v[164:167], v[16:31]
	v_exp_f32_e32 v56, v56
	v_exp_f32_e32 v57, v57
	v_exp_f32_e32 v58, v58
	v_exp_f32_e32 v59, v59
	v_exp_f32_e32 v60, v60
	v_exp_f32_e32 v61, v61
	ds_read_b64_tr_b16 v[200:201], v162 offset:30720
	ds_read_b64_tr_b16 v[198:199], v159 offset:28672
	s_waitcnt lgkmcnt(4)
	v_mfma_f32_32x32x16_bf16 v[0:15], v[202:205], v[164:167], v[0:15]
	v_exp_f32_e32 v62, v62
	v_exp_f32_e32 v63, v63
	v_add_f32_e32 v163, v50, v163
	v_add_f32_e32 v163, v51, v163
	v_add_f32_e32 v163, v52, v163
	v_add_f32_e32 v163, v53, v163
	v_cvt_pk_bf16_f32 v164, v56, v57
	v_cvt_pk_bf16_f32 v165, v58, v59
	v_cvt_pk_bf16_f32 v166, v60, v61
	v_cvt_pk_bf16_f32 v167, v62, v63
	v_add_f32_e32 v163, v54, v163
	v_add_f32_e32 v163, v55, v163
	v_mfma_f32_32x32x16_bf16 v[64:79], v[206:209], v[164:167], v[64:79]
	v_add_f32_e32 v163, v56, v163
	v_add_f32_e32 v163, v57, v163
	v_add_f32_e32 v163, v58, v163
	v_add_f32_e32 v163, v59, v163
	v_add_f32_e32 v163, v60, v163
	v_add_f32_e32 v163, v61, v163
	v_add_f32_e32 v163, v62, v163
	v_mfma_f32_32x32x16_bf16 v[32:47], v[210:213], v[164:167], v[32:47]
	v_add_f32_e32 v163, v63, v163
	v_add_f32_e32 v161, v161, v163
	s_waitcnt lgkmcnt(2)
	v_mfma_f32_32x32x16_bf16 v[16:31], v[214:217], v[164:167], v[16:31]
	s_waitcnt lgkmcnt(0)
	v_mfma_f32_32x32x16_bf16 v[0:15], v[198:201], v[164:167], v[0:15]
	v_max_f32_e32 v164, v81, v81
	v_max_f32_e32 v165, v80, v80
	v_max_f32_e32 v164, v165, v164
	v_max3_f32 v164, v164, v82, v83
	v_max3_f32 v164, v164, v84, v85
	v_max3_f32 v164, v164, v86, v87
	v_max3_f32 v164, v164, v88, v89
	v_max3_f32 v164, v164, v90, v91
	v_max3_f32 v164, v164, v92, v93
	v_max3_f32 v164, v164, v94, v95
	v_mov_b32_e32 v163, v164
	s_nop 1
	v_permlane32_swap_b32_e32 v164, v163
	v_max_f32_e32 v163, v164, v163
	v_sub_f32_e32 v163, v163, v157
	v_cmp_lt_f32_e32 vcc, s24, v163
	s_cbranch_vccz .LBB0_1828
	v_max_f32_e32 v163, v163, v163
	v_max_f32_e32 v163, 0, v163
	v_exp_f32_e64 v164, -v163
	v_add_f32_e32 v157, v157, v163
	v_pk_mul_f32 v[78:79], v[78:79], v[164:165] op_sel_hi:[1,0]
	v_pk_mul_f32 v[76:77], v[76:77], v[164:165] op_sel_hi:[1,0]
	v_pk_mul_f32 v[74:75], v[74:75], v[164:165] op_sel_hi:[1,0]
	v_pk_mul_f32 v[72:73], v[72:73], v[164:165] op_sel_hi:[1,0]
	v_pk_mul_f32 v[70:71], v[70:71], v[164:165] op_sel_hi:[1,0]
	v_pk_mul_f32 v[68:69], v[68:69], v[164:165] op_sel_hi:[1,0]
	v_pk_mul_f32 v[66:67], v[66:67], v[164:165] op_sel_hi:[1,0]
	v_pk_mul_f32 v[64:65], v[64:65], v[164:165] op_sel_hi:[1,0]
	v_pk_mul_f32 v[46:47], v[46:47], v[164:165] op_sel_hi:[1,0]
	v_pk_mul_f32 v[44:45], v[44:45], v[164:165] op_sel_hi:[1,0]
	v_pk_mul_f32 v[42:43], v[42:43], v[164:165] op_sel_hi:[1,0]
	v_pk_mul_f32 v[40:41], v[40:41], v[164:165] op_sel_hi:[1,0]
	v_pk_mul_f32 v[38:39], v[38:39], v[164:165] op_sel_hi:[1,0]
	v_pk_mul_f32 v[36:37], v[36:37], v[164:165] op_sel_hi:[1,0]
	v_pk_mul_f32 v[34:35], v[34:35], v[164:165] op_sel_hi:[1,0]
	v_pk_mul_f32 v[32:33], v[32:33], v[164:165] op_sel_hi:[1,0]
	v_pk_mul_f32 v[30:31], v[30:31], v[164:165] op_sel_hi:[1,0]
	v_pk_mul_f32 v[28:29], v[28:29], v[164:165] op_sel_hi:[1,0]
	v_pk_mul_f32 v[26:27], v[26:27], v[164:165] op_sel_hi:[1,0]
	v_pk_mul_f32 v[24:25], v[24:25], v[164:165] op_sel_hi:[1,0]
	v_pk_mul_f32 v[22:23], v[22:23], v[164:165] op_sel_hi:[1,0]
	v_pk_mul_f32 v[20:21], v[20:21], v[164:165] op_sel_hi:[1,0]
	v_pk_mul_f32 v[18:19], v[18:19], v[164:165] op_sel_hi:[1,0]
	v_pk_mul_f32 v[16:17], v[16:17], v[164:165] op_sel_hi:[1,0]
	v_pk_mul_f32 v[14:15], v[14:15], v[164:165] op_sel_hi:[1,0]
	v_pk_mul_f32 v[12:13], v[12:13], v[164:165] op_sel_hi:[1,0]
	v_pk_mul_f32 v[10:11], v[10:11], v[164:165] op_sel_hi:[1,0]
	v_pk_mul_f32 v[8:9], v[8:9], v[164:165] op_sel_hi:[1,0]
	v_pk_mul_f32 v[6:7], v[6:7], v[164:165] op_sel_hi:[1,0]
	v_pk_mul_f32 v[4:5], v[4:5], v[164:165] op_sel_hi:[1,0]
	v_pk_mul_f32 v[2:3], v[2:3], v[164:165] op_sel_hi:[1,0]
	v_pk_mul_f32 v[0:1], v[0:1], v[164:165] op_sel_hi:[1,0]
	v_mul_f32_e32 v161, v161, v164

.LBB0_1829:
	s_setprio 0
	v_mov_b32_e32 v48, v161
	s_nop 1
	v_permlane32_swap_b32_e32 v161, v48
	v_add_f32_e32 v48, v161, v48
	v_div_scale_f32 v49, s[2:3], v48, v48, 1.0
	v_rcp_f32_e32 v50, v49
	s_mulk_i32 s21, 0x2200
	s_add_i32 s7, s21, 0
	v_mul_u32_u24_e32 v195, 0x110, v194
	v_fma_f32 v51, -v49, v50, 1.0
	v_fmac_f32_e32 v50, v51, v50
	v_div_scale_f32 v51, vcc, 1.0, v48, 1.0
	v_mul_f32_e32 v52, v51, v50
	v_fma_f32 v53, -v49, v52, v51
	v_fmac_f32_e32 v52, v53, v50
	v_fma_f32 v49, -v49, v52, v51
	v_div_fmas_f32 v49, v49, v50, v52
	v_div_fixup_f32 v48, v49, v48, 1.0
	v_add3_u32 v49, s7, v195, v181
	v_pk_mul_f32 v[50:51], v[64:65], v[48:49] op_sel_hi:[1,0]
	v_pk_mul_f32 v[52:53], v[66:67], v[48:49] op_sel_hi:[1,0]
	v_cvt_pk_bf16_f32 v50, v50, v51
	v_cvt_pk_bf16_f32 v51, v52, v53
	v_pk_mul_f32 v[52:53], v[68:69], v[48:49] op_sel_hi:[1,0]
	v_pk_mul_f32 v[54:55], v[70:71], v[48:49] op_sel_hi:[1,0]
	v_add_u32_e32 v49, 0xa000, v49
	v_pk_mul_f32 v[32:33], v[32:33], v[48:49] op_sel_hi:[1,0]
	v_pk_mul_f32 v[34:35], v[34:35], v[48:49] op_sel_hi:[1,0]
	v_pk_mul_f32 v[16:17], v[16:17], v[48:49] op_sel_hi:[1,0]
	v_pk_mul_f32 v[18:19], v[18:19], v[48:49] op_sel_hi:[1,0]
	v_pk_mul_f32 v[0:1], v[0:1], v[48:49] op_sel_hi:[1,0]
	v_pk_mul_f32 v[2:3], v[2:3], v[48:49] op_sel_hi:[1,0]
	v_cvt_pk_bf16_f32 v32, v32, v33
	v_cvt_pk_bf16_f32 v33, v34, v35
	v_pk_mul_f32 v[34:35], v[36:37], v[48:49] op_sel_hi:[1,0]
	v_pk_mul_f32 v[36:37], v[38:39], v[48:49] op_sel_hi:[1,0]
	v_cvt_pk_bf16_f32 v16, v16, v17
	v_cvt_pk_bf16_f32 v17, v18, v19
	v_pk_mul_f32 v[18:19], v[20:21], v[48:49] op_sel_hi:[1,0]
	v_pk_mul_f32 v[20:21], v[22:23], v[48:49] op_sel_hi:[1,0]
	v_cvt_pk_bf16_f32 v0, v0, v1
	v_cvt_pk_bf16_f32 v1, v2, v3
	v_pk_mul_f32 v[2:3], v[4:5], v[48:49] op_sel_hi:[1,0]
	v_pk_mul_f32 v[4:5], v[6:7], v[48:49] op_sel_hi:[1,0]
	v_cvt_pk_bf16_f32 v52, v52, v53
	v_cvt_pk_bf16_f32 v53, v54, v55
	v_cvt_pk_bf16_f32 v34, v34, v35
	v_cvt_pk_bf16_f32 v35, v36, v37
	v_cvt_pk_bf16_f32 v18, v18, v19
	v_cvt_pk_bf16_f32 v19, v20, v21
	v_cvt_pk_bf16_f32 v2, v2, v3
	v_cvt_pk_bf16_f32 v3, v4, v5
	s_waitcnt vmcnt(0) lgkmcnt(0)
	s_barrier
	ds_write2_b64 v49, v[50:51], v[52:53] offset1:2
	v_pk_mul_f32 v[50:51], v[72:73], v[48:49] op_sel_hi:[1,0]
	v_pk_mul_f32 v[52:53], v[74:75], v[48:49] op_sel_hi:[1,0]
	ds_write2_b64 v49, v[32:33], v[34:35] offset0:8 offset1:10
	v_pk_mul_f32 v[32:33], v[40:41], v[48:49] op_sel_hi:[1,0]
	v_pk_mul_f32 v[34:35], v[42:43], v[48:49] op_sel_hi:[1,0]
	ds_write2_b64 v49, v[16:17], v[18:19] offset0:16 offset1:18
	v_pk_mul_f32 v[16:17], v[24:25], v[48:49] op_sel_hi:[1,0]
	v_pk_mul_f32 v[18:19], v[26:27], v[48:49] op_sel_hi:[1,0]
	ds_write2_b64 v49, v[0:1], v[2:3] offset0:24 offset1:26
	v_pk_mul_f32 v[0:1], v[8:9], v[48:49] op_sel_hi:[1,0]
	v_pk_mul_f32 v[2:3], v[10:11], v[48:49] op_sel_hi:[1,0]
	v_cvt_pk_bf16_f32 v50, v50, v51
	v_cvt_pk_bf16_f32 v51, v52, v53
	v_pk_mul_f32 v[52:53], v[76:77], v[48:49] op_sel_hi:[1,0]
	v_pk_mul_f32 v[54:55], v[78:79], v[48:49] op_sel_hi:[1,0]
	v_cvt_pk_bf16_f32 v32, v32, v33
	v_cvt_pk_bf16_f32 v33, v34, v35
	v_pk_mul_f32 v[34:35], v[44:45], v[48:49] op_sel_hi:[1,0]
	v_pk_mul_f32 v[36:37], v[46:47], v[48:49] op_sel_hi:[1,0]
	v_cvt_pk_bf16_f32 v16, v16, v17
	v_cvt_pk_bf16_f32 v17, v18, v19
	v_pk_mul_f32 v[18:19], v[28:29], v[48:49] op_sel_hi:[1,0]
	v_pk_mul_f32 v[20:21], v[30:31], v[48:49] op_sel_hi:[1,0]
	v_cvt_pk_bf16_f32 v0, v0, v1
	v_cvt_pk_bf16_f32 v1, v2, v3
	v_pk_mul_f32 v[2:3], v[12:13], v[48:49] op_sel_hi:[1,0]
	v_pk_mul_f32 v[4:5], v[14:15], v[48:49] op_sel_hi:[1,0]
	v_cvt_pk_bf16_f32 v52, v52, v53
	v_cvt_pk_bf16_f32 v53, v54, v55
	v_cvt_pk_bf16_f32 v34, v34, v35
	v_cvt_pk_bf16_f32 v35, v36, v37
	v_cvt_pk_bf16_f32 v18, v18, v19
	v_cvt_pk_bf16_f32 v19, v20, v21
	v_cvt_pk_bf16_f32 v2, v2, v3
	v_cvt_pk_bf16_f32 v3, v4, v5
	s_mulk_i32 s20, 0x1800
	s_mul_hi_u32 s2, s19, 0x1800
	v_lshrrev_b32_e32 v14, 4, v197
	v_and_b32_e32 v164, 15, v222
	ds_write2_b64 v49, v[50:51], v[52:53] offset0:4 offset1:6
	ds_write2_b64 v49, v[32:33], v[34:35] offset0:12 offset1:14
	ds_write2_b64 v49, v[16:17], v[18:19] offset0:20 offset1:22
	ds_write2_b64 v49, v[0:1], v[2:3] offset0:28 offset1:30
	s_add_i32 s2, s2, s20
	s_mulk_i32 s19, 0x1800
	v_lshlrev_b32_e32 v144, 4, v164
	v_mul_u32_u24_e32 v196, 0x110, v14
	s_nop 0
	s_add_u32 s3, s4, s19
	v_add3_u32 v15, s7, v144, v196
	s_addc_u32 s10, s5, s2
	ds_read_b128 v[0:3], v15 offset:40960
	s_add_u32 s2, s3, s6
	s_addc_u32 s3, s10, 0
	v_mov_b32_e32 v145, 0
	v_mul_u32_u24_e32 v16, 0xc00, v14
	ds_read_b128 v[4:7], v15 offset:42048
	v_lshl_add_u64 v[8:9], s[2:3], 0, v[144:145]
	v_lshlrev_b32_e32 v146, 1, v16
	v_mov_b32_e32 v147, v145
	v_lshl_add_u64 v[10:11], v[8:9], 0, v[146:147]
	s_movk_i32 s3, 0x6000
	s_waitcnt lgkmcnt(1)
	global_store_dwordx4 v[10:11], v[0:3], off
	v_mov_b32_e32 v149, v145
	s_movk_i32 s2, 0xc00
	v_add_co_u32_e32 v0, vcc, s3, v10
	s_mov_b32 s3, 0xc000
	s_nop 0
	v_addc_co_u32_e32 v1, vcc, 0, v11, vcc
	s_waitcnt lgkmcnt(0)
	global_store_dwordx4 v[0:1], v[4:7], off
	ds_read_b128 v[0:3], v15 offset:43136
	ds_read_b128 v[4:7], v15 offset:44224
	v_add_co_u32_e32 v12, vcc, s3, v10
	s_mov_b32 s3, 0x12000
	s_nop 0
	v_addc_co_u32_e32 v13, vcc, 0, v11, vcc
	s_waitcnt lgkmcnt(1)
	global_store_dwordx4 v[12:13], v[0:3], off
	v_mov_b32_e32 v153, v145
	v_mov_b32_e32 v151, v145
	v_add_co_u32_e32 v0, vcc, s3, v10
	v_mov_b32_e32 v155, v145
	s_nop 0
	v_addc_co_u32_e32 v1, vcc, 0, v11, vcc
	s_waitcnt lgkmcnt(0)
	global_store_dwordx4 v[0:1], v[4:7], off
	ds_read_b128 v[0:3], v15 offset:45312
	v_readfirstlane_b32 s12, v222
	v_or_b32_e32 v4, 0xc000, v16
	v_lshlrev_b32_e32 v148, 1, v4
	v_lshl_add_u64 v[10:11], v[8:9], 0, v[148:149]
	ds_read_b128 v[4:7], v15 offset:46400
	s_waitcnt lgkmcnt(1)
	global_store_dwordx4 v[10:11], v[0:3], off
	s_nop 1
	v_mov_b32_e32 v0, 0xf000
	v_mad_u32_u24 v0, v14, s2, v0
	v_lshlrev_b32_e32 v152, 1, v0
	v_lshl_add_u64 v[0:1], v[8:9], 0, v[152:153]
	s_waitcnt lgkmcnt(0)
	global_store_dwordx4 v[0:1], v[4:7], off
	ds_read_b128 v[0:3], v15 offset:47488
	s_nop 0
	v_mov_b32_e32 v4, 0x12000
	v_mad_u32_u24 v4, v14, s2, v4
	v_lshlrev_b32_e32 v150, 1, v4
	v_lshl_add_u64 v[10:11], v[8:9], 0, v[150:151]
	ds_read_b128 v[4:7], v15 offset:48576
	s_waitcnt lgkmcnt(1)
	global_store_dwordx4 v[10:11], v[0:3], off
	s_nop 1
	v_mov_b32_e32 v0, 0x15000
	v_mad_u32_u24 v0, v14, s2, v0
	v_lshlrev_b32_e32 v154, 1, v0
	v_lshl_add_u64 v[0:1], v[8:9], 0, v[154:155]
	s_and_b32 s2, s12, 0xffffffc0
	s_waitcnt lgkmcnt(0)
	global_store_dwordx4 v[0:1], v[4:7], off
	v_or_b32_e32 v0, s2, v197
	s_mov_b32 s2, 0x2aaaaaab
	v_mul_hi_i32 v1, v0, s2
	v_lshrrev_b32_e32 v2, 31, v1
	v_ashrrev_i32_e32 v1, 2, v1
	v_add_u32_e32 v2, v1, v2
	s_movk_i32 s2, 0xffe8
	v_lshrrev_b32_e32 v165, 1, v2
	v_mad_u64_u32 v[158:159], s[2:3], v2, s2, v[0:1]
	v_xor_b32_e32 v1, v165, v222
	v_bfi_b32 v1, -8, v158, v1
	v_cmp_lt_i32_e32 vcc, 15, v1
	v_add_u32_e32 v2, s8, v2
	s_and_saveexec_b64 s[2:3], vcc
	s_xor_b64 s[2:3], exec, s[2:3]
	v_mov_b32_e32 v3, 0xbfff80
	v_lshl_add_u32 v155, v2, 6, v3
	s_or_saveexec_b64 s[2:3], s[2:3]
	v_mov_b32_e32 v145, 0x1000
	s_xor_b64 exec, exec, s[2:3]
	v_lshl_or_b32 v2, v2, 11, s17
	v_add_u32_e32 v155, 0x8000000, v2
	v_mov_b32_e32 v145, 0x20000
	s_or_b64 exec, exec, s[2:3]
	v_add_u32_e32 v2, 0x200, v0
	s_mov_b32 s2, 0x2aaaaaab
	v_mul_hi_i32 v3, v2, s2
	v_lshrrev_b32_e32 v4, 31, v3
	v_ashrrev_i32_e32 v3, 2, v3
	v_add_u32_e32 v4, v3, v4
	s_movk_i32 s2, 0xffe8
	v_lshrrev_b32_e32 v166, 1, v4
	v_mad_u64_u32 v[160:161], s[2:3], v4, s2, v[2:3]
	v_xor_b32_e32 v3, v166, v222
	v_bfi_b32 v3, -8, v160, v3
	v_cmp_lt_i32_e32 vcc, 15, v3
	v_add_u32_e32 v4, s8, v4
	s_and_saveexec_b64 s[2:3], vcc
	s_xor_b64 s[2:3], exec, s[2:3]
	v_mov_b32_e32 v5, 0xbfff80
	v_lshl_add_u32 v159, v4, 6, v5
	s_or_saveexec_b64 s[2:3], s[2:3]
	v_mov_b32_e32 v147, 0x1000
	s_xor_b64 exec, exec, s[2:3]
	v_lshl_or_b32 v4, v4, 11, s17
	v_add_u32_e32 v159, 0x8000000, v4
	v_mov_b32_e32 v147, 0x20000
	s_or_b64 exec, exec, s[2:3]
	v_add_u32_e32 v4, 0x400, v0
	s_mov_b32 s2, 0x2aaaaaab
	v_mul_hi_i32 v5, v4, s2
	v_lshrrev_b32_e32 v6, 31, v5
	v_ashrrev_i32_e32 v5, 2, v5
	v_add_u32_e32 v5, v5, v6
	s_movk_i32 s2, 0xffe8
	v_mad_u64_u32 v[162:163], s[2:3], v5, s2, v[4:5]
	v_lshrrev_b32_e32 v163, 1, v5
	v_xor_b32_e32 v4, v163, v222
	v_bfi_b32 v4, -8, v162, v4
	v_cmp_lt_i32_e32 vcc, 15, v4
	v_add_u32_e32 v5, s8, v5
	s_and_saveexec_b64 s[2:3], vcc
	s_xor_b64 s[2:3], exec, s[2:3]
	v_mov_b32_e32 v6, 0xbfff80
	v_lshl_add_u32 v161, v5, 6, v6
	s_or_saveexec_b64 s[2:3], s[2:3]
	v_mov_b32_e32 v149, 0x1000
	s_xor_b64 exec, exec, s[2:3]
	v_lshl_or_b32 v5, v5, 11, s17
	v_add_u32_e32 v161, 0x8000000, v5
	v_mov_b32_e32 v149, 0x20000
	s_or_b64 exec, exec, s[2:3]
	s_lshr_b32 s21, s12, 6
	s_or_b32 s15, s16, 0x1800
	s_lshl_b32 s22, s21, 5
	s_or_b32 s3, s8, s15
	s_add_u32 s19, s3, s22
	s_movk_i32 s2, 0x1800
	v_or_b32_e32 v5, s19, v194
	v_mov_b64_e32 v[6:7], s[4:5]
	s_addc_u32 s20, s9, 0
	v_mad_u64_u32 v[6:7], s[2:3], v5, s2, v[6:7]
	v_mov_b32_e32 v5, 0x1800
	s_mov_b32 s7, 0
	v_mad_i32_i24 v7, s20, v5, v7
	v_lshl_add_u32 v8, v1, 3, v155
	v_ashrrev_i32_e32 v1, 31, v0
	v_lshl_add_u64 v[6:7], v[6:7], 0, s[6:7]
	v_lshlrev_b32_e32 v156, 1, v181
	v_mov_b32_e32 v157, 0
	v_lshrrev_b32_e32 v10, 28, v1
	v_lshl_add_u64 v[6:7], v[6:7], 0, v[156:157]
	v_lshl_add_u32 v4, v4, 3, v161
	v_mov_b32_e32 v5, v157
	v_add_u32_e32 v16, v0, v10
	global_load_dwordx4 v[96:99], v[6:7], off
	global_load_dwordx4 v[100:103], v[6:7], off offset:32
	global_load_dwordx4 v[104:107], v[6:7], off offset:64
	global_load_dwordx4 v[108:111], v[6:7], off offset:96
	global_load_dwordx4 v[112:115], v[6:7], off offset:128
	global_load_dwordx4 v[116:119], v[6:7], off offset:160
	global_load_dwordx4 v[120:123], v[6:7], off offset:192
	global_load_dwordx4 v[124:127], v[6:7], off offset:224
	global_load_dwordx4 v[128:131], v[6:7], off offset:256
	global_load_dwordx4 v[132:135], v[6:7], off offset:288
	global_load_dwordx4 v[136:139], v[6:7], off offset:320
	global_load_dwordx4 v[140:143], v[6:7], off offset:352
	v_lshl_add_u32 v6, v3, 3, v159
	v_ashrrev_i32_e32 v3, 31, v2
	v_lshl_add_u64 v[14:15], v[4:5], 1, s[84:85]
	v_ashrrev_i32_e32 v167, 4, v16
	v_and_b32_e32 v5, 0x1ffffff0, v16
	v_lshrrev_b32_e32 v11, 28, v3
	v_mov_b32_e32 v9, v157
	s_lshl_b32 s2, s21, 10
	v_sub_u32_e32 v0, v0, v5
	v_lshlrev_b32_e32 v5, 2, v167
	v_mov_b32_e32 v7, v157
	v_add_u32_e32 v17, v2, v11
	v_lshl_add_u64 v[10:11], v[8:9], 1, s[84:85]
	v_bfe_u32 v9, v167, 2, 2
	s_add_i32 s7, s2, 0
	v_and_b32_e32 v5, 12, v5
	v_lshl_add_u64 v[12:13], v[6:7], 1, s[84:85]
	v_ashrrev_i32_e32 v168, 4, v17
	v_and_b32_e32 v7, 0x1ffffff0, v17
	v_bitop3_b32 v0, v5, v0, v9 bitop3:0x36
	s_mov_b32 m0, s7
	v_add_lshl_u32 v16, v167, s8, 11
	v_sub_u32_e32 v2, v2, v7
	v_lshlrev_b32_e32 v7, 2, v168
	global_load_lds_dwordx4 v[10:11], off
	s_add_i32 m0, s7, 0x2000
	v_lshlrev_b32_e32 v169, 3, v0
	v_mov_b32_e32 v1, v157
	v_bfe_u32 v17, v168, 2, 2
	v_and_b32_e32 v7, 12, v7
	global_load_lds_dwordx4 v[12:13], off
	s_add_i32 m0, s7, 0x4000
	v_add3_u32 v0, s18, v16, v169
	v_bitop3_b32 v2, v7, v2, v17 bitop3:0x36
	global_load_lds_dwordx4 v[14:15], off
	s_add_i32 m0, s7, 0x6000
	v_lshl_add_u64 v[10:11], v[0:1], 1, s[84:85]
	v_add_lshl_u32 v18, v168, s8, 11
	v_lshlrev_b32_e32 v198, 3, v2
	global_load_lds_dwordx4 v[10:11], off
	s_add_i32 m0, s7, 0x8000
	v_mov_b32_e32 v3, v157
	v_add3_u32 v2, s18, v18, v198
	s_cmpk_gt_u32 s12, 0xff
	v_lshl_add_u64 v[12:13], v[2:3], 1, s[84:85]
	s_cselect_b64 s[10:11], -1, 0
	s_cmpk_lt_u32 s12, 0x100
	v_add_u32_e32 v8, v8, v145
	v_mov_b32_e32 v9, v157
	global_load_lds_dwordx4 v[12:13], off
	s_cselect_b64 s[12:13], -1, 0
	s_add_i32 m0, s7, 0xa000
	v_lshl_add_u64 v[8:9], v[8:9], 1, s[84:85]
	v_add_u32_e32 v6, v6, v147
	v_mov_b32_e32 v7, v157
	s_waitcnt vmcnt(0) lgkmcnt(0)
	s_barrier
	s_waitcnt vmcnt(0)
	global_load_lds_dwordx4 v[8:9], off
	v_lshl_add_u64 v[6:7], v[6:7], 1, s[84:85]
	s_add_i32 m0, s7, 0xc000
	v_add_u32_e32 v4, v4, v149
	v_mov_b32_e32 v5, v157
	global_load_lds_dwordx4 v[6:7], off
	v_lshl_add_u64 v[4:5], v[4:5], 1, s[84:85]
	s_add_i32 m0, s7, 0xe000
	v_add_u32_e32 v0, 0x20000, v0
	v_mov_b32_e32 v1, v157
	global_load_lds_dwordx4 v[4:5], off
	s_add_i32 m0, s7, 0x10000
	v_lshl_add_u64 v[0:1], v[0:1], 1, s[84:85]
	global_load_lds_dwordx4 v[0:1], off
	v_add_u32_e32 v0, 0x20000, v2
	v_mov_b32_e32 v1, v157
	v_lshl_add_u64 v[0:1], v[0:1], 1, s[84:85]
	s_add_i32 m0, s7, 0x12000
	s_and_b64 vcc, exec, s[12:13]
	global_load_lds_dwordx4 v[0:1], off
	ds_read_b128 v[0:3], v190
	ds_read_b128 v[4:7], v191
	ds_read_b128 v[8:11], v192
	ds_read_b128 v[12:15], v193
	s_waitcnt lgkmcnt(3)
	v_mfma_f32_32x32x16_bf16 v[48:63], v[0:3], v[96:99], 0
	ds_read_b128 v[0:3], v190 offset:128
	s_waitcnt lgkmcnt(3)
	v_mfma_f32_32x32x16_bf16 v[48:63], v[4:7], v[100:103], v[48:63]
	ds_read_b128 v[4:7], v191 offset:128
	s_waitcnt lgkmcnt(3)
	v_mfma_f32_32x32x16_bf16 v[48:63], v[8:11], v[104:107], v[48:63]
	ds_read_b128 v[8:11], v192 offset:128
	s_waitcnt lgkmcnt(3)
	v_mfma_f32_32x32x16_bf16 v[48:63], v[12:15], v[108:111], v[48:63]
	ds_read_b128 v[12:15], v193 offset:128
	s_waitcnt lgkmcnt(3)
	v_mfma_f32_32x32x16_bf16 v[48:63], v[0:3], v[112:115], v[48:63]
	ds_read_b128 v[0:3], v190 offset:256
	s_waitcnt lgkmcnt(3)
	v_mfma_f32_32x32x16_bf16 v[48:63], v[4:7], v[116:119], v[48:63]
	ds_read_b128 v[4:7], v191 offset:256
	s_waitcnt lgkmcnt(3)
	v_mfma_f32_32x32x16_bf16 v[48:63], v[8:11], v[120:123], v[48:63]
	ds_read_b128 v[8:11], v192 offset:256
	s_waitcnt lgkmcnt(3)
	v_mfma_f32_32x32x16_bf16 v[48:63], v[12:15], v[124:127], v[48:63]
	ds_read_b128 v[12:15], v193 offset:256
	s_waitcnt lgkmcnt(3)
	v_mfma_f32_32x32x16_bf16 v[48:63], v[0:3], v[128:131], v[48:63]
	ds_read_b128 v[0:3], v190 offset:12288
	s_waitcnt lgkmcnt(3)
	v_mfma_f32_32x32x16_bf16 v[48:63], v[4:7], v[132:135], v[48:63]
	ds_read_b128 v[4:7], v191 offset:12288
	s_waitcnt lgkmcnt(3)
	v_mfma_f32_32x32x16_bf16 v[48:63], v[8:11], v[136:139], v[48:63]
	ds_read_b128 v[8:11], v192 offset:12288
	s_waitcnt lgkmcnt(2)
	v_mfma_f32_32x32x16_bf16 v[80:95], v[0:3], v[96:99], 0
	ds_read_b128 v[16:19], v193 offset:12288
	s_waitcnt lgkmcnt(2)
	v_mfma_f32_32x32x16_bf16 v[80:95], v[4:7], v[100:103], v[80:95]
	ds_read_b128 v[20:23], v190 offset:12416
	s_waitcnt lgkmcnt(2)
	v_mfma_f32_32x32x16_bf16 v[80:95], v[8:11], v[104:107], v[80:95]
	ds_read_b128 v[24:27], v191 offset:12416
	s_waitcnt lgkmcnt(2)
	v_mfma_f32_32x32x16_bf16 v[80:95], v[16:19], v[108:111], v[80:95]
	ds_read_b128 v[28:31], v192 offset:12416
	s_waitcnt lgkmcnt(2)
	v_mfma_f32_32x32x16_bf16 v[80:95], v[20:23], v[112:115], v[80:95]
	ds_read_b128 v[32:35], v193 offset:12416
	s_waitcnt lgkmcnt(2)
	v_mfma_f32_32x32x16_bf16 v[80:95], v[24:27], v[116:119], v[80:95]
	ds_read_b128 v[36:39], v190 offset:12544
	s_waitcnt lgkmcnt(2)
	v_mfma_f32_32x32x16_bf16 v[80:95], v[28:31], v[120:123], v[80:95]
	ds_read_b128 v[40:43], v191 offset:12544
	s_waitcnt lgkmcnt(2)
	v_mfma_f32_32x32x16_bf16 v[80:95], v[32:35], v[124:127], v[80:95]
	ds_read_b128 v[44:47], v192 offset:12544
	s_waitcnt lgkmcnt(2)
	v_mfma_f32_32x32x16_bf16 v[80:95], v[36:39], v[128:131], v[80:95]
	ds_read_b128 v[64:67], v193 offset:12544
	s_waitcnt lgkmcnt(2)
	v_mfma_f32_32x32x16_bf16 v[80:95], v[40:43], v[132:135], v[80:95]
	s_waitcnt lgkmcnt(1)
	v_mfma_f32_32x32x16_bf16 v[80:95], v[44:47], v[136:139], v[80:95]
	s_waitcnt lgkmcnt(0)
	v_mfma_f32_32x32x16_bf16 v[80:95], v[64:67], v[140:143], v[80:95]
	v_mfma_f32_32x32x16_bf16 v[48:63], v[12:15], v[140:143], v[48:63]
	s_cbranch_vccnz .LBB0_1843
	s_waitcnt vmcnt(0) lgkmcnt(0)
	s_barrier
.LBB0_1843:
	s_nop 10
	v_max_f32_e32 v0, v48, v49
	v_max3_f32 v0, v0, v50, v51
	v_max3_f32 v0, v0, v52, v53
	v_max3_f32 v0, v0, v54, v55
	v_max3_f32 v0, v0, v56, v57
	v_max3_f32 v0, v0, v58, v59
	v_max3_f32 v0, v0, v60, v61
	v_max3_f32 v0, v0, v62, v63
	v_mov_b32_e32 v1, v0
	s_nop 1
	v_permlane32_swap_b32_e32 v0, v1
	v_max_f32_e32 v0, v0, v1
	s_cmp_lg_u64 exec, 0
	v_add_f32_e32 v0, 0, v0
	s_cselect_b64 vcc, -1, 0
	v_cndmask_b32_e32 v151, 0, v0, vcc
	v_sub_f32_e32 v0, v48, v151
	v_exp_f32_e32 v48, v0
	v_sub_f32_e32 v0, v49, v151
	v_exp_f32_e32 v49, v0
	v_sub_f32_e32 v0, v50, v151
	v_exp_f32_e32 v50, v0
	v_sub_f32_e32 v0, v51, v151
	v_exp_f32_e32 v51, v0
	v_sub_f32_e32 v0, v52, v151
	v_exp_f32_e32 v52, v0
	v_sub_f32_e32 v0, v53, v151
	v_exp_f32_e32 v53, v0
	v_sub_f32_e32 v0, v54, v151
	v_exp_f32_e32 v54, v0
	v_sub_f32_e32 v0, v55, v151
	v_exp_f32_e32 v55, v0
	v_sub_f32_e32 v0, v56, v151
	v_exp_f32_e32 v56, v0
	ds_read_b64_tr_b16 v[0:1], v183 offset:24576
	ds_read_b64_tr_b16 v[2:3], v185 offset:26624
	v_cvt_pk_bf16_f32 v4, v48, v49
	v_cvt_pk_bf16_f32 v5, v50, v51
	v_cvt_pk_bf16_f32 v6, v52, v53
	v_cvt_pk_bf16_f32 v7, v54, v55
	ds_read_b64_tr_b16 v[8:9], v182 offset:24576
	ds_read_b64_tr_b16 v[10:11], v184 offset:26624
	ds_read_b64_tr_b16 v[202:203], v185 offset:30720
	ds_read_b64_tr_b16 v[200:201], v183 offset:28672
	s_waitcnt lgkmcnt(4)
	v_mfma_f32_32x32x16_bf16 v[64:79], v[0:3], v[4:7], 0
	v_sub_f32_e32 v0, v57, v151
	v_add_f32_e32 v153, 0, v48
	v_exp_f32_e32 v57, v0
	ds_read_b64_tr_b16 v[0:1], v186 offset:24576
	ds_read_b64_tr_b16 v[2:3], v188 offset:26624
	ds_read_b64_tr_b16 v[206:207], v184 offset:30720
	ds_read_b64_tr_b16 v[204:205], v182 offset:28672
	v_add_f32_e32 v153, v49, v153
	v_add_f32_e32 v153, v50, v153
	v_add_f32_e32 v153, v51, v153
	s_waitcnt lgkmcnt(6)
	v_mfma_f32_32x32x16_bf16 v[32:47], v[8:11], v[4:7], 0
	v_sub_f32_e32 v8, v59, v151
	v_exp_f32_e32 v59, v8
	ds_read_b64_tr_b16 v[8:9], v187 offset:24576
	ds_read_b64_tr_b16 v[10:11], v189 offset:26624
	ds_read_b64_tr_b16 v[210:211], v188 offset:30720
	ds_read_b64_tr_b16 v[208:209], v186 offset:28672
	v_add_f32_e32 v153, v52, v153
	v_sub_f32_e32 v12, v58, v151
	v_add_f32_e32 v153, v53, v153
	v_exp_f32_e32 v58, v12
	s_waitcnt lgkmcnt(6)
	v_mfma_f32_32x32x16_bf16 v[16:31], v[0:3], v[4:7], 0
	v_sub_f32_e32 v0, v60, v151
	v_exp_f32_e32 v60, v0
	v_sub_f32_e32 v0, v61, v151
	v_exp_f32_e32 v61, v0
	v_add_f32_e32 v153, v54, v153
	v_add_f32_e32 v153, v55, v153
	v_max_f32_e32 v157, v81, v81
	s_waitcnt lgkmcnt(2)
	v_mfma_f32_32x32x16_bf16 v[0:15], v[8:11], v[4:7], 0
	v_max_f32_e32 v199, v80, v80
	v_sub_f32_e32 v62, v62, v151
	v_sub_f32_e32 v63, v63, v151
	v_add_f32_e32 v153, v56, v153
	v_max_f32_e32 v157, v199, v157
	ds_read_b64_tr_b16 v[214:215], v189 offset:30720
	ds_read_b64_tr_b16 v[212:213], v187 offset:28672
	v_exp_f32_e32 v62, v62
	v_exp_f32_e32 v63, v63
	v_add_f32_e32 v153, v57, v153
	v_max3_f32 v157, v157, v82, v83
	v_add_f32_e32 v153, v58, v153
	v_max3_f32 v157, v157, v84, v85
	v_add_f32_e32 v153, v59, v153
	v_max3_f32 v157, v157, v86, v87
	v_add_f32_e32 v153, v60, v153
	v_max3_f32 v157, v157, v88, v89
	v_cvt_pk_bf16_f32 v216, v56, v57
	v_cvt_pk_bf16_f32 v217, v58, v59
	v_cvt_pk_bf16_f32 v218, v60, v61
	v_cvt_pk_bf16_f32 v219, v62, v63
	v_add_f32_e32 v153, v61, v153
	v_max3_f32 v157, v157, v90, v91
	v_mfma_f32_32x32x16_bf16 v[64:79], v[200:203], v[216:219], v[64:79]
	v_add_f32_e32 v153, v62, v153
	v_max3_f32 v157, v157, v92, v93
	v_add_f32_e32 v153, v63, v153
	v_max3_f32 v199, v157, v94, v95
	v_add_f32_e32 v157, 0, v153
	v_mov_b32_e32 v153, v199
	s_nop 1
	v_permlane32_swap_b32_e32 v199, v153
	v_mfma_f32_32x32x16_bf16 v[32:47], v[204:207], v[216:219], v[32:47]
	v_max_f32_e32 v153, v153, v153
	v_max_f32_e32 v199, v199, v199
	v_max_f32_e32 v153, v199, v153
	v_sub_f32_e32 v153, v153, v151
	s_mov_b32 s2, 0x41000000
	v_cmp_lt_f32_e32 vcc, s2, v153
	s_waitcnt lgkmcnt(2)
	v_mfma_f32_32x32x16_bf16 v[16:31], v[208:211], v[216:219], v[16:31]
	s_waitcnt lgkmcnt(0)
	v_mfma_f32_32x32x16_bf16 v[0:15], v[212:215], v[216:219], v[0:15]
	s_cbranch_vccz .LBB0_1845
	v_max_f32_e32 v153, v153, v153
	v_max_f32_e32 v153, 0, v153
	v_exp_f32_e64 v200, -v153
	v_add_f32_e32 v151, v151, v153
	v_pk_mul_f32 v[78:79], v[78:79], v[200:201] op_sel_hi:[1,0]
	v_pk_mul_f32 v[76:77], v[76:77], v[200:201] op_sel_hi:[1,0]
	v_pk_mul_f32 v[74:75], v[74:75], v[200:201] op_sel_hi:[1,0]
	v_pk_mul_f32 v[72:73], v[72:73], v[200:201] op_sel_hi:[1,0]
	v_pk_mul_f32 v[70:71], v[70:71], v[200:201] op_sel_hi:[1,0]
	v_pk_mul_f32 v[68:69], v[68:69], v[200:201] op_sel_hi:[1,0]
	v_pk_mul_f32 v[66:67], v[66:67], v[200:201] op_sel_hi:[1,0]
	v_pk_mul_f32 v[64:65], v[64:65], v[200:201] op_sel_hi:[1,0]
	v_pk_mul_f32 v[46:47], v[46:47], v[200:201] op_sel_hi:[1,0]
	v_pk_mul_f32 v[44:45], v[44:45], v[200:201] op_sel_hi:[1,0]
	v_pk_mul_f32 v[42:43], v[42:43], v[200:201] op_sel_hi:[1,0]
	v_pk_mul_f32 v[40:41], v[40:41], v[200:201] op_sel_hi:[1,0]
	v_pk_mul_f32 v[38:39], v[38:39], v[200:201] op_sel_hi:[1,0]
	v_pk_mul_f32 v[36:37], v[36:37], v[200:201] op_sel_hi:[1,0]
	v_pk_mul_f32 v[34:35], v[34:35], v[200:201] op_sel_hi:[1,0]
	v_pk_mul_f32 v[32:33], v[32:33], v[200:201] op_sel_hi:[1,0]
	v_pk_mul_f32 v[30:31], v[30:31], v[200:201] op_sel_hi:[1,0]
	v_pk_mul_f32 v[28:29], v[28:29], v[200:201] op_sel_hi:[1,0]
	v_pk_mul_f32 v[26:27], v[26:27], v[200:201] op_sel_hi:[1,0]
	v_pk_mul_f32 v[24:25], v[24:25], v[200:201] op_sel_hi:[1,0]
	v_pk_mul_f32 v[22:23], v[22:23], v[200:201] op_sel_hi:[1,0]
	v_pk_mul_f32 v[20:21], v[20:21], v[200:201] op_sel_hi:[1,0]
	v_pk_mul_f32 v[18:19], v[18:19], v[200:201] op_sel_hi:[1,0]
	v_pk_mul_f32 v[16:17], v[16:17], v[200:201] op_sel_hi:[1,0]
	v_pk_mul_f32 v[14:15], v[14:15], v[200:201] op_sel_hi:[1,0]
	v_pk_mul_f32 v[12:13], v[12:13], v[200:201] op_sel_hi:[1,0]
	v_pk_mul_f32 v[10:11], v[10:11], v[200:201] op_sel_hi:[1,0]
	v_pk_mul_f32 v[8:9], v[8:9], v[200:201] op_sel_hi:[1,0]
	v_pk_mul_f32 v[6:7], v[6:7], v[200:201] op_sel_hi:[1,0]
	v_pk_mul_f32 v[4:5], v[4:5], v[200:201] op_sel_hi:[1,0]
	v_pk_mul_f32 v[2:3], v[2:3], v[200:201] op_sel_hi:[1,0]
	v_pk_mul_f32 v[0:1], v[0:1], v[200:201] op_sel_hi:[1,0]
	v_mul_f32_e32 v157, v157, v200

.LBB0_1856:
	s_setprio 0
	v_add_u32_e32 v155, s27, v170
	ds_read_b128 v[48:51], v155
	v_add_u32_e32 v161, s27, v171
	v_add_u32_e32 v163, s27, v172
	v_add_u32_e32 v165, s27, v173
	ds_read_b128 v[80:83], v161
	ds_read_b128 v[84:87], v163
	ds_read_b128 v[88:91], v165
	s_waitcnt lgkmcnt(3)
	v_mfma_f32_32x32x16_bf16 v[48:63], v[48:51], v[96:99], 0
	ds_read_b128 v[92:95], v155 offset:128
	s_waitcnt lgkmcnt(3)
	v_mfma_f32_32x32x16_bf16 v[48:63], v[80:83], v[100:103], v[48:63]
	ds_read_b128 v[80:83], v161 offset:128
	s_waitcnt lgkmcnt(3)
	v_mfma_f32_32x32x16_bf16 v[48:63], v[84:87], v[104:107], v[48:63]
	ds_read_b128 v[84:87], v163 offset:128
	s_waitcnt lgkmcnt(3)
	v_mfma_f32_32x32x16_bf16 v[48:63], v[88:91], v[108:111], v[48:63]
	ds_read_b128 v[88:91], v165 offset:128
	s_waitcnt lgkmcnt(3)
	v_mfma_f32_32x32x16_bf16 v[48:63], v[92:95], v[112:115], v[48:63]
	ds_read_b128 v[92:95], v155 offset:256
	s_waitcnt lgkmcnt(3)
	v_mfma_f32_32x32x16_bf16 v[48:63], v[80:83], v[116:119], v[48:63]
	ds_read_b128 v[80:83], v161 offset:256
	s_waitcnt lgkmcnt(3)
	v_mfma_f32_32x32x16_bf16 v[48:63], v[84:87], v[120:123], v[48:63]
	ds_read_b128 v[84:87], v163 offset:256
	s_waitcnt lgkmcnt(3)
	v_mfma_f32_32x32x16_bf16 v[48:63], v[88:91], v[124:127], v[48:63]
	ds_read_b128 v[198:201], v165 offset:256
	s_waitcnt lgkmcnt(3)
	v_mfma_f32_32x32x16_bf16 v[48:63], v[92:95], v[128:131], v[48:63]
	ds_read_b128 v[88:91], v155 offset:12288
	s_waitcnt lgkmcnt(3)
	v_mfma_f32_32x32x16_bf16 v[48:63], v[80:83], v[132:135], v[48:63]
	ds_read_b128 v[202:205], v161 offset:12288
	s_waitcnt lgkmcnt(3)
	v_mfma_f32_32x32x16_bf16 v[48:63], v[84:87], v[136:139], v[48:63]
	ds_read_b128 v[206:209], v163 offset:12288
	s_waitcnt lgkmcnt(2)
	v_mfma_f32_32x32x16_bf16 v[80:95], v[88:91], v[96:99], 0
	ds_read_b128 v[210:213], v165 offset:12288
	s_waitcnt lgkmcnt(2)
	v_mfma_f32_32x32x16_bf16 v[80:95], v[202:205], v[100:103], v[80:95]
	ds_read_b128 v[214:217], v155 offset:12416
	s_waitcnt lgkmcnt(2)
	v_mfma_f32_32x32x16_bf16 v[80:95], v[206:209], v[104:107], v[80:95]
	ds_read_b128 v[218:221], v161 offset:12416
	s_waitcnt lgkmcnt(2)
	v_mfma_f32_32x32x16_bf16 v[80:95], v[210:213], v[108:111], v[80:95]
	ds_read_b128 v[224:227], v163 offset:12416
	s_waitcnt lgkmcnt(2)
	v_mfma_f32_32x32x16_bf16 v[80:95], v[214:217], v[112:115], v[80:95]
	ds_read_b128 v[228:231], v165 offset:12416
	s_waitcnt lgkmcnt(2)
	v_mfma_f32_32x32x16_bf16 v[80:95], v[218:221], v[116:119], v[80:95]
	ds_read_b128 v[232:235], v155 offset:12544
	s_waitcnt lgkmcnt(2)
	v_mfma_f32_32x32x16_bf16 v[80:95], v[224:227], v[120:123], v[80:95]
	ds_read_b128 v[236:239], v161 offset:12544
	s_waitcnt lgkmcnt(2)
	v_mfma_f32_32x32x16_bf16 v[80:95], v[228:231], v[124:127], v[80:95]
	ds_read_b128 v[240:243], v163 offset:12544
	s_waitcnt lgkmcnt(2)
	v_mfma_f32_32x32x16_bf16 v[80:95], v[232:235], v[128:131], v[80:95]
	ds_read_b128 v[244:247], v165 offset:12544
	s_waitcnt lgkmcnt(2)
	v_mfma_f32_32x32x16_bf16 v[80:95], v[236:239], v[132:135], v[80:95]
	s_waitcnt lgkmcnt(1)
	v_mfma_f32_32x32x16_bf16 v[80:95], v[240:243], v[136:139], v[80:95]
	s_waitcnt lgkmcnt(0)
	v_mfma_f32_32x32x16_bf16 v[80:95], v[244:247], v[140:143], v[80:95]
	v_mfma_f32_32x32x16_bf16 v[48:63], v[198:201], v[140:143], v[48:63]
	s_andn2_b64 vcc, exec, s[10:11]
	s_cbranch_vccnz .LBB0_1851

.LBB0_1860:
	v_add_u32_e32 v168, s27, v174
	v_add_u32_e32 v198, s27, v175
	v_sub_f32_e32 v48, v48, v151
	v_sub_f32_e32 v49, v49, v151
	v_sub_f32_e32 v50, v50, v151
	v_sub_f32_e32 v51, v51, v151
	v_sub_f32_e32 v52, v52, v151
	v_sub_f32_e32 v53, v53, v151
	v_sub_f32_e32 v54, v54, v151
	v_sub_f32_e32 v55, v55, v151
	v_add_u32_e32 v161, v168, v177
	v_exp_f32_e32 v48, v48
	v_exp_f32_e32 v49, v49
	v_exp_f32_e32 v50, v50
	v_exp_f32_e32 v51, v51
	v_exp_f32_e32 v52, v52
	v_exp_f32_e32 v53, v53
	v_exp_f32_e32 v54, v54
	v_exp_f32_e32 v55, v55
	v_add_u32_e32 v165, v198, v177
	ds_read_b64_tr_b16 v[204:205], v161 offset:24576
	ds_read_b64_tr_b16 v[206:207], v165 offset:26624
	v_add_u32_e32 v155, v168, v178
	v_add_u32_e32 v163, v198, v178
	ds_read_b64_tr_b16 v[208:209], v155 offset:24576
	ds_read_b64_tr_b16 v[210:211], v163 offset:26624
	ds_read_b64_tr_b16 v[214:215], v165 offset:30720
	ds_read_b64_tr_b16 v[212:213], v161 offset:28672
	v_cvt_pk_bf16_f32 v200, v48, v49
	v_cvt_pk_bf16_f32 v201, v50, v51
	v_cvt_pk_bf16_f32 v202, v52, v53
	v_cvt_pk_bf16_f32 v203, v54, v55
	v_add_u32_e32 v167, v168, v179
	v_add_u32_e32 v168, v168, v180
	s_waitcnt lgkmcnt(4)
	v_mfma_f32_32x32x16_bf16 v[64:79], v[204:207], v[200:203], v[64:79]
	v_add_u32_e32 v169, v198, v179
	ds_read_b64_tr_b16 v[204:205], v167 offset:24576
	ds_read_b64_tr_b16 v[206:207], v169 offset:26624
	ds_read_b64_tr_b16 v[218:219], v163 offset:30720
	ds_read_b64_tr_b16 v[216:217], v155 offset:28672
	v_add_u32_e32 v198, v198, v180
	v_add_f32_e32 v199, 0, v48
	v_sub_f32_e32 v56, v56, v151
	v_sub_f32_e32 v57, v57, v151
	v_sub_f32_e32 v58, v58, v151
	s_waitcnt lgkmcnt(6)
	v_mfma_f32_32x32x16_bf16 v[32:47], v[208:211], v[200:203], v[32:47]
	ds_read_b64_tr_b16 v[208:209], v168 offset:24576
	ds_read_b64_tr_b16 v[210:211], v198 offset:26624
	ds_read_b64_tr_b16 v[226:227], v169 offset:30720
	ds_read_b64_tr_b16 v[224:225], v167 offset:28672
	v_sub_f32_e32 v59, v59, v151
	v_sub_f32_e32 v60, v60, v151
	v_sub_f32_e32 v61, v61, v151
	v_sub_f32_e32 v62, v62, v151
	v_sub_f32_e32 v63, v63, v151
	v_add_f32_e32 v199, v49, v199
	s_waitcnt lgkmcnt(6)
	v_mfma_f32_32x32x16_bf16 v[16:31], v[204:207], v[200:203], v[16:31]
	v_exp_f32_e32 v56, v56
	v_exp_f32_e32 v57, v57
	v_exp_f32_e32 v58, v58
	v_exp_f32_e32 v59, v59
	v_exp_f32_e32 v60, v60
	v_exp_f32_e32 v61, v61
	ds_read_b64_tr_b16 v[206:207], v198 offset:30720
	ds_read_b64_tr_b16 v[204:205], v168 offset:28672
	s_waitcnt lgkmcnt(4)
	v_mfma_f32_32x32x16_bf16 v[0:15], v[208:211], v[200:203], v[0:15]
	v_exp_f32_e32 v62, v62
	v_exp_f32_e32 v63, v63
	v_add_f32_e32 v199, v50, v199
	v_add_f32_e32 v199, v51, v199
	v_add_f32_e32 v199, v52, v199
	v_add_f32_e32 v199, v53, v199
	v_cvt_pk_bf16_f32 v200, v56, v57
	v_cvt_pk_bf16_f32 v201, v58, v59
	v_cvt_pk_bf16_f32 v202, v60, v61
	v_cvt_pk_bf16_f32 v203, v62, v63
	v_add_f32_e32 v199, v54, v199
	v_add_f32_e32 v199, v55, v199
	v_mfma_f32_32x32x16_bf16 v[64:79], v[212:215], v[200:203], v[64:79]
	v_add_f32_e32 v199, v56, v199
	v_add_f32_e32 v199, v57, v199
	v_add_f32_e32 v199, v58, v199
	v_add_f32_e32 v199, v59, v199
	v_add_f32_e32 v199, v60, v199
	v_add_f32_e32 v199, v61, v199
	v_add_f32_e32 v199, v62, v199
	v_mfma_f32_32x32x16_bf16 v[32:47], v[216:219], v[200:203], v[32:47]
	v_add_f32_e32 v199, v63, v199
	v_add_f32_e32 v157, v157, v199
	s_waitcnt lgkmcnt(2)
	v_mfma_f32_32x32x16_bf16 v[16:31], v[224:227], v[200:203], v[16:31]
	s_waitcnt lgkmcnt(0)
	v_mfma_f32_32x32x16_bf16 v[0:15], v[204:207], v[200:203], v[0:15]
	v_max_f32_e32 v200, v81, v81
	v_max_f32_e32 v201, v80, v80
	v_max_f32_e32 v200, v201, v200
	v_max3_f32 v200, v200, v82, v83
	v_max3_f32 v200, v200, v84, v85
	v_max3_f32 v200, v200, v86, v87
	v_max3_f32 v200, v200, v88, v89
	v_max3_f32 v200, v200, v90, v91
	v_max3_f32 v200, v200, v92, v93
	v_max3_f32 v200, v200, v94, v95
	v_mov_b32_e32 v199, v200
	s_nop 1
	v_permlane32_swap_b32_e32 v200, v199
	v_max_f32_e32 v199, v200, v199
	v_sub_f32_e32 v199, v199, v151
	v_cmp_lt_f32_e32 vcc, s26, v199
	s_cbranch_vccz .LBB0_1862
	v_max_f32_e32 v199, v199, v199
	v_max_f32_e32 v199, 0, v199
	v_exp_f32_e64 v200, -v199
	v_add_f32_e32 v151, v151, v199
	v_pk_mul_f32 v[78:79], v[78:79], v[200:201] op_sel_hi:[1,0]
	v_pk_mul_f32 v[76:77], v[76:77], v[200:201] op_sel_hi:[1,0]
	v_pk_mul_f32 v[74:75], v[74:75], v[200:201] op_sel_hi:[1,0]
	v_pk_mul_f32 v[72:73], v[72:73], v[200:201] op_sel_hi:[1,0]
	v_pk_mul_f32 v[70:71], v[70:71], v[200:201] op_sel_hi:[1,0]
	v_pk_mul_f32 v[68:69], v[68:69], v[200:201] op_sel_hi:[1,0]
	v_pk_mul_f32 v[66:67], v[66:67], v[200:201] op_sel_hi:[1,0]
	v_pk_mul_f32 v[64:65], v[64:65], v[200:201] op_sel_hi:[1,0]
	v_pk_mul_f32 v[46:47], v[46:47], v[200:201] op_sel_hi:[1,0]
	v_pk_mul_f32 v[44:45], v[44:45], v[200:201] op_sel_hi:[1,0]
	v_pk_mul_f32 v[42:43], v[42:43], v[200:201] op_sel_hi:[1,0]
	v_pk_mul_f32 v[40:41], v[40:41], v[200:201] op_sel_hi:[1,0]
	v_pk_mul_f32 v[38:39], v[38:39], v[200:201] op_sel_hi:[1,0]
	v_pk_mul_f32 v[36:37], v[36:37], v[200:201] op_sel_hi:[1,0]
	v_pk_mul_f32 v[34:35], v[34:35], v[200:201] op_sel_hi:[1,0]
	v_pk_mul_f32 v[32:33], v[32:33], v[200:201] op_sel_hi:[1,0]
	v_pk_mul_f32 v[30:31], v[30:31], v[200:201] op_sel_hi:[1,0]
	v_pk_mul_f32 v[28:29], v[28:29], v[200:201] op_sel_hi:[1,0]
	v_pk_mul_f32 v[26:27], v[26:27], v[200:201] op_sel_hi:[1,0]
	v_pk_mul_f32 v[24:25], v[24:25], v[200:201] op_sel_hi:[1,0]
	v_pk_mul_f32 v[22:23], v[22:23], v[200:201] op_sel_hi:[1,0]
	v_pk_mul_f32 v[20:21], v[20:21], v[200:201] op_sel_hi:[1,0]
	v_pk_mul_f32 v[18:19], v[18:19], v[200:201] op_sel_hi:[1,0]
	v_pk_mul_f32 v[16:17], v[16:17], v[200:201] op_sel_hi:[1,0]
	v_pk_mul_f32 v[14:15], v[14:15], v[200:201] op_sel_hi:[1,0]
	v_pk_mul_f32 v[12:13], v[12:13], v[200:201] op_sel_hi:[1,0]
	v_pk_mul_f32 v[10:11], v[10:11], v[200:201] op_sel_hi:[1,0]
	v_pk_mul_f32 v[8:9], v[8:9], v[200:201] op_sel_hi:[1,0]
	v_pk_mul_f32 v[6:7], v[6:7], v[200:201] op_sel_hi:[1,0]
	v_pk_mul_f32 v[4:5], v[4:5], v[200:201] op_sel_hi:[1,0]
	v_pk_mul_f32 v[2:3], v[2:3], v[200:201] op_sel_hi:[1,0]
	v_pk_mul_f32 v[0:1], v[0:1], v[200:201] op_sel_hi:[1,0]
	v_mul_f32_e32 v157, v157, v200

.LBB0_1863:
	s_setprio 0
	v_mov_b32_e32 v48, v157
	s_nop 1
	v_permlane32_swap_b32_e32 v157, v48
	v_add_f32_e32 v48, v157, v48
	v_div_scale_f32 v49, s[2:3], v48, v48, 1.0
	v_rcp_f32_e32 v50, v49
	s_mulk_i32 s21, 0x2200
	s_add_i32 s7, s21, 0
	s_waitcnt vmcnt(0) lgkmcnt(0)
	s_barrier
	v_fma_f32 v51, -v49, v50, 1.0
	v_fmac_f32_e32 v50, v51, v50
	v_div_scale_f32 v51, vcc, 1.0, v48, 1.0
	v_mul_f32_e32 v52, v51, v50
	v_fma_f32 v53, -v49, v52, v51
	v_fmac_f32_e32 v52, v53, v50
	v_fma_f32 v49, -v49, v52, v51
	v_div_fmas_f32 v49, v49, v50, v52
	v_div_fixup_f32 v48, v49, v48, 1.0
	v_add3_u32 v49, s7, v195, v181
	v_pk_mul_f32 v[50:51], v[64:65], v[48:49] op_sel_hi:[1,0]
	v_pk_mul_f32 v[52:53], v[66:67], v[48:49] op_sel_hi:[1,0]
	v_cvt_pk_bf16_f32 v50, v50, v51
	v_cvt_pk_bf16_f32 v51, v52, v53
	v_pk_mul_f32 v[52:53], v[68:69], v[48:49] op_sel_hi:[1,0]
	v_pk_mul_f32 v[54:55], v[70:71], v[48:49] op_sel_hi:[1,0]
	v_add_u32_e32 v49, 0xa000, v49
	v_pk_mul_f32 v[32:33], v[32:33], v[48:49] op_sel_hi:[1,0]
	v_pk_mul_f32 v[34:35], v[34:35], v[48:49] op_sel_hi:[1,0]
	v_pk_mul_f32 v[16:17], v[16:17], v[48:49] op_sel_hi:[1,0]
	v_pk_mul_f32 v[18:19], v[18:19], v[48:49] op_sel_hi:[1,0]
	v_pk_mul_f32 v[0:1], v[0:1], v[48:49] op_sel_hi:[1,0]
	v_pk_mul_f32 v[2:3], v[2:3], v[48:49] op_sel_hi:[1,0]
	v_cvt_pk_bf16_f32 v32, v32, v33
	v_cvt_pk_bf16_f32 v33, v34, v35
	v_pk_mul_f32 v[34:35], v[36:37], v[48:49] op_sel_hi:[1,0]
	v_pk_mul_f32 v[36:37], v[38:39], v[48:49] op_sel_hi:[1,0]
	v_cvt_pk_bf16_f32 v16, v16, v17
	v_cvt_pk_bf16_f32 v17, v18, v19
	v_pk_mul_f32 v[18:19], v[20:21], v[48:49] op_sel_hi:[1,0]
	v_pk_mul_f32 v[20:21], v[22:23], v[48:49] op_sel_hi:[1,0]
	v_cvt_pk_bf16_f32 v0, v0, v1
	v_cvt_pk_bf16_f32 v1, v2, v3
	v_pk_mul_f32 v[2:3], v[4:5], v[48:49] op_sel_hi:[1,0]
	v_pk_mul_f32 v[4:5], v[6:7], v[48:49] op_sel_hi:[1,0]
	v_cvt_pk_bf16_f32 v52, v52, v53
	v_cvt_pk_bf16_f32 v53, v54, v55
	v_cvt_pk_bf16_f32 v34, v34, v35
	v_cvt_pk_bf16_f32 v35, v36, v37
	v_cvt_pk_bf16_f32 v18, v18, v19
	v_cvt_pk_bf16_f32 v19, v20, v21
	v_cvt_pk_bf16_f32 v2, v2, v3
	v_cvt_pk_bf16_f32 v3, v4, v5
	ds_write2_b64 v49, v[50:51], v[52:53] offset1:2
	v_pk_mul_f32 v[50:51], v[72:73], v[48:49] op_sel_hi:[1,0]
	v_pk_mul_f32 v[52:53], v[74:75], v[48:49] op_sel_hi:[1,0]
	ds_write2_b64 v49, v[32:33], v[34:35] offset0:8 offset1:10
	v_pk_mul_f32 v[32:33], v[40:41], v[48:49] op_sel_hi:[1,0]
	v_pk_mul_f32 v[34:35], v[42:43], v[48:49] op_sel_hi:[1,0]
	ds_write2_b64 v49, v[16:17], v[18:19] offset0:16 offset1:18
	v_pk_mul_f32 v[16:17], v[24:25], v[48:49] op_sel_hi:[1,0]
	v_pk_mul_f32 v[18:19], v[26:27], v[48:49] op_sel_hi:[1,0]
	ds_write2_b64 v49, v[0:1], v[2:3] offset0:24 offset1:26
	v_pk_mul_f32 v[0:1], v[8:9], v[48:49] op_sel_hi:[1,0]
	v_pk_mul_f32 v[2:3], v[10:11], v[48:49] op_sel_hi:[1,0]
	v_cvt_pk_bf16_f32 v50, v50, v51
	v_cvt_pk_bf16_f32 v51, v52, v53
	v_pk_mul_f32 v[52:53], v[76:77], v[48:49] op_sel_hi:[1,0]
	v_pk_mul_f32 v[54:55], v[78:79], v[48:49] op_sel_hi:[1,0]
	v_cvt_pk_bf16_f32 v32, v32, v33
	v_cvt_pk_bf16_f32 v33, v34, v35
	v_pk_mul_f32 v[34:35], v[44:45], v[48:49] op_sel_hi:[1,0]
	v_pk_mul_f32 v[36:37], v[46:47], v[48:49] op_sel_hi:[1,0]
	v_cvt_pk_bf16_f32 v16, v16, v17
	v_cvt_pk_bf16_f32 v17, v18, v19
	v_pk_mul_f32 v[18:19], v[28:29], v[48:49] op_sel_hi:[1,0]
	v_pk_mul_f32 v[20:21], v[30:31], v[48:49] op_sel_hi:[1,0]
	v_cvt_pk_bf16_f32 v0, v0, v1
	v_cvt_pk_bf16_f32 v1, v2, v3
	v_pk_mul_f32 v[2:3], v[12:13], v[48:49] op_sel_hi:[1,0]
	v_pk_mul_f32 v[4:5], v[14:15], v[48:49] op_sel_hi:[1,0]
	v_cvt_pk_bf16_f32 v52, v52, v53
	v_cvt_pk_bf16_f32 v53, v54, v55
	v_cvt_pk_bf16_f32 v34, v34, v35
	v_cvt_pk_bf16_f32 v35, v36, v37
	v_cvt_pk_bf16_f32 v18, v18, v19
	v_cvt_pk_bf16_f32 v19, v20, v21
	v_cvt_pk_bf16_f32 v2, v2, v3
	v_cvt_pk_bf16_f32 v3, v4, v5
	s_mulk_i32 s20, 0x1800
	s_mul_hi_u32 s2, s19, 0x1800
	ds_write2_b64 v49, v[50:51], v[52:53] offset0:4 offset1:6
	ds_write2_b64 v49, v[32:33], v[34:35] offset0:12 offset1:14
	ds_write2_b64 v49, v[16:17], v[18:19] offset0:20 offset1:22
	ds_write2_b64 v49, v[0:1], v[2:3] offset0:28 offset1:30
	s_add_i32 s2, s2, s20
	s_mulk_i32 s19, 0x1800
	s_nop 0
	s_add_u32 s3, s4, s19
	v_add3_u32 v14, s7, v144, v196
	s_addc_u32 s10, s5, s2
	ds_read_b128 v[0:3], v14 offset:40960
	s_add_u32 s2, s3, s6
	s_addc_u32 s3, s10, 0
	v_lshlrev_b32_e32 v158, 1, v153
	v_mov_b32_e32 v159, 0
	ds_read_b128 v[4:7], v14 offset:42048
	v_lshl_add_u64 v[8:9], s[2:3], 0, v[158:159]
	v_mov_b32_e32 v147, v159
	v_lshl_add_u64 v[10:11], v[8:9], 0, v[146:147]
	s_movk_i32 s2, 0x6000
	s_waitcnt lgkmcnt(1)
	global_store_dwordx4 v[10:11], v[0:3], off
	v_mov_b32_e32 v149, v159
	v_mov_b32_e32 v153, v159
	v_add_co_u32_e32 v0, vcc, s2, v10
	s_mov_b32 s2, 0xc000
	s_nop 0
	v_addc_co_u32_e32 v1, vcc, 0, v11, vcc
	s_waitcnt lgkmcnt(0)
	global_store_dwordx4 v[0:1], v[4:7], off
	ds_read_b128 v[0:3], v14 offset:43136
	ds_read_b128 v[4:7], v14 offset:44224
	v_add_co_u32_e32 v12, vcc, s2, v10
	s_mov_b32 s2, 0x12000
	s_nop 0
	v_addc_co_u32_e32 v13, vcc, 0, v11, vcc
	v_add_co_u32_e32 v10, vcc, s2, v10
	s_waitcnt lgkmcnt(1)
	global_store_dwordx4 v[12:13], v[0:3], off
	v_addc_co_u32_e32 v11, vcc, 0, v11, vcc
	ds_read_b128 v[0:3], v14 offset:45312
	s_waitcnt lgkmcnt(1)
	global_store_dwordx4 v[10:11], v[4:7], off
	ds_read_b128 v[4:7], v14 offset:46400
	v_lshl_add_u64 v[10:11], v[8:9], 0, v[148:149]
	v_mov_b32_e32 v151, v159
	s_waitcnt lgkmcnt(1)
	global_store_dwordx4 v[10:11], v[0:3], off
	v_lshl_add_u64 v[10:11], v[8:9], 0, v[152:153]
	ds_read_b128 v[0:3], v14 offset:47488
	s_waitcnt lgkmcnt(1)
	global_store_dwordx4 v[10:11], v[4:7], off
	ds_read_b128 v[4:7], v14 offset:48576
	v_lshl_add_u64 v[10:11], v[8:9], 0, v[150:151]
	v_mov_b32_e32 v155, v159
	v_readfirstlane_b32 s12, v222
	s_waitcnt lgkmcnt(1)
	global_store_dwordx4 v[10:11], v[0:3], off
	s_and_b32 s2, s12, 0xffffffc0
	s_nop 0
	v_lshl_add_u64 v[0:1], v[8:9], 0, v[154:155]
	s_waitcnt lgkmcnt(0)
	global_store_dwordx4 v[0:1], v[4:7], off
	v_or_b32_e32 v0, s2, v197
	s_mov_b32 s2, 0x2aaaaaab
	v_mul_hi_i32 v1, v0, s2
	v_lshrrev_b32_e32 v2, 31, v1
	v_ashrrev_i32_e32 v1, 2, v1
	v_add_u32_e32 v2, v1, v2
	s_movk_i32 s2, 0xffe8
	v_lshrrev_b32_e32 v159, 1, v2
	v_mad_u64_u32 v[160:161], s[2:3], v2, s2, v[0:1]
	v_xor_b32_e32 v1, v159, v222
	v_bfi_b32 v1, -8, v160, v1
	v_cmp_lt_i32_e32 vcc, 15, v1
	v_add_u32_e32 v2, s8, v2
	s_and_saveexec_b64 s[2:3], vcc
	s_xor_b64 s[2:3], exec, s[2:3]
	v_mov_b32_e32 v3, 0xbfff80
	v_lshl_add_u32 v153, v2, 6, v3
	s_or_saveexec_b64 s[2:3], s[2:3]
	v_mov_b32_e32 v145, 0x1000
	s_xor_b64 exec, exec, s[2:3]
	v_lshl_or_b32 v2, v2, 11, s17
	v_add_u32_e32 v153, 0x8000000, v2
	v_mov_b32_e32 v145, 0x20000
	s_or_b64 exec, exec, s[2:3]
	v_add_u32_e32 v2, 0x200, v0
	s_mov_b32 s2, 0x2aaaaaab
	v_mul_hi_i32 v3, v2, s2
	v_lshrrev_b32_e32 v4, 31, v3
	v_ashrrev_i32_e32 v3, 2, v3
	v_add_u32_e32 v4, v3, v4
	s_movk_i32 s2, 0xffe8
	v_mad_u64_u32 v[162:163], s[2:3], v4, s2, v[2:3]
	v_lshrrev_b32_e32 v163, 1, v4
	v_xor_b32_e32 v3, v163, v222
	v_bfi_b32 v3, -8, v162, v3
	v_cmp_lt_i32_e32 vcc, 15, v3
	v_add_u32_e32 v4, s8, v4
	s_and_saveexec_b64 s[2:3], vcc
	s_xor_b64 s[2:3], exec, s[2:3]
	v_mov_b32_e32 v5, 0xbfff80
	v_lshl_add_u32 v155, v4, 6, v5
	s_or_saveexec_b64 s[2:3], s[2:3]
	v_mov_b32_e32 v147, 0x1000
	s_xor_b64 exec, exec, s[2:3]
	v_lshl_or_b32 v4, v4, 11, s17
	v_add_u32_e32 v155, 0x8000000, v4
	v_mov_b32_e32 v147, 0x20000
	s_or_b64 exec, exec, s[2:3]
	v_add_u32_e32 v4, 0x400, v0
	s_mov_b32 s2, 0x2aaaaaab
	v_mul_hi_i32 v5, v4, s2
	v_lshrrev_b32_e32 v6, 31, v5
	v_ashrrev_i32_e32 v5, 2, v5
	v_add_u32_e32 v5, v5, v6
	s_movk_i32 s2, 0xffe8
	v_mad_u64_u32 v[164:165], s[2:3], v5, s2, v[4:5]
	v_lshrrev_b32_e32 v165, 1, v5
	v_xor_b32_e32 v4, v165, v222
	v_bfi_b32 v4, -8, v164, v4
	v_cmp_lt_i32_e32 vcc, 15, v4
	v_add_u32_e32 v5, s8, v5
	s_and_saveexec_b64 s[2:3], vcc
	s_xor_b64 s[2:3], exec, s[2:3]
	v_mov_b32_e32 v6, 0xbfff80
	v_lshl_add_u32 v161, v5, 6, v6
	s_or_saveexec_b64 s[2:3], s[2:3]
	v_mov_b32_e32 v149, 0x1000
	s_xor_b64 exec, exec, s[2:3]
	v_lshl_or_b32 v5, v5, 11, s17
	v_add_u32_e32 v161, 0x8000000, v5
	v_mov_b32_e32 v149, 0x20000
	s_or_b64 exec, exec, s[2:3]
	s_lshr_b32 s21, s12, 6
	s_xor_b32 s22, s16, 0x1700
	s_lshl_b32 s23, s21, 5
	s_or_b32 s2, s8, s22
	s_add_u32 s19, s2, s23
	v_or_b32_e32 v5, s19, v194
	s_movk_i32 s2, 0x1800
	v_mov_b64_e32 v[6:7], s[4:5]
	s_addc_u32 s20, s9, 0
	v_mad_u64_u32 v[6:7], s[2:3], v5, s2, v[6:7]
	v_mov_b32_e32 v5, 0x1800
	s_mov_b32 s7, 0
	v_mad_i32_i24 v7, s20, v5, v7
	v_lshl_add_u32 v8, v1, 3, v153
	v_ashrrev_i32_e32 v1, 31, v0
	v_lshl_add_u64 v[6:7], v[6:7], 0, s[6:7]
	v_mov_b32_e32 v157, 0
	v_lshrrev_b32_e32 v10, 28, v1
	v_lshl_add_u64 v[6:7], v[6:7], 0, v[156:157]
	v_lshl_add_u32 v4, v4, 3, v161
	v_mov_b32_e32 v5, v157
	v_add_u32_e32 v16, v0, v10
	global_load_dwordx4 v[96:99], v[6:7], off
	global_load_dwordx4 v[100:103], v[6:7], off offset:32
	global_load_dwordx4 v[104:107], v[6:7], off offset:64
	global_load_dwordx4 v[108:111], v[6:7], off offset:96
	global_load_dwordx4 v[112:115], v[6:7], off offset:128
	global_load_dwordx4 v[116:119], v[6:7], off offset:160
	global_load_dwordx4 v[120:123], v[6:7], off offset:192
	global_load_dwordx4 v[124:127], v[6:7], off offset:224
	global_load_dwordx4 v[128:131], v[6:7], off offset:256
	global_load_dwordx4 v[132:135], v[6:7], off offset:288
	global_load_dwordx4 v[136:139], v[6:7], off offset:320
	global_load_dwordx4 v[140:143], v[6:7], off offset:352
	v_lshl_add_u32 v6, v3, 3, v155
	v_ashrrev_i32_e32 v3, 31, v2
	v_lshl_add_u64 v[14:15], v[4:5], 1, s[84:85]
	v_ashrrev_i32_e32 v167, 4, v16
	v_and_b32_e32 v5, 0x1ffffff0, v16
	v_lshrrev_b32_e32 v11, 28, v3
	v_mov_b32_e32 v9, v157
	s_lshl_b32 s2, s21, 10
	v_sub_u32_e32 v0, v0, v5
	v_lshlrev_b32_e32 v5, 2, v167
	v_mov_b32_e32 v7, v157
	v_add_u32_e32 v17, v2, v11
	v_lshl_add_u64 v[10:11], v[8:9], 1, s[84:85]
	v_bfe_u32 v9, v167, 2, 2
	s_add_i32 s7, s2, 0
	v_and_b32_e32 v5, 12, v5
	v_lshl_add_u64 v[12:13], v[6:7], 1, s[84:85]
	v_ashrrev_i32_e32 v166, 4, v17
	v_and_b32_e32 v7, 0x1ffffff0, v17
	v_bitop3_b32 v0, v5, v0, v9 bitop3:0x36
	s_mov_b32 m0, s7
	v_add_lshl_u32 v16, v167, s8, 11
	v_sub_u32_e32 v2, v2, v7
	v_lshlrev_b32_e32 v7, 2, v166
	global_load_lds_dwordx4 v[10:11], off
	s_add_i32 m0, s7, 0x2000
	v_lshlrev_b32_e32 v168, 3, v0
	v_mov_b32_e32 v1, v157
	v_bfe_u32 v17, v166, 2, 2
	v_and_b32_e32 v7, 12, v7
	global_load_lds_dwordx4 v[12:13], off
	s_add_i32 m0, s7, 0x4000
	v_add3_u32 v0, s18, v16, v168
	v_bitop3_b32 v2, v7, v2, v17 bitop3:0x36
	global_load_lds_dwordx4 v[14:15], off
	s_add_i32 m0, s7, 0x6000
	v_lshl_add_u64 v[10:11], v[0:1], 1, s[84:85]
	v_add_lshl_u32 v18, v166, s8, 11
	v_lshlrev_b32_e32 v169, 3, v2
	global_load_lds_dwordx4 v[10:11], off
	s_add_i32 m0, s7, 0x8000
	v_mov_b32_e32 v3, v157
	v_add3_u32 v2, s18, v18, v169
	s_cmpk_gt_u32 s12, 0xff
	v_lshl_add_u64 v[12:13], v[2:3], 1, s[84:85]
	s_cselect_b64 s[10:11], -1, 0
	s_cmpk_lt_u32 s12, 0x100
	v_add_u32_e32 v8, v8, v145
	v_mov_b32_e32 v9, v157
	global_load_lds_dwordx4 v[12:13], off
	s_cselect_b64 s[12:13], -1, 0
	s_add_i32 m0, s7, 0xa000
	v_lshl_add_u64 v[8:9], v[8:9], 1, s[84:85]
	v_add_u32_e32 v6, v6, v147
	v_mov_b32_e32 v7, v157
	s_waitcnt vmcnt(0) lgkmcnt(0)
	s_barrier
	s_waitcnt vmcnt(0)
	global_load_lds_dwordx4 v[8:9], off
	v_lshl_add_u64 v[6:7], v[6:7], 1, s[84:85]
	s_add_i32 m0, s7, 0xc000
	v_add_u32_e32 v4, v4, v149
	v_mov_b32_e32 v5, v157
	global_load_lds_dwordx4 v[6:7], off
	v_lshl_add_u64 v[4:5], v[4:5], 1, s[84:85]
	s_add_i32 m0, s7, 0xe000
	v_add_u32_e32 v0, 0x20000, v0
	v_mov_b32_e32 v1, v157
	global_load_lds_dwordx4 v[4:5], off
	s_add_i32 m0, s7, 0x10000
	v_lshl_add_u64 v[0:1], v[0:1], 1, s[84:85]
	global_load_lds_dwordx4 v[0:1], off
	v_add_u32_e32 v0, 0x20000, v2
	v_mov_b32_e32 v1, v157
	v_lshl_add_u64 v[0:1], v[0:1], 1, s[84:85]
	s_add_i32 m0, s7, 0x12000
	s_and_b64 vcc, exec, s[12:13]
	global_load_lds_dwordx4 v[0:1], off
	ds_read_b128 v[0:3], v190
	ds_read_b128 v[4:7], v191
	ds_read_b128 v[8:11], v192
	ds_read_b128 v[12:15], v193
	s_waitcnt lgkmcnt(3)
	v_mfma_f32_32x32x16_bf16 v[48:63], v[0:3], v[96:99], 0
	ds_read_b128 v[0:3], v190 offset:128
	s_waitcnt lgkmcnt(3)
	v_mfma_f32_32x32x16_bf16 v[48:63], v[4:7], v[100:103], v[48:63]
	ds_read_b128 v[4:7], v191 offset:128
	s_waitcnt lgkmcnt(3)
	v_mfma_f32_32x32x16_bf16 v[48:63], v[8:11], v[104:107], v[48:63]
	ds_read_b128 v[8:11], v192 offset:128
	s_waitcnt lgkmcnt(3)
	v_mfma_f32_32x32x16_bf16 v[48:63], v[12:15], v[108:111], v[48:63]
	ds_read_b128 v[12:15], v193 offset:128
	s_waitcnt lgkmcnt(3)
	v_mfma_f32_32x32x16_bf16 v[48:63], v[0:3], v[112:115], v[48:63]
	ds_read_b128 v[0:3], v190 offset:256
	s_waitcnt lgkmcnt(3)
	v_mfma_f32_32x32x16_bf16 v[48:63], v[4:7], v[116:119], v[48:63]
	ds_read_b128 v[4:7], v191 offset:256
	s_waitcnt lgkmcnt(3)
	v_mfma_f32_32x32x16_bf16 v[48:63], v[8:11], v[120:123], v[48:63]
	ds_read_b128 v[8:11], v192 offset:256
	s_waitcnt lgkmcnt(3)
	v_mfma_f32_32x32x16_bf16 v[48:63], v[12:15], v[124:127], v[48:63]
	ds_read_b128 v[12:15], v193 offset:256
	s_waitcnt lgkmcnt(3)
	v_mfma_f32_32x32x16_bf16 v[48:63], v[0:3], v[128:131], v[48:63]
	ds_read_b128 v[0:3], v190 offset:12288
	s_waitcnt lgkmcnt(3)
	v_mfma_f32_32x32x16_bf16 v[48:63], v[4:7], v[132:135], v[48:63]
	ds_read_b128 v[4:7], v191 offset:12288
	s_waitcnt lgkmcnt(3)
	v_mfma_f32_32x32x16_bf16 v[48:63], v[8:11], v[136:139], v[48:63]
	ds_read_b128 v[8:11], v192 offset:12288
	s_waitcnt lgkmcnt(2)
	v_mfma_f32_32x32x16_bf16 v[80:95], v[0:3], v[96:99], 0
	ds_read_b128 v[16:19], v193 offset:12288
	s_waitcnt lgkmcnt(2)
	v_mfma_f32_32x32x16_bf16 v[80:95], v[4:7], v[100:103], v[80:95]
	ds_read_b128 v[20:23], v190 offset:12416
	s_waitcnt lgkmcnt(2)
	v_mfma_f32_32x32x16_bf16 v[80:95], v[8:11], v[104:107], v[80:95]
	ds_read_b128 v[24:27], v191 offset:12416
	s_waitcnt lgkmcnt(2)
	v_mfma_f32_32x32x16_bf16 v[80:95], v[16:19], v[108:111], v[80:95]
	ds_read_b128 v[28:31], v192 offset:12416
	s_waitcnt lgkmcnt(2)
	v_mfma_f32_32x32x16_bf16 v[80:95], v[20:23], v[112:115], v[80:95]
	ds_read_b128 v[32:35], v193 offset:12416
	s_waitcnt lgkmcnt(2)
	v_mfma_f32_32x32x16_bf16 v[80:95], v[24:27], v[116:119], v[80:95]
	ds_read_b128 v[36:39], v190 offset:12544
	s_waitcnt lgkmcnt(2)
	v_mfma_f32_32x32x16_bf16 v[80:95], v[28:31], v[120:123], v[80:95]
	ds_read_b128 v[40:43], v191 offset:12544
	s_waitcnt lgkmcnt(2)
	v_mfma_f32_32x32x16_bf16 v[80:95], v[32:35], v[124:127], v[80:95]
	ds_read_b128 v[44:47], v192 offset:12544
	s_waitcnt lgkmcnt(2)
	v_mfma_f32_32x32x16_bf16 v[80:95], v[36:39], v[128:131], v[80:95]
	ds_read_b128 v[64:67], v193 offset:12544
	s_waitcnt lgkmcnt(2)
	v_mfma_f32_32x32x16_bf16 v[80:95], v[40:43], v[132:135], v[80:95]
	s_waitcnt lgkmcnt(1)
	v_mfma_f32_32x32x16_bf16 v[80:95], v[44:47], v[136:139], v[80:95]
	s_waitcnt lgkmcnt(0)
	v_mfma_f32_32x32x16_bf16 v[80:95], v[64:67], v[140:143], v[80:95]
	v_mfma_f32_32x32x16_bf16 v[48:63], v[12:15], v[140:143], v[48:63]
	s_cbranch_vccnz .LBB0_1877
	s_waitcnt vmcnt(0) lgkmcnt(0)
	s_barrier
.LBB0_1877:
	s_nop 10
	v_max_f32_e32 v0, v48, v49
	v_max3_f32 v0, v0, v50, v51
	v_max3_f32 v0, v0, v52, v53
	v_max3_f32 v0, v0, v54, v55
	v_max3_f32 v0, v0, v56, v57
	v_max3_f32 v0, v0, v58, v59
	v_max3_f32 v0, v0, v60, v61
	v_max3_f32 v0, v0, v62, v63
	v_mov_b32_e32 v1, v0
	s_nop 1
	v_permlane32_swap_b32_e32 v0, v1
	v_max_f32_e32 v0, v0, v1
	s_cmp_lg_u64 exec, 0
	v_add_f32_e32 v0, 0, v0
	s_cselect_b64 vcc, -1, 0
	v_cndmask_b32_e32 v151, 0, v0, vcc
	v_sub_f32_e32 v0, v48, v151
	v_exp_f32_e32 v48, v0
	v_sub_f32_e32 v0, v49, v151
	v_exp_f32_e32 v49, v0
	v_sub_f32_e32 v0, v50, v151
	v_exp_f32_e32 v50, v0
	v_sub_f32_e32 v0, v51, v151
	v_exp_f32_e32 v51, v0
	v_sub_f32_e32 v0, v52, v151
	v_exp_f32_e32 v52, v0
	v_sub_f32_e32 v0, v53, v151
	v_exp_f32_e32 v53, v0
	v_sub_f32_e32 v0, v54, v151
	v_exp_f32_e32 v54, v0
	v_sub_f32_e32 v0, v55, v151
	v_exp_f32_e32 v55, v0
	v_sub_f32_e32 v0, v56, v151
	v_exp_f32_e32 v56, v0
	ds_read_b64_tr_b16 v[0:1], v183 offset:24576
	ds_read_b64_tr_b16 v[2:3], v185 offset:26624
	v_cvt_pk_bf16_f32 v4, v48, v49
	v_cvt_pk_bf16_f32 v5, v50, v51
	v_cvt_pk_bf16_f32 v6, v52, v53
	v_cvt_pk_bf16_f32 v7, v54, v55
	ds_read_b64_tr_b16 v[8:9], v182 offset:24576
	ds_read_b64_tr_b16 v[10:11], v184 offset:26624
	ds_read_b64_tr_b16 v[200:201], v185 offset:30720
	ds_read_b64_tr_b16 v[198:199], v183 offset:28672
	s_waitcnt lgkmcnt(4)
	v_mfma_f32_32x32x16_bf16 v[64:79], v[0:3], v[4:7], 0
	v_sub_f32_e32 v0, v57, v151
	v_exp_f32_e32 v57, v0
	ds_read_b64_tr_b16 v[0:1], v186 offset:24576
	ds_read_b64_tr_b16 v[2:3], v188 offset:26624
	ds_read_b64_tr_b16 v[204:205], v184 offset:30720
	ds_read_b64_tr_b16 v[202:203], v182 offset:28672
	v_sub_f32_e32 v12, v58, v151
	v_sub_f32_e32 v62, v62, v151
	v_sub_f32_e32 v63, v63, v151
	v_exp_f32_e32 v58, v12
	s_waitcnt lgkmcnt(2)
	v_mfma_f32_32x32x16_bf16 v[16:31], v[0:3], v[4:7], 0
	v_sub_f32_e32 v0, v60, v151
	v_exp_f32_e32 v60, v0
	v_sub_f32_e32 v0, v61, v151
	v_exp_f32_e32 v61, v0
	v_exp_f32_e32 v62, v62
	v_exp_f32_e32 v63, v63
	v_add_f32_e32 v157, 0, v48
	v_mfma_f32_32x32x16_bf16 v[32:47], v[8:11], v[4:7], 0
	v_sub_f32_e32 v8, v59, v151
	v_exp_f32_e32 v59, v8
	ds_read_b64_tr_b16 v[8:9], v187 offset:24576
	ds_read_b64_tr_b16 v[10:11], v189 offset:26624
	ds_read_b64_tr_b16 v[208:209], v188 offset:30720
	ds_read_b64_tr_b16 v[206:207], v186 offset:28672
	v_cvt_pk_bf16_f32 v214, v56, v57
	v_cvt_pk_bf16_f32 v216, v60, v61
	v_cvt_pk_bf16_f32 v215, v58, v59
	v_cvt_pk_bf16_f32 v217, v62, v63
	s_waitcnt lgkmcnt(2)
	v_mfma_f32_32x32x16_bf16 v[0:15], v[8:11], v[4:7], 0
	v_add_f32_e32 v157, v49, v157
	v_add_f32_e32 v157, v50, v157
	v_add_f32_e32 v157, v51, v157
	ds_read_b64_tr_b16 v[212:213], v189 offset:30720
	ds_read_b64_tr_b16 v[210:211], v187 offset:28672
	v_add_f32_e32 v157, v52, v157
	v_add_f32_e32 v157, v53, v157
	v_add_f32_e32 v157, v54, v157
	v_mfma_f32_32x32x16_bf16 v[64:79], v[198:201], v[214:217], v[64:79]
	v_max_f32_e32 v198, v80, v81
	v_max3_f32 v198, v198, v82, v83
	v_max3_f32 v198, v198, v84, v85
	v_max3_f32 v198, v198, v86, v87
	v_add_f32_e32 v157, v55, v157
	v_max3_f32 v198, v198, v88, v89
	v_add_f32_e32 v157, v56, v157
	v_max3_f32 v198, v198, v90, v91
	v_mfma_f32_32x32x16_bf16 v[32:47], v[202:205], v[214:217], v[32:47]
	v_add_f32_e32 v157, v57, v157
	v_max3_f32 v198, v198, v92, v93
	v_add_f32_e32 v157, v58, v157
	v_max3_f32 v198, v198, v94, v95
	v_add_f32_e32 v157, v59, v157
	v_mov_b32_e32 v199, v198
	v_add_f32_e32 v157, v60, v157
	s_waitcnt lgkmcnt(2)
	v_mfma_f32_32x32x16_bf16 v[16:31], v[206:209], v[214:217], v[16:31]
	v_permlane32_swap_b32_e32 v198, v199
	v_add_f32_e32 v157, v61, v157
	v_max_f32_e32 v199, v199, v199
	v_max_f32_e32 v198, v198, v198
	v_add_f32_e32 v157, v62, v157
	v_max_f32_e32 v198, v198, v199
	s_waitcnt lgkmcnt(0)
	v_mfma_f32_32x32x16_bf16 v[0:15], v[210:213], v[214:217], v[0:15]
	v_add_f32_e32 v157, v63, v157
	v_sub_f32_e32 v198, v198, v151
	s_mov_b32 s2, 0x41000000
	v_add_f32_e32 v157, 0, v157
	v_cmp_lt_f32_e32 vcc, s2, v198
	s_cbranch_vccz .LBB0_1879
	v_max_f32_e32 v198, v198, v198
	v_max_f32_e32 v199, 0, v198
	v_exp_f32_e64 v198, -v199
	v_add_f32_e32 v151, v151, v199
	v_pk_mul_f32 v[78:79], v[78:79], v[198:199] op_sel_hi:[1,0]
	v_pk_mul_f32 v[76:77], v[76:77], v[198:199] op_sel_hi:[1,0]
	v_pk_mul_f32 v[74:75], v[74:75], v[198:199] op_sel_hi:[1,0]
	v_pk_mul_f32 v[72:73], v[72:73], v[198:199] op_sel_hi:[1,0]
	v_pk_mul_f32 v[70:71], v[70:71], v[198:199] op_sel_hi:[1,0]
	v_pk_mul_f32 v[68:69], v[68:69], v[198:199] op_sel_hi:[1,0]
	v_pk_mul_f32 v[66:67], v[66:67], v[198:199] op_sel_hi:[1,0]
	v_pk_mul_f32 v[64:65], v[64:65], v[198:199] op_sel_hi:[1,0]
	v_pk_mul_f32 v[46:47], v[46:47], v[198:199] op_sel_hi:[1,0]
	v_pk_mul_f32 v[44:45], v[44:45], v[198:199] op_sel_hi:[1,0]
	v_pk_mul_f32 v[42:43], v[42:43], v[198:199] op_sel_hi:[1,0]
	v_pk_mul_f32 v[40:41], v[40:41], v[198:199] op_sel_hi:[1,0]
	v_pk_mul_f32 v[38:39], v[38:39], v[198:199] op_sel_hi:[1,0]
	v_pk_mul_f32 v[36:37], v[36:37], v[198:199] op_sel_hi:[1,0]
	v_pk_mul_f32 v[34:35], v[34:35], v[198:199] op_sel_hi:[1,0]
	v_pk_mul_f32 v[32:33], v[32:33], v[198:199] op_sel_hi:[1,0]
	v_pk_mul_f32 v[30:31], v[30:31], v[198:199] op_sel_hi:[1,0]
	v_pk_mul_f32 v[28:29], v[28:29], v[198:199] op_sel_hi:[1,0]
	v_pk_mul_f32 v[26:27], v[26:27], v[198:199] op_sel_hi:[1,0]
	v_pk_mul_f32 v[24:25], v[24:25], v[198:199] op_sel_hi:[1,0]
	v_pk_mul_f32 v[22:23], v[22:23], v[198:199] op_sel_hi:[1,0]
	v_pk_mul_f32 v[20:21], v[20:21], v[198:199] op_sel_hi:[1,0]
	v_pk_mul_f32 v[18:19], v[18:19], v[198:199] op_sel_hi:[1,0]
	v_pk_mul_f32 v[16:17], v[16:17], v[198:199] op_sel_hi:[1,0]
	v_pk_mul_f32 v[14:15], v[14:15], v[198:199] op_sel_hi:[1,0]
	v_pk_mul_f32 v[12:13], v[12:13], v[198:199] op_sel_hi:[1,0]
	v_pk_mul_f32 v[10:11], v[10:11], v[198:199] op_sel_hi:[1,0]
	v_pk_mul_f32 v[8:9], v[8:9], v[198:199] op_sel_hi:[1,0]
	v_pk_mul_f32 v[6:7], v[6:7], v[198:199] op_sel_hi:[1,0]
	v_pk_mul_f32 v[4:5], v[4:5], v[198:199] op_sel_hi:[1,0]
	v_pk_mul_f32 v[2:3], v[2:3], v[198:199] op_sel_hi:[1,0]
	v_pk_mul_f32 v[0:1], v[0:1], v[198:199] op_sel_hi:[1,0]
	v_mul_f32_e32 v157, v157, v198

.LBB0_1890:
	s_setprio 0
	v_add_u32_e32 v153, s27, v170
	ds_read_b128 v[48:51], v153
	v_add_u32_e32 v155, s27, v171
	v_add_u32_e32 v159, s27, v172
	v_add_u32_e32 v163, s27, v173
	ds_read_b128 v[80:83], v155
	ds_read_b128 v[84:87], v159
	ds_read_b128 v[88:91], v163
	s_waitcnt lgkmcnt(3)
	v_mfma_f32_32x32x16_bf16 v[48:63], v[48:51], v[96:99], 0
	ds_read_b128 v[92:95], v153 offset:128
	s_waitcnt lgkmcnt(3)
	v_mfma_f32_32x32x16_bf16 v[48:63], v[80:83], v[100:103], v[48:63]
	ds_read_b128 v[80:83], v155 offset:128
	s_waitcnt lgkmcnt(3)
	v_mfma_f32_32x32x16_bf16 v[48:63], v[84:87], v[104:107], v[48:63]
	ds_read_b128 v[84:87], v159 offset:128
	s_waitcnt lgkmcnt(3)
	v_mfma_f32_32x32x16_bf16 v[48:63], v[88:91], v[108:111], v[48:63]
	ds_read_b128 v[88:91], v163 offset:128
	s_waitcnt lgkmcnt(3)
	v_mfma_f32_32x32x16_bf16 v[48:63], v[92:95], v[112:115], v[48:63]
	ds_read_b128 v[92:95], v153 offset:256
	s_waitcnt lgkmcnt(3)
	v_mfma_f32_32x32x16_bf16 v[48:63], v[80:83], v[116:119], v[48:63]
	ds_read_b128 v[80:83], v155 offset:256
	s_waitcnt lgkmcnt(3)
	v_mfma_f32_32x32x16_bf16 v[48:63], v[84:87], v[120:123], v[48:63]
	ds_read_b128 v[84:87], v159 offset:256
	s_waitcnt lgkmcnt(3)
	v_mfma_f32_32x32x16_bf16 v[48:63], v[88:91], v[124:127], v[48:63]
	ds_read_b128 v[198:201], v163 offset:256
	s_waitcnt lgkmcnt(3)
	v_mfma_f32_32x32x16_bf16 v[48:63], v[92:95], v[128:131], v[48:63]
	ds_read_b128 v[88:91], v153 offset:12288
	s_waitcnt lgkmcnt(3)
	v_mfma_f32_32x32x16_bf16 v[48:63], v[80:83], v[132:135], v[48:63]
	ds_read_b128 v[202:205], v155 offset:12288
	s_waitcnt lgkmcnt(3)
	v_mfma_f32_32x32x16_bf16 v[48:63], v[84:87], v[136:139], v[48:63]
	ds_read_b128 v[206:209], v159 offset:12288
	s_waitcnt lgkmcnt(2)
	v_mfma_f32_32x32x16_bf16 v[80:95], v[88:91], v[96:99], 0
	ds_read_b128 v[210:213], v163 offset:12288
	s_waitcnt lgkmcnt(2)
	v_mfma_f32_32x32x16_bf16 v[80:95], v[202:205], v[100:103], v[80:95]
	ds_read_b128 v[214:217], v153 offset:12416
	s_waitcnt lgkmcnt(2)
	v_mfma_f32_32x32x16_bf16 v[80:95], v[206:209], v[104:107], v[80:95]
	ds_read_b128 v[218:221], v155 offset:12416
	s_waitcnt lgkmcnt(2)
	v_mfma_f32_32x32x16_bf16 v[80:95], v[210:213], v[108:111], v[80:95]
	ds_read_b128 v[224:227], v159 offset:12416
	s_waitcnt lgkmcnt(2)
	v_mfma_f32_32x32x16_bf16 v[80:95], v[214:217], v[112:115], v[80:95]
	ds_read_b128 v[228:231], v163 offset:12416
	s_waitcnt lgkmcnt(2)
	v_mfma_f32_32x32x16_bf16 v[80:95], v[218:221], v[116:119], v[80:95]
	ds_read_b128 v[232:235], v153 offset:12544
	s_waitcnt lgkmcnt(2)
	v_mfma_f32_32x32x16_bf16 v[80:95], v[224:227], v[120:123], v[80:95]
	ds_read_b128 v[236:239], v155 offset:12544
	s_waitcnt lgkmcnt(2)
	v_mfma_f32_32x32x16_bf16 v[80:95], v[228:231], v[124:127], v[80:95]
	ds_read_b128 v[240:243], v159 offset:12544
	s_waitcnt lgkmcnt(2)
	v_mfma_f32_32x32x16_bf16 v[80:95], v[232:235], v[128:131], v[80:95]
	ds_read_b128 v[244:247], v163 offset:12544
	s_waitcnt lgkmcnt(2)
	v_mfma_f32_32x32x16_bf16 v[80:95], v[236:239], v[132:135], v[80:95]
	s_waitcnt lgkmcnt(1)
	v_mfma_f32_32x32x16_bf16 v[80:95], v[240:243], v[136:139], v[80:95]
	s_waitcnt lgkmcnt(0)
	v_mfma_f32_32x32x16_bf16 v[80:95], v[244:247], v[140:143], v[80:95]
	v_mfma_f32_32x32x16_bf16 v[48:63], v[198:201], v[140:143], v[48:63]
	s_andn2_b64 vcc, exec, s[10:11]
	s_cbranch_vccnz .LBB0_1885

.LBB0_1894:
	v_add_u32_e32 v167, s27, v174
	v_add_u32_e32 v198, s27, v175
	v_sub_f32_e32 v48, v48, v151
	v_sub_f32_e32 v49, v49, v151
	v_sub_f32_e32 v50, v50, v151
	v_sub_f32_e32 v51, v51, v151
	v_sub_f32_e32 v52, v52, v151
	v_sub_f32_e32 v53, v53, v151
	v_sub_f32_e32 v54, v54, v151
	v_sub_f32_e32 v55, v55, v151
	v_add_u32_e32 v155, v167, v177
	v_exp_f32_e32 v48, v48
	v_exp_f32_e32 v49, v49
	v_exp_f32_e32 v50, v50
	v_exp_f32_e32 v51, v51
	v_exp_f32_e32 v52, v52
	v_exp_f32_e32 v53, v53
	v_exp_f32_e32 v54, v54
	v_exp_f32_e32 v55, v55
	v_add_u32_e32 v163, v198, v177
	ds_read_b64_tr_b16 v[204:205], v155 offset:24576
	ds_read_b64_tr_b16 v[206:207], v163 offset:26624
	v_add_u32_e32 v153, v167, v178
	v_add_u32_e32 v159, v198, v178
	ds_read_b64_tr_b16 v[208:209], v153 offset:24576
	ds_read_b64_tr_b16 v[210:211], v159 offset:26624
	ds_read_b64_tr_b16 v[214:215], v163 offset:30720
	ds_read_b64_tr_b16 v[212:213], v155 offset:28672
	v_cvt_pk_bf16_f32 v200, v48, v49
	v_cvt_pk_bf16_f32 v201, v50, v51
	v_cvt_pk_bf16_f32 v202, v52, v53
	v_cvt_pk_bf16_f32 v203, v54, v55
	v_add_u32_e32 v165, v167, v179
	v_add_u32_e32 v167, v167, v180
	s_waitcnt lgkmcnt(4)
	v_mfma_f32_32x32x16_bf16 v[64:79], v[204:207], v[200:203], v[64:79]
	v_add_u32_e32 v169, v198, v179
	ds_read_b64_tr_b16 v[204:205], v165 offset:24576
	ds_read_b64_tr_b16 v[206:207], v169 offset:26624
	ds_read_b64_tr_b16 v[218:219], v159 offset:30720
	ds_read_b64_tr_b16 v[216:217], v153 offset:28672
	v_add_u32_e32 v198, v198, v180
	v_add_f32_e32 v199, 0, v48
	v_sub_f32_e32 v56, v56, v151
	v_sub_f32_e32 v57, v57, v151
	v_sub_f32_e32 v58, v58, v151
	s_waitcnt lgkmcnt(6)
	v_mfma_f32_32x32x16_bf16 v[32:47], v[208:211], v[200:203], v[32:47]
	ds_read_b64_tr_b16 v[208:209], v167 offset:24576
	ds_read_b64_tr_b16 v[210:211], v198 offset:26624
	ds_read_b64_tr_b16 v[226:227], v169 offset:30720
	ds_read_b64_tr_b16 v[224:225], v165 offset:28672
	v_sub_f32_e32 v59, v59, v151
	v_sub_f32_e32 v60, v60, v151
	v_sub_f32_e32 v61, v61, v151
	v_sub_f32_e32 v62, v62, v151
	v_sub_f32_e32 v63, v63, v151
	v_add_f32_e32 v199, v49, v199
	s_waitcnt lgkmcnt(6)
	v_mfma_f32_32x32x16_bf16 v[16:31], v[204:207], v[200:203], v[16:31]
	v_exp_f32_e32 v56, v56
	v_exp_f32_e32 v57, v57
	v_exp_f32_e32 v58, v58
	v_exp_f32_e32 v59, v59
	v_exp_f32_e32 v60, v60
	v_exp_f32_e32 v61, v61
	ds_read_b64_tr_b16 v[206:207], v198 offset:30720
	ds_read_b64_tr_b16 v[204:205], v167 offset:28672
	s_waitcnt lgkmcnt(4)
	v_mfma_f32_32x32x16_bf16 v[0:15], v[208:211], v[200:203], v[0:15]
	v_exp_f32_e32 v62, v62
	v_exp_f32_e32 v63, v63
	v_add_f32_e32 v199, v50, v199
	v_add_f32_e32 v199, v51, v199
	v_add_f32_e32 v199, v52, v199
	v_add_f32_e32 v199, v53, v199
	v_cvt_pk_bf16_f32 v200, v56, v57
	v_cvt_pk_bf16_f32 v201, v58, v59
	v_cvt_pk_bf16_f32 v202, v60, v61
	v_cvt_pk_bf16_f32 v203, v62, v63
	v_add_f32_e32 v199, v54, v199
	v_add_f32_e32 v199, v55, v199
	v_mfma_f32_32x32x16_bf16 v[64:79], v[212:215], v[200:203], v[64:79]
	v_add_f32_e32 v199, v56, v199
	v_add_f32_e32 v199, v57, v199
	v_add_f32_e32 v199, v58, v199
	v_add_f32_e32 v199, v59, v199
	v_add_f32_e32 v199, v60, v199
	v_add_f32_e32 v199, v61, v199
	v_add_f32_e32 v199, v62, v199
	v_mfma_f32_32x32x16_bf16 v[32:47], v[216:219], v[200:203], v[32:47]
	v_add_f32_e32 v199, v63, v199
	v_add_f32_e32 v157, v157, v199
	s_waitcnt lgkmcnt(2)
	v_mfma_f32_32x32x16_bf16 v[16:31], v[224:227], v[200:203], v[16:31]
	s_waitcnt lgkmcnt(0)
	v_mfma_f32_32x32x16_bf16 v[0:15], v[204:207], v[200:203], v[0:15]
	v_max_f32_e32 v200, v81, v81
	v_max_f32_e32 v201, v80, v80
	v_max_f32_e32 v200, v201, v200
	v_max3_f32 v200, v200, v82, v83
	v_max3_f32 v200, v200, v84, v85
	v_max3_f32 v200, v200, v86, v87
	v_max3_f32 v200, v200, v88, v89
	v_max3_f32 v200, v200, v90, v91
	v_max3_f32 v200, v200, v92, v93
	v_max3_f32 v200, v200, v94, v95
	v_mov_b32_e32 v199, v200
	s_nop 1
	v_permlane32_swap_b32_e32 v200, v199
	v_max_f32_e32 v199, v200, v199
	v_sub_f32_e32 v199, v199, v151
	v_cmp_lt_f32_e32 vcc, s25, v199
	s_cbranch_vccz .LBB0_1896
	v_max_f32_e32 v199, v199, v199
	v_max_f32_e32 v199, 0, v199
	v_exp_f32_e64 v200, -v199
	v_add_f32_e32 v151, v151, v199
	v_pk_mul_f32 v[78:79], v[78:79], v[200:201] op_sel_hi:[1,0]
	v_pk_mul_f32 v[76:77], v[76:77], v[200:201] op_sel_hi:[1,0]
	v_pk_mul_f32 v[74:75], v[74:75], v[200:201] op_sel_hi:[1,0]
	v_pk_mul_f32 v[72:73], v[72:73], v[200:201] op_sel_hi:[1,0]
	v_pk_mul_f32 v[70:71], v[70:71], v[200:201] op_sel_hi:[1,0]
	v_pk_mul_f32 v[68:69], v[68:69], v[200:201] op_sel_hi:[1,0]
	v_pk_mul_f32 v[66:67], v[66:67], v[200:201] op_sel_hi:[1,0]
	v_pk_mul_f32 v[64:65], v[64:65], v[200:201] op_sel_hi:[1,0]
	v_pk_mul_f32 v[46:47], v[46:47], v[200:201] op_sel_hi:[1,0]
	v_pk_mul_f32 v[44:45], v[44:45], v[200:201] op_sel_hi:[1,0]
	v_pk_mul_f32 v[42:43], v[42:43], v[200:201] op_sel_hi:[1,0]
	v_pk_mul_f32 v[40:41], v[40:41], v[200:201] op_sel_hi:[1,0]
	v_pk_mul_f32 v[38:39], v[38:39], v[200:201] op_sel_hi:[1,0]
	v_pk_mul_f32 v[36:37], v[36:37], v[200:201] op_sel_hi:[1,0]
	v_pk_mul_f32 v[34:35], v[34:35], v[200:201] op_sel_hi:[1,0]
	v_pk_mul_f32 v[32:33], v[32:33], v[200:201] op_sel_hi:[1,0]
	v_pk_mul_f32 v[30:31], v[30:31], v[200:201] op_sel_hi:[1,0]
	v_pk_mul_f32 v[28:29], v[28:29], v[200:201] op_sel_hi:[1,0]
	v_pk_mul_f32 v[26:27], v[26:27], v[200:201] op_sel_hi:[1,0]
	v_pk_mul_f32 v[24:25], v[24:25], v[200:201] op_sel_hi:[1,0]
	v_pk_mul_f32 v[22:23], v[22:23], v[200:201] op_sel_hi:[1,0]
	v_pk_mul_f32 v[20:21], v[20:21], v[200:201] op_sel_hi:[1,0]
	v_pk_mul_f32 v[18:19], v[18:19], v[200:201] op_sel_hi:[1,0]
	v_pk_mul_f32 v[16:17], v[16:17], v[200:201] op_sel_hi:[1,0]
	v_pk_mul_f32 v[14:15], v[14:15], v[200:201] op_sel_hi:[1,0]
	v_pk_mul_f32 v[12:13], v[12:13], v[200:201] op_sel_hi:[1,0]
	v_pk_mul_f32 v[10:11], v[10:11], v[200:201] op_sel_hi:[1,0]
	v_pk_mul_f32 v[8:9], v[8:9], v[200:201] op_sel_hi:[1,0]
	v_pk_mul_f32 v[6:7], v[6:7], v[200:201] op_sel_hi:[1,0]
	v_pk_mul_f32 v[4:5], v[4:5], v[200:201] op_sel_hi:[1,0]
	v_pk_mul_f32 v[2:3], v[2:3], v[200:201] op_sel_hi:[1,0]
	v_pk_mul_f32 v[0:1], v[0:1], v[200:201] op_sel_hi:[1,0]
	v_mul_f32_e32 v157, v157, v200

.LBB0_1897:
	s_setprio 0
	v_mov_b32_e32 v48, v157
	s_nop 1
	v_permlane32_swap_b32_e32 v157, v48
	v_add_f32_e32 v48, v157, v48
	v_div_scale_f32 v49, s[2:3], v48, v48, 1.0
	v_rcp_f32_e32 v50, v49
	s_mulk_i32 s21, 0x2200
	s_add_i32 s7, s21, 0
	s_waitcnt vmcnt(0) lgkmcnt(0)
	s_barrier
	v_fma_f32 v51, -v49, v50, 1.0
	v_fmac_f32_e32 v50, v51, v50
	v_div_scale_f32 v51, vcc, 1.0, v48, 1.0
	v_mul_f32_e32 v52, v51, v50
	v_fma_f32 v53, -v49, v52, v51
	v_fmac_f32_e32 v52, v53, v50
	v_fma_f32 v49, -v49, v52, v51
	v_div_fmas_f32 v49, v49, v50, v52
	v_div_fixup_f32 v48, v49, v48, 1.0
	v_add3_u32 v49, s7, v195, v181
	v_pk_mul_f32 v[50:51], v[64:65], v[48:49] op_sel_hi:[1,0]
	v_pk_mul_f32 v[52:53], v[66:67], v[48:49] op_sel_hi:[1,0]
	v_cvt_pk_bf16_f32 v50, v50, v51
	v_cvt_pk_bf16_f32 v51, v52, v53
	v_pk_mul_f32 v[52:53], v[68:69], v[48:49] op_sel_hi:[1,0]
	v_pk_mul_f32 v[54:55], v[70:71], v[48:49] op_sel_hi:[1,0]
	v_add_u32_e32 v49, 0xa000, v49
	v_pk_mul_f32 v[32:33], v[32:33], v[48:49] op_sel_hi:[1,0]
	v_pk_mul_f32 v[34:35], v[34:35], v[48:49] op_sel_hi:[1,0]
	v_pk_mul_f32 v[16:17], v[16:17], v[48:49] op_sel_hi:[1,0]
	v_pk_mul_f32 v[18:19], v[18:19], v[48:49] op_sel_hi:[1,0]
	v_pk_mul_f32 v[0:1], v[0:1], v[48:49] op_sel_hi:[1,0]
	v_pk_mul_f32 v[2:3], v[2:3], v[48:49] op_sel_hi:[1,0]
	v_cvt_pk_bf16_f32 v32, v32, v33
	v_cvt_pk_bf16_f32 v33, v34, v35
	v_pk_mul_f32 v[34:35], v[36:37], v[48:49] op_sel_hi:[1,0]
	v_pk_mul_f32 v[36:37], v[38:39], v[48:49] op_sel_hi:[1,0]
	v_cvt_pk_bf16_f32 v16, v16, v17
	v_cvt_pk_bf16_f32 v17, v18, v19
	v_pk_mul_f32 v[18:19], v[20:21], v[48:49] op_sel_hi:[1,0]
	v_pk_mul_f32 v[20:21], v[22:23], v[48:49] op_sel_hi:[1,0]
	v_cvt_pk_bf16_f32 v0, v0, v1
	v_cvt_pk_bf16_f32 v1, v2, v3
	v_pk_mul_f32 v[2:3], v[4:5], v[48:49] op_sel_hi:[1,0]
	v_pk_mul_f32 v[4:5], v[6:7], v[48:49] op_sel_hi:[1,0]
	v_cvt_pk_bf16_f32 v52, v52, v53
	v_cvt_pk_bf16_f32 v53, v54, v55
	v_cvt_pk_bf16_f32 v34, v34, v35
	v_cvt_pk_bf16_f32 v35, v36, v37
	v_cvt_pk_bf16_f32 v18, v18, v19
	v_cvt_pk_bf16_f32 v19, v20, v21
	v_cvt_pk_bf16_f32 v2, v2, v3
	v_cvt_pk_bf16_f32 v3, v4, v5
	ds_write2_b64 v49, v[50:51], v[52:53] offset1:2
	v_pk_mul_f32 v[50:51], v[72:73], v[48:49] op_sel_hi:[1,0]
	v_pk_mul_f32 v[52:53], v[74:75], v[48:49] op_sel_hi:[1,0]
	ds_write2_b64 v49, v[32:33], v[34:35] offset0:8 offset1:10
	v_pk_mul_f32 v[32:33], v[40:41], v[48:49] op_sel_hi:[1,0]
	v_pk_mul_f32 v[34:35], v[42:43], v[48:49] op_sel_hi:[1,0]
	ds_write2_b64 v49, v[16:17], v[18:19] offset0:16 offset1:18
	v_pk_mul_f32 v[16:17], v[24:25], v[48:49] op_sel_hi:[1,0]
	v_pk_mul_f32 v[18:19], v[26:27], v[48:49] op_sel_hi:[1,0]
	ds_write2_b64 v49, v[0:1], v[2:3] offset0:24 offset1:26
	v_pk_mul_f32 v[0:1], v[8:9], v[48:49] op_sel_hi:[1,0]
	v_pk_mul_f32 v[2:3], v[10:11], v[48:49] op_sel_hi:[1,0]
	v_cvt_pk_bf16_f32 v50, v50, v51
	v_cvt_pk_bf16_f32 v51, v52, v53
	v_pk_mul_f32 v[52:53], v[76:77], v[48:49] op_sel_hi:[1,0]
	v_pk_mul_f32 v[54:55], v[78:79], v[48:49] op_sel_hi:[1,0]
	v_cvt_pk_bf16_f32 v32, v32, v33
	v_cvt_pk_bf16_f32 v33, v34, v35
	v_pk_mul_f32 v[34:35], v[44:45], v[48:49] op_sel_hi:[1,0]
	v_pk_mul_f32 v[36:37], v[46:47], v[48:49] op_sel_hi:[1,0]
	v_cvt_pk_bf16_f32 v16, v16, v17
	v_cvt_pk_bf16_f32 v17, v18, v19
	v_pk_mul_f32 v[18:19], v[28:29], v[48:49] op_sel_hi:[1,0]
	v_pk_mul_f32 v[20:21], v[30:31], v[48:49] op_sel_hi:[1,0]
	v_cvt_pk_bf16_f32 v0, v0, v1
	v_cvt_pk_bf16_f32 v1, v2, v3
	v_pk_mul_f32 v[2:3], v[12:13], v[48:49] op_sel_hi:[1,0]
	v_pk_mul_f32 v[4:5], v[14:15], v[48:49] op_sel_hi:[1,0]
	v_cvt_pk_bf16_f32 v52, v52, v53
	v_cvt_pk_bf16_f32 v53, v54, v55
	v_cvt_pk_bf16_f32 v34, v34, v35
	v_cvt_pk_bf16_f32 v35, v36, v37
	v_cvt_pk_bf16_f32 v18, v18, v19
	v_cvt_pk_bf16_f32 v19, v20, v21
	v_cvt_pk_bf16_f32 v2, v2, v3
	v_cvt_pk_bf16_f32 v3, v4, v5
	s_mulk_i32 s20, 0x1800
	s_mul_hi_u32 s2, s19, 0x1800
	ds_write2_b64 v49, v[50:51], v[52:53] offset0:4 offset1:6
	ds_write2_b64 v49, v[32:33], v[34:35] offset0:12 offset1:14
	ds_write2_b64 v49, v[16:17], v[18:19] offset0:20 offset1:22
	ds_write2_b64 v49, v[0:1], v[2:3] offset0:28 offset1:30
	s_add_i32 s2, s2, s20
	s_mulk_i32 s19, 0x1800
	s_nop 0
	s_add_u32 s3, s4, s19
	v_add3_u32 v14, s7, v144, v196
	s_addc_u32 s10, s5, s2
	ds_read_b128 v[0:3], v14 offset:40960
	s_add_u32 s2, s3, s6
	s_addc_u32 s3, s10, 0
	v_mov_b32_e32 v159, 0
	ds_read_b128 v[4:7], v14 offset:42048
	v_lshl_add_u64 v[8:9], s[2:3], 0, v[158:159]
	v_mov_b32_e32 v147, v159
	v_lshl_add_u64 v[10:11], v[8:9], 0, v[146:147]
	s_movk_i32 s2, 0x6000
	s_waitcnt lgkmcnt(1)
	global_store_dwordx4 v[10:11], v[0:3], off
	v_mov_b32_e32 v149, v159
	v_mov_b32_e32 v153, v159
	v_add_co_u32_e32 v0, vcc, s2, v10
	s_mov_b32 s2, 0xc000
	s_nop 0
	v_addc_co_u32_e32 v1, vcc, 0, v11, vcc
	s_waitcnt lgkmcnt(0)
	global_store_dwordx4 v[0:1], v[4:7], off
	ds_read_b128 v[0:3], v14 offset:43136
	ds_read_b128 v[4:7], v14 offset:44224
	v_add_co_u32_e32 v12, vcc, s2, v10
	s_mov_b32 s2, 0x12000
	s_nop 0
	v_addc_co_u32_e32 v13, vcc, 0, v11, vcc
	v_add_co_u32_e32 v10, vcc, s2, v10
	s_waitcnt lgkmcnt(1)
	global_store_dwordx4 v[12:13], v[0:3], off
	v_addc_co_u32_e32 v11, vcc, 0, v11, vcc
	ds_read_b128 v[0:3], v14 offset:45312
	s_waitcnt lgkmcnt(1)
	global_store_dwordx4 v[10:11], v[4:7], off
	ds_read_b128 v[4:7], v14 offset:46400
	v_lshl_add_u64 v[10:11], v[8:9], 0, v[148:149]
	v_mov_b32_e32 v151, v159
	s_waitcnt lgkmcnt(1)
	global_store_dwordx4 v[10:11], v[0:3], off
	v_lshl_add_u64 v[10:11], v[8:9], 0, v[152:153]
	ds_read_b128 v[0:3], v14 offset:47488
	s_waitcnt lgkmcnt(1)
	global_store_dwordx4 v[10:11], v[4:7], off
	ds_read_b128 v[4:7], v14 offset:48576
	v_lshl_add_u64 v[10:11], v[8:9], 0, v[150:151]
	v_mov_b32_e32 v155, v159
	v_readfirstlane_b32 s12, v222
	s_waitcnt lgkmcnt(1)
	global_store_dwordx4 v[10:11], v[0:3], off
	s_and_b32 s2, s12, 0xffffffc0
	s_nop 0
	v_lshl_add_u64 v[0:1], v[8:9], 0, v[154:155]
	s_waitcnt lgkmcnt(0)
	global_store_dwordx4 v[0:1], v[4:7], off
	v_or_b32_e32 v0, s2, v197
	s_mov_b32 s2, 0x2aaaaaab
	v_mul_hi_i32 v1, v0, s2
	v_lshrrev_b32_e32 v2, 31, v1
	v_ashrrev_i32_e32 v1, 2, v1
	v_add_u32_e32 v2, v1, v2
	s_movk_i32 s2, 0xffe8
	v_lshrrev_b32_e32 v159, 1, v2
	v_mad_u64_u32 v[160:161], s[2:3], v2, s2, v[0:1]
	v_xor_b32_e32 v1, v159, v222
	v_bfi_b32 v1, -8, v160, v1
	v_cmp_lt_i32_e32 vcc, 15, v1
	v_add_u32_e32 v2, s8, v2
	s_and_saveexec_b64 s[2:3], vcc
	s_xor_b64 s[2:3], exec, s[2:3]
	v_mov_b32_e32 v3, 0xbfff80
	v_lshl_add_u32 v153, v2, 6, v3
	s_or_saveexec_b64 s[2:3], s[2:3]
	v_mov_b32_e32 v145, 0x1000
	s_xor_b64 exec, exec, s[2:3]
	v_lshl_or_b32 v2, v2, 11, s17
	v_add_u32_e32 v153, 0x8000000, v2
	v_mov_b32_e32 v145, 0x20000
	s_or_b64 exec, exec, s[2:3]
	v_add_u32_e32 v2, 0x200, v0
	s_mov_b32 s2, 0x2aaaaaab
	v_mul_hi_i32 v3, v2, s2
	v_lshrrev_b32_e32 v4, 31, v3
	v_ashrrev_i32_e32 v3, 2, v3
	v_add_u32_e32 v4, v3, v4
	s_movk_i32 s2, 0xffe8
	v_mad_u64_u32 v[162:163], s[2:3], v4, s2, v[2:3]
	v_lshrrev_b32_e32 v163, 1, v4
	v_xor_b32_e32 v3, v163, v222
	v_bfi_b32 v3, -8, v162, v3
	v_cmp_lt_i32_e32 vcc, 15, v3
	v_add_u32_e32 v4, s8, v4
	s_and_saveexec_b64 s[2:3], vcc
	s_xor_b64 s[2:3], exec, s[2:3]
	v_mov_b32_e32 v5, 0xbfff80
	v_lshl_add_u32 v155, v4, 6, v5
	s_or_saveexec_b64 s[2:3], s[2:3]
	v_mov_b32_e32 v147, 0x1000
	s_xor_b64 exec, exec, s[2:3]
	v_lshl_or_b32 v4, v4, 11, s17
	v_add_u32_e32 v155, 0x8000000, v4
	v_mov_b32_e32 v147, 0x20000
	s_or_b64 exec, exec, s[2:3]
	v_add_u32_e32 v4, 0x400, v0
	s_mov_b32 s2, 0x2aaaaaab
	v_mul_hi_i32 v5, v4, s2
	v_lshrrev_b32_e32 v6, 31, v5
	v_ashrrev_i32_e32 v5, 2, v5
	v_add_u32_e32 v5, v5, v6
	s_movk_i32 s2, 0xffe8
	v_mad_u64_u32 v[164:165], s[2:3], v5, s2, v[4:5]
	v_lshrrev_b32_e32 v165, 1, v5
	v_xor_b32_e32 v4, v165, v222
	v_bfi_b32 v4, -8, v164, v4
	v_cmp_lt_i32_e32 vcc, 15, v4
	v_add_u32_e32 v5, s8, v5
	s_and_saveexec_b64 s[2:3], vcc
	s_xor_b64 s[2:3], exec, s[2:3]
	v_mov_b32_e32 v6, 0xbfff80
	v_lshl_add_u32 v161, v5, 6, v6
	s_or_saveexec_b64 s[2:3], s[2:3]
	v_mov_b32_e32 v149, 0x1000
	s_xor_b64 exec, exec, s[2:3]
	v_lshl_or_b32 v5, v5, 11, s17
	v_add_u32_e32 v161, 0x8000000, v5
	v_mov_b32_e32 v149, 0x20000
	s_or_b64 exec, exec, s[2:3]
	s_lshr_b32 s21, s12, 6
	s_or_b32 s22, s16, 0x1000
	s_lshl_b32 s23, s21, 5
	s_or_b32 s2, s8, s22
	s_add_u32 s19, s2, s23
	v_or_b32_e32 v5, s19, v194
	s_movk_i32 s2, 0x1800
	v_mov_b64_e32 v[6:7], s[4:5]
	s_addc_u32 s20, s9, 0
	v_mad_u64_u32 v[6:7], s[2:3], v5, s2, v[6:7]
	v_mov_b32_e32 v5, 0x1800
	s_mov_b32 s7, 0
	v_mad_i32_i24 v7, s20, v5, v7
	v_lshl_add_u32 v8, v1, 3, v153
	v_ashrrev_i32_e32 v1, 31, v0
	v_lshl_add_u64 v[6:7], v[6:7], 0, s[6:7]
	v_mov_b32_e32 v157, 0
	v_lshrrev_b32_e32 v10, 28, v1
	v_lshl_add_u64 v[6:7], v[6:7], 0, v[156:157]
	v_lshl_add_u32 v4, v4, 3, v161
	v_mov_b32_e32 v5, v157
	v_add_u32_e32 v16, v0, v10
	global_load_dwordx4 v[96:99], v[6:7], off
	global_load_dwordx4 v[100:103], v[6:7], off offset:32
	global_load_dwordx4 v[104:107], v[6:7], off offset:64
	global_load_dwordx4 v[108:111], v[6:7], off offset:96
	global_load_dwordx4 v[112:115], v[6:7], off offset:128
	global_load_dwordx4 v[116:119], v[6:7], off offset:160
	global_load_dwordx4 v[120:123], v[6:7], off offset:192
	global_load_dwordx4 v[124:127], v[6:7], off offset:224
	global_load_dwordx4 v[128:131], v[6:7], off offset:256
	global_load_dwordx4 v[132:135], v[6:7], off offset:288
	global_load_dwordx4 v[136:139], v[6:7], off offset:320
	global_load_dwordx4 v[140:143], v[6:7], off offset:352
	v_lshl_add_u32 v6, v3, 3, v155
	v_ashrrev_i32_e32 v3, 31, v2
	v_lshl_add_u64 v[14:15], v[4:5], 1, s[84:85]
	v_ashrrev_i32_e32 v167, 4, v16
	v_and_b32_e32 v5, 0x1ffffff0, v16
	v_lshrrev_b32_e32 v11, 28, v3
	v_mov_b32_e32 v9, v157
	s_lshl_b32 s2, s21, 10
	v_sub_u32_e32 v0, v0, v5
	v_lshlrev_b32_e32 v5, 2, v167
	v_mov_b32_e32 v7, v157
	v_add_u32_e32 v17, v2, v11
	v_lshl_add_u64 v[10:11], v[8:9], 1, s[84:85]
	v_bfe_u32 v9, v167, 2, 2
	s_add_i32 s7, s2, 0
	v_and_b32_e32 v5, 12, v5
	v_lshl_add_u64 v[12:13], v[6:7], 1, s[84:85]
	v_ashrrev_i32_e32 v166, 4, v17
	v_and_b32_e32 v7, 0x1ffffff0, v17
	v_bitop3_b32 v0, v5, v0, v9 bitop3:0x36
	s_mov_b32 m0, s7
	v_add_lshl_u32 v16, v167, s8, 11
	v_sub_u32_e32 v2, v2, v7
	v_lshlrev_b32_e32 v7, 2, v166
	global_load_lds_dwordx4 v[10:11], off
	s_add_i32 m0, s7, 0x2000
	v_lshlrev_b32_e32 v168, 3, v0
	v_mov_b32_e32 v1, v157
	v_bfe_u32 v17, v166, 2, 2
	v_and_b32_e32 v7, 12, v7
	global_load_lds_dwordx4 v[12:13], off
	s_add_i32 m0, s7, 0x4000
	v_add3_u32 v0, s18, v16, v168
	v_bitop3_b32 v2, v7, v2, v17 bitop3:0x36
	global_load_lds_dwordx4 v[14:15], off
	s_add_i32 m0, s7, 0x6000
	v_lshl_add_u64 v[10:11], v[0:1], 1, s[84:85]
	v_add_lshl_u32 v18, v166, s8, 11
	v_lshlrev_b32_e32 v169, 3, v2
	global_load_lds_dwordx4 v[10:11], off
	s_add_i32 m0, s7, 0x8000
	v_mov_b32_e32 v3, v157
	v_add3_u32 v2, s18, v18, v169
	s_cmpk_gt_u32 s12, 0xff
	v_lshl_add_u64 v[12:13], v[2:3], 1, s[84:85]
	s_cselect_b64 s[10:11], -1, 0
	s_cmpk_lt_u32 s12, 0x100
	v_add_u32_e32 v8, v8, v145
	v_mov_b32_e32 v9, v157
	global_load_lds_dwordx4 v[12:13], off
	s_cselect_b64 s[12:13], -1, 0
	s_add_i32 m0, s7, 0xa000
	v_lshl_add_u64 v[8:9], v[8:9], 1, s[84:85]
	v_add_u32_e32 v6, v6, v147
	v_mov_b32_e32 v7, v157
	s_waitcnt vmcnt(0) lgkmcnt(0)
	s_barrier
	s_waitcnt vmcnt(0)
	global_load_lds_dwordx4 v[8:9], off
	v_lshl_add_u64 v[6:7], v[6:7], 1, s[84:85]
	s_add_i32 m0, s7, 0xc000
	v_add_u32_e32 v4, v4, v149
	v_mov_b32_e32 v5, v157
	global_load_lds_dwordx4 v[6:7], off
	v_lshl_add_u64 v[4:5], v[4:5], 1, s[84:85]
	s_add_i32 m0, s7, 0xe000
	v_add_u32_e32 v0, 0x20000, v0
	v_mov_b32_e32 v1, v157
	global_load_lds_dwordx4 v[4:5], off
	s_add_i32 m0, s7, 0x10000
	v_lshl_add_u64 v[0:1], v[0:1], 1, s[84:85]
	global_load_lds_dwordx4 v[0:1], off
	v_add_u32_e32 v0, 0x20000, v2
	v_mov_b32_e32 v1, v157
	v_lshl_add_u64 v[0:1], v[0:1], 1, s[84:85]
	s_add_i32 m0, s7, 0x12000
	s_and_b64 vcc, exec, s[12:13]
	global_load_lds_dwordx4 v[0:1], off
	ds_read_b128 v[0:3], v190
	ds_read_b128 v[4:7], v191
	ds_read_b128 v[8:11], v192
	ds_read_b128 v[12:15], v193
	s_waitcnt lgkmcnt(3)
	v_mfma_f32_32x32x16_bf16 v[48:63], v[0:3], v[96:99], 0
	ds_read_b128 v[0:3], v190 offset:128
	s_waitcnt lgkmcnt(3)
	v_mfma_f32_32x32x16_bf16 v[48:63], v[4:7], v[100:103], v[48:63]
	ds_read_b128 v[4:7], v191 offset:128
	s_waitcnt lgkmcnt(3)
	v_mfma_f32_32x32x16_bf16 v[48:63], v[8:11], v[104:107], v[48:63]
	ds_read_b128 v[8:11], v192 offset:128
	s_waitcnt lgkmcnt(3)
	v_mfma_f32_32x32x16_bf16 v[48:63], v[12:15], v[108:111], v[48:63]
	ds_read_b128 v[12:15], v193 offset:128
	s_waitcnt lgkmcnt(3)
	v_mfma_f32_32x32x16_bf16 v[48:63], v[0:3], v[112:115], v[48:63]
	ds_read_b128 v[0:3], v190 offset:256
	s_waitcnt lgkmcnt(3)
	v_mfma_f32_32x32x16_bf16 v[48:63], v[4:7], v[116:119], v[48:63]
	ds_read_b128 v[4:7], v191 offset:256
	s_waitcnt lgkmcnt(3)
	v_mfma_f32_32x32x16_bf16 v[48:63], v[8:11], v[120:123], v[48:63]
	ds_read_b128 v[8:11], v192 offset:256
	s_waitcnt lgkmcnt(3)
	v_mfma_f32_32x32x16_bf16 v[48:63], v[12:15], v[124:127], v[48:63]
	ds_read_b128 v[12:15], v193 offset:256
	s_waitcnt lgkmcnt(3)
	v_mfma_f32_32x32x16_bf16 v[48:63], v[0:3], v[128:131], v[48:63]
	ds_read_b128 v[0:3], v190 offset:12288
	s_waitcnt lgkmcnt(3)
	v_mfma_f32_32x32x16_bf16 v[48:63], v[4:7], v[132:135], v[48:63]
	ds_read_b128 v[4:7], v191 offset:12288
	s_waitcnt lgkmcnt(3)
	v_mfma_f32_32x32x16_bf16 v[48:63], v[8:11], v[136:139], v[48:63]
	ds_read_b128 v[8:11], v192 offset:12288
	s_waitcnt lgkmcnt(2)
	v_mfma_f32_32x32x16_bf16 v[80:95], v[0:3], v[96:99], 0
	ds_read_b128 v[16:19], v193 offset:12288
	s_waitcnt lgkmcnt(2)
	v_mfma_f32_32x32x16_bf16 v[80:95], v[4:7], v[100:103], v[80:95]
	ds_read_b128 v[20:23], v190 offset:12416
	s_waitcnt lgkmcnt(2)
	v_mfma_f32_32x32x16_bf16 v[80:95], v[8:11], v[104:107], v[80:95]
	ds_read_b128 v[24:27], v191 offset:12416
	s_waitcnt lgkmcnt(2)
	v_mfma_f32_32x32x16_bf16 v[80:95], v[16:19], v[108:111], v[80:95]
	ds_read_b128 v[28:31], v192 offset:12416
	s_waitcnt lgkmcnt(2)
	v_mfma_f32_32x32x16_bf16 v[80:95], v[20:23], v[112:115], v[80:95]
	ds_read_b128 v[32:35], v193 offset:12416
	s_waitcnt lgkmcnt(2)
	v_mfma_f32_32x32x16_bf16 v[80:95], v[24:27], v[116:119], v[80:95]
	ds_read_b128 v[36:39], v190 offset:12544
	s_waitcnt lgkmcnt(2)
	v_mfma_f32_32x32x16_bf16 v[80:95], v[28:31], v[120:123], v[80:95]
	ds_read_b128 v[40:43], v191 offset:12544
	s_waitcnt lgkmcnt(2)
	v_mfma_f32_32x32x16_bf16 v[80:95], v[32:35], v[124:127], v[80:95]
	ds_read_b128 v[44:47], v192 offset:12544
	s_waitcnt lgkmcnt(2)
	v_mfma_f32_32x32x16_bf16 v[80:95], v[36:39], v[128:131], v[80:95]
	ds_read_b128 v[64:67], v193 offset:12544
	s_waitcnt lgkmcnt(2)
	v_mfma_f32_32x32x16_bf16 v[80:95], v[40:43], v[132:135], v[80:95]
	s_waitcnt lgkmcnt(1)
	v_mfma_f32_32x32x16_bf16 v[80:95], v[44:47], v[136:139], v[80:95]
	s_waitcnt lgkmcnt(0)
	v_mfma_f32_32x32x16_bf16 v[80:95], v[64:67], v[140:143], v[80:95]
	v_mfma_f32_32x32x16_bf16 v[48:63], v[12:15], v[140:143], v[48:63]
	s_cbranch_vccnz .LBB0_1911
	s_waitcnt vmcnt(0) lgkmcnt(0)
	s_barrier

.LBB0_1928:
	v_add_u32_e32 v167, s27, v174
	v_add_u32_e32 v198, s27, v175
	v_sub_f32_e32 v48, v48, v151
	v_sub_f32_e32 v49, v49, v151
	v_sub_f32_e32 v50, v50, v151
	v_sub_f32_e32 v51, v51, v151
	v_sub_f32_e32 v52, v52, v151
	v_sub_f32_e32 v53, v53, v151
	v_sub_f32_e32 v54, v54, v151
	v_sub_f32_e32 v55, v55, v151
	v_add_u32_e32 v155, v167, v177
	v_exp_f32_e32 v48, v48
	v_exp_f32_e32 v49, v49
	v_exp_f32_e32 v50, v50
	v_exp_f32_e32 v51, v51
	v_exp_f32_e32 v52, v52
	v_exp_f32_e32 v53, v53
	v_exp_f32_e32 v54, v54
	v_exp_f32_e32 v55, v55
	v_add_u32_e32 v163, v198, v177
	ds_read_b64_tr_b16 v[204:205], v155 offset:24576
	ds_read_b64_tr_b16 v[206:207], v163 offset:26624
	v_add_u32_e32 v153, v167, v178
	v_add_u32_e32 v159, v198, v178
	ds_read_b64_tr_b16 v[208:209], v153 offset:24576
	ds_read_b64_tr_b16 v[210:211], v159 offset:26624
	ds_read_b64_tr_b16 v[214:215], v163 offset:30720
	ds_read_b64_tr_b16 v[212:213], v155 offset:28672
	v_cvt_pk_bf16_f32 v200, v48, v49
	v_cvt_pk_bf16_f32 v201, v50, v51
	v_cvt_pk_bf16_f32 v202, v52, v53
	v_cvt_pk_bf16_f32 v203, v54, v55
	v_add_u32_e32 v165, v167, v179
	v_add_u32_e32 v167, v167, v180
	s_waitcnt lgkmcnt(4)
	v_mfma_f32_32x32x16_bf16 v[64:79], v[204:207], v[200:203], v[64:79]
	v_add_u32_e32 v169, v198, v179
	ds_read_b64_tr_b16 v[204:205], v165 offset:24576
	ds_read_b64_tr_b16 v[206:207], v169 offset:26624
	ds_read_b64_tr_b16 v[218:219], v159 offset:30720
	ds_read_b64_tr_b16 v[216:217], v153 offset:28672
	v_add_u32_e32 v198, v198, v180
	v_add_f32_e32 v199, 0, v48
	v_sub_f32_e32 v56, v56, v151
	v_sub_f32_e32 v57, v57, v151
	v_sub_f32_e32 v58, v58, v151
	s_waitcnt lgkmcnt(6)
	v_mfma_f32_32x32x16_bf16 v[32:47], v[208:211], v[200:203], v[32:47]
	ds_read_b64_tr_b16 v[208:209], v167 offset:24576
	ds_read_b64_tr_b16 v[210:211], v198 offset:26624
	ds_read_b64_tr_b16 v[226:227], v169 offset:30720
	ds_read_b64_tr_b16 v[224:225], v165 offset:28672
	v_sub_f32_e32 v59, v59, v151
	v_sub_f32_e32 v60, v60, v151
	v_sub_f32_e32 v61, v61, v151
	v_sub_f32_e32 v62, v62, v151
	v_sub_f32_e32 v63, v63, v151
	v_add_f32_e32 v199, v49, v199
	s_waitcnt lgkmcnt(6)
	v_mfma_f32_32x32x16_bf16 v[16:31], v[204:207], v[200:203], v[16:31]
	v_exp_f32_e32 v56, v56
	v_exp_f32_e32 v57, v57
	v_exp_f32_e32 v58, v58
	v_exp_f32_e32 v59, v59
	v_exp_f32_e32 v60, v60
	v_exp_f32_e32 v61, v61
	ds_read_b64_tr_b16 v[206:207], v198 offset:30720
	ds_read_b64_tr_b16 v[204:205], v167 offset:28672
	s_waitcnt lgkmcnt(4)
	v_mfma_f32_32x32x16_bf16 v[0:15], v[208:211], v[200:203], v[0:15]
	v_exp_f32_e32 v62, v62
	v_exp_f32_e32 v63, v63
	v_add_f32_e32 v199, v50, v199
	v_add_f32_e32 v199, v51, v199
	v_add_f32_e32 v199, v52, v199
	v_add_f32_e32 v199, v53, v199
	v_cvt_pk_bf16_f32 v200, v56, v57
	v_cvt_pk_bf16_f32 v201, v58, v59
	v_cvt_pk_bf16_f32 v202, v60, v61
	v_cvt_pk_bf16_f32 v203, v62, v63
	v_add_f32_e32 v199, v54, v199
	v_add_f32_e32 v199, v55, v199
	v_mfma_f32_32x32x16_bf16 v[64:79], v[212:215], v[200:203], v[64:79]
	v_add_f32_e32 v199, v56, v199
	v_add_f32_e32 v199, v57, v199
	v_add_f32_e32 v199, v58, v199
	v_add_f32_e32 v199, v59, v199
	v_add_f32_e32 v199, v60, v199
	v_add_f32_e32 v199, v61, v199
	v_add_f32_e32 v199, v62, v199
	v_mfma_f32_32x32x16_bf16 v[32:47], v[216:219], v[200:203], v[32:47]
	v_add_f32_e32 v199, v63, v199
	v_add_f32_e32 v157, v157, v199
	s_waitcnt lgkmcnt(2)
	v_mfma_f32_32x32x16_bf16 v[16:31], v[224:227], v[200:203], v[16:31]
	s_waitcnt lgkmcnt(0)
	v_mfma_f32_32x32x16_bf16 v[0:15], v[204:207], v[200:203], v[0:15]
	v_max_f32_e32 v200, v81, v81
	v_max_f32_e32 v201, v80, v80
	v_max_f32_e32 v200, v201, v200
	v_max3_f32 v200, v200, v82, v83
	v_max3_f32 v200, v200, v84, v85
	v_max3_f32 v200, v200, v86, v87
	v_max3_f32 v200, v200, v88, v89
	v_max3_f32 v200, v200, v90, v91
	v_max3_f32 v200, v200, v92, v93
	v_max3_f32 v200, v200, v94, v95
	v_mov_b32_e32 v199, v200
	s_nop 1
	v_permlane32_swap_b32_e32 v200, v199
	v_max_f32_e32 v199, v200, v199
	v_sub_f32_e32 v199, v199, v151
	v_cmp_lt_f32_e32 vcc, s26, v199
	s_cbranch_vccz .LBB0_1930
	v_max_f32_e32 v199, v199, v199
	v_max_f32_e32 v199, 0, v199
	v_exp_f32_e64 v200, -v199
	v_add_f32_e32 v151, v151, v199
	v_pk_mul_f32 v[78:79], v[78:79], v[200:201] op_sel_hi:[1,0]
	v_pk_mul_f32 v[76:77], v[76:77], v[200:201] op_sel_hi:[1,0]
	v_pk_mul_f32 v[74:75], v[74:75], v[200:201] op_sel_hi:[1,0]
	v_pk_mul_f32 v[72:73], v[72:73], v[200:201] op_sel_hi:[1,0]
	v_pk_mul_f32 v[70:71], v[70:71], v[200:201] op_sel_hi:[1,0]
	v_pk_mul_f32 v[68:69], v[68:69], v[200:201] op_sel_hi:[1,0]
	v_pk_mul_f32 v[66:67], v[66:67], v[200:201] op_sel_hi:[1,0]
	v_pk_mul_f32 v[64:65], v[64:65], v[200:201] op_sel_hi:[1,0]
	v_pk_mul_f32 v[46:47], v[46:47], v[200:201] op_sel_hi:[1,0]
	v_pk_mul_f32 v[44:45], v[44:45], v[200:201] op_sel_hi:[1,0]
	v_pk_mul_f32 v[42:43], v[42:43], v[200:201] op_sel_hi:[1,0]
	v_pk_mul_f32 v[40:41], v[40:41], v[200:201] op_sel_hi:[1,0]
	v_pk_mul_f32 v[38:39], v[38:39], v[200:201] op_sel_hi:[1,0]
	v_pk_mul_f32 v[36:37], v[36:37], v[200:201] op_sel_hi:[1,0]
	v_pk_mul_f32 v[34:35], v[34:35], v[200:201] op_sel_hi:[1,0]
	v_pk_mul_f32 v[32:33], v[32:33], v[200:201] op_sel_hi:[1,0]
	v_pk_mul_f32 v[30:31], v[30:31], v[200:201] op_sel_hi:[1,0]
	v_pk_mul_f32 v[28:29], v[28:29], v[200:201] op_sel_hi:[1,0]
	v_pk_mul_f32 v[26:27], v[26:27], v[200:201] op_sel_hi:[1,0]
	v_pk_mul_f32 v[24:25], v[24:25], v[200:201] op_sel_hi:[1,0]
	v_pk_mul_f32 v[22:23], v[22:23], v[200:201] op_sel_hi:[1,0]
	v_pk_mul_f32 v[20:21], v[20:21], v[200:201] op_sel_hi:[1,0]
	v_pk_mul_f32 v[18:19], v[18:19], v[200:201] op_sel_hi:[1,0]
	v_pk_mul_f32 v[16:17], v[16:17], v[200:201] op_sel_hi:[1,0]
	v_pk_mul_f32 v[14:15], v[14:15], v[200:201] op_sel_hi:[1,0]
	v_pk_mul_f32 v[12:13], v[12:13], v[200:201] op_sel_hi:[1,0]
	v_pk_mul_f32 v[10:11], v[10:11], v[200:201] op_sel_hi:[1,0]
	v_pk_mul_f32 v[8:9], v[8:9], v[200:201] op_sel_hi:[1,0]
	v_pk_mul_f32 v[6:7], v[6:7], v[200:201] op_sel_hi:[1,0]
	v_pk_mul_f32 v[4:5], v[4:5], v[200:201] op_sel_hi:[1,0]
	v_pk_mul_f32 v[2:3], v[2:3], v[200:201] op_sel_hi:[1,0]
	v_pk_mul_f32 v[0:1], v[0:1], v[200:201] op_sel_hi:[1,0]
	v_mul_f32_e32 v157, v157, v200

.LBB0_1931:
	s_setprio 0
	v_mov_b32_e32 v48, v157
	s_nop 1
	v_permlane32_swap_b32_e32 v157, v48
	v_add_f32_e32 v48, v157, v48
	v_div_scale_f32 v49, s[2:3], v48, v48, 1.0
	v_rcp_f32_e32 v50, v49
	s_mulk_i32 s21, 0x2200
	s_add_i32 s7, s21, 0
	s_waitcnt vmcnt(0) lgkmcnt(0)
	s_barrier
	v_fma_f32 v51, -v49, v50, 1.0
	v_fmac_f32_e32 v50, v51, v50
	v_div_scale_f32 v51, vcc, 1.0, v48, 1.0
	v_mul_f32_e32 v52, v51, v50
	v_fma_f32 v53, -v49, v52, v51
	v_fmac_f32_e32 v52, v53, v50
	v_fma_f32 v49, -v49, v52, v51
	v_div_fmas_f32 v49, v49, v50, v52
	v_div_fixup_f32 v48, v49, v48, 1.0
	v_add3_u32 v49, s7, v195, v181
	v_pk_mul_f32 v[50:51], v[64:65], v[48:49] op_sel_hi:[1,0]
	v_pk_mul_f32 v[52:53], v[66:67], v[48:49] op_sel_hi:[1,0]
	v_cvt_pk_bf16_f32 v50, v50, v51
	v_cvt_pk_bf16_f32 v51, v52, v53
	v_pk_mul_f32 v[52:53], v[68:69], v[48:49] op_sel_hi:[1,0]
	v_pk_mul_f32 v[54:55], v[70:71], v[48:49] op_sel_hi:[1,0]
	v_add_u32_e32 v49, 0xa000, v49
	v_pk_mul_f32 v[32:33], v[32:33], v[48:49] op_sel_hi:[1,0]
	v_pk_mul_f32 v[34:35], v[34:35], v[48:49] op_sel_hi:[1,0]
	v_pk_mul_f32 v[16:17], v[16:17], v[48:49] op_sel_hi:[1,0]
	v_pk_mul_f32 v[18:19], v[18:19], v[48:49] op_sel_hi:[1,0]
	v_pk_mul_f32 v[0:1], v[0:1], v[48:49] op_sel_hi:[1,0]
	v_pk_mul_f32 v[2:3], v[2:3], v[48:49] op_sel_hi:[1,0]
	v_cvt_pk_bf16_f32 v32, v32, v33
	v_cvt_pk_bf16_f32 v33, v34, v35
	v_pk_mul_f32 v[34:35], v[36:37], v[48:49] op_sel_hi:[1,0]
	v_pk_mul_f32 v[36:37], v[38:39], v[48:49] op_sel_hi:[1,0]
	v_cvt_pk_bf16_f32 v16, v16, v17
	v_cvt_pk_bf16_f32 v17, v18, v19
	v_pk_mul_f32 v[18:19], v[20:21], v[48:49] op_sel_hi:[1,0]
	v_pk_mul_f32 v[20:21], v[22:23], v[48:49] op_sel_hi:[1,0]
	v_cvt_pk_bf16_f32 v0, v0, v1
	v_cvt_pk_bf16_f32 v1, v2, v3
	v_pk_mul_f32 v[2:3], v[4:5], v[48:49] op_sel_hi:[1,0]
	v_pk_mul_f32 v[4:5], v[6:7], v[48:49] op_sel_hi:[1,0]
	v_cvt_pk_bf16_f32 v52, v52, v53
	v_cvt_pk_bf16_f32 v53, v54, v55
	v_cvt_pk_bf16_f32 v34, v34, v35
	v_cvt_pk_bf16_f32 v35, v36, v37
	v_cvt_pk_bf16_f32 v18, v18, v19
	v_cvt_pk_bf16_f32 v19, v20, v21
	v_cvt_pk_bf16_f32 v2, v2, v3
	v_cvt_pk_bf16_f32 v3, v4, v5
	ds_write2_b64 v49, v[50:51], v[52:53] offset1:2
	v_pk_mul_f32 v[50:51], v[72:73], v[48:49] op_sel_hi:[1,0]
	v_pk_mul_f32 v[52:53], v[74:75], v[48:49] op_sel_hi:[1,0]
	ds_write2_b64 v49, v[32:33], v[34:35] offset0:8 offset1:10
	v_pk_mul_f32 v[32:33], v[40:41], v[48:49] op_sel_hi:[1,0]
	v_pk_mul_f32 v[34:35], v[42:43], v[48:49] op_sel_hi:[1,0]
	ds_write2_b64 v49, v[16:17], v[18:19] offset0:16 offset1:18
	v_pk_mul_f32 v[16:17], v[24:25], v[48:49] op_sel_hi:[1,0]
	v_pk_mul_f32 v[18:19], v[26:27], v[48:49] op_sel_hi:[1,0]
	ds_write2_b64 v49, v[0:1], v[2:3] offset0:24 offset1:26
	v_pk_mul_f32 v[0:1], v[8:9], v[48:49] op_sel_hi:[1,0]
	v_pk_mul_f32 v[2:3], v[10:11], v[48:49] op_sel_hi:[1,0]
	v_cvt_pk_bf16_f32 v50, v50, v51
	v_cvt_pk_bf16_f32 v51, v52, v53
	v_pk_mul_f32 v[52:53], v[76:77], v[48:49] op_sel_hi:[1,0]
	v_pk_mul_f32 v[54:55], v[78:79], v[48:49] op_sel_hi:[1,0]
	v_cvt_pk_bf16_f32 v32, v32, v33
	v_cvt_pk_bf16_f32 v33, v34, v35
	v_pk_mul_f32 v[34:35], v[44:45], v[48:49] op_sel_hi:[1,0]
	v_pk_mul_f32 v[36:37], v[46:47], v[48:49] op_sel_hi:[1,0]
	v_cvt_pk_bf16_f32 v16, v16, v17
	v_cvt_pk_bf16_f32 v17, v18, v19
	v_pk_mul_f32 v[18:19], v[28:29], v[48:49] op_sel_hi:[1,0]
	v_pk_mul_f32 v[20:21], v[30:31], v[48:49] op_sel_hi:[1,0]
	v_cvt_pk_bf16_f32 v0, v0, v1
	v_cvt_pk_bf16_f32 v1, v2, v3
	v_pk_mul_f32 v[2:3], v[12:13], v[48:49] op_sel_hi:[1,0]
	v_pk_mul_f32 v[4:5], v[14:15], v[48:49] op_sel_hi:[1,0]
	v_cvt_pk_bf16_f32 v52, v52, v53
	v_cvt_pk_bf16_f32 v53, v54, v55
	v_cvt_pk_bf16_f32 v34, v34, v35
	v_cvt_pk_bf16_f32 v35, v36, v37
	v_cvt_pk_bf16_f32 v18, v18, v19
	v_cvt_pk_bf16_f32 v19, v20, v21
	v_cvt_pk_bf16_f32 v2, v2, v3
	v_cvt_pk_bf16_f32 v3, v4, v5
	s_mulk_i32 s20, 0x1800
	s_mul_hi_u32 s2, s19, 0x1800
	ds_write2_b64 v49, v[50:51], v[52:53] offset0:4 offset1:6
	ds_write2_b64 v49, v[32:33], v[34:35] offset0:12 offset1:14
	ds_write2_b64 v49, v[16:17], v[18:19] offset0:20 offset1:22
	ds_write2_b64 v49, v[0:1], v[2:3] offset0:28 offset1:30
	s_add_i32 s2, s2, s20
	s_mulk_i32 s19, 0x1800
	s_nop 0
	s_add_u32 s3, s4, s19
	v_add3_u32 v14, s7, v144, v196
	s_addc_u32 s10, s5, s2
	ds_read_b128 v[0:3], v14 offset:40960
	s_add_u32 s2, s3, s6
	s_addc_u32 s3, s10, 0
	v_mov_b32_e32 v159, 0
	ds_read_b128 v[4:7], v14 offset:42048
	v_lshl_add_u64 v[8:9], s[2:3], 0, v[158:159]
	v_mov_b32_e32 v147, v159
	v_lshl_add_u64 v[10:11], v[8:9], 0, v[146:147]
	s_movk_i32 s2, 0x6000
	s_waitcnt lgkmcnt(1)
	global_store_dwordx4 v[10:11], v[0:3], off
	v_mov_b32_e32 v149, v159
	v_mov_b32_e32 v153, v159
	v_add_co_u32_e32 v0, vcc, s2, v10
	s_mov_b32 s2, 0xc000
	s_nop 0
	v_addc_co_u32_e32 v1, vcc, 0, v11, vcc
	s_waitcnt lgkmcnt(0)
	global_store_dwordx4 v[0:1], v[4:7], off
	ds_read_b128 v[0:3], v14 offset:43136
	ds_read_b128 v[4:7], v14 offset:44224
	v_add_co_u32_e32 v12, vcc, s2, v10
	s_mov_b32 s2, 0x12000
	s_nop 0
	v_addc_co_u32_e32 v13, vcc, 0, v11, vcc
	v_add_co_u32_e32 v10, vcc, s2, v10
	s_waitcnt lgkmcnt(1)
	global_store_dwordx4 v[12:13], v[0:3], off
	v_addc_co_u32_e32 v11, vcc, 0, v11, vcc
	ds_read_b128 v[0:3], v14 offset:45312
	s_waitcnt lgkmcnt(1)
	global_store_dwordx4 v[10:11], v[4:7], off
	ds_read_b128 v[4:7], v14 offset:46400
	v_lshl_add_u64 v[10:11], v[8:9], 0, v[148:149]
	v_mov_b32_e32 v151, v159
	s_waitcnt lgkmcnt(1)
	global_store_dwordx4 v[10:11], v[0:3], off
	v_lshl_add_u64 v[10:11], v[8:9], 0, v[152:153]
	ds_read_b128 v[0:3], v14 offset:47488
	s_waitcnt lgkmcnt(1)
	global_store_dwordx4 v[10:11], v[4:7], off
	ds_read_b128 v[4:7], v14 offset:48576
	v_lshl_add_u64 v[10:11], v[8:9], 0, v[150:151]
	v_mov_b32_e32 v155, v159
	v_readfirstlane_b32 s12, v222
	s_waitcnt lgkmcnt(1)
	global_store_dwordx4 v[10:11], v[0:3], off
	s_and_b32 s2, s12, 0xffffffc0
	s_nop 0
	v_lshl_add_u64 v[0:1], v[8:9], 0, v[154:155]
	s_waitcnt lgkmcnt(0)
	global_store_dwordx4 v[0:1], v[4:7], off
	v_or_b32_e32 v0, s2, v197
	s_mov_b32 s2, 0x2aaaaaab
	v_mul_hi_i32 v1, v0, s2
	v_lshrrev_b32_e32 v2, 31, v1
	v_ashrrev_i32_e32 v1, 2, v1
	v_add_u32_e32 v2, v1, v2
	s_movk_i32 s2, 0xffe8
	v_lshrrev_b32_e32 v159, 1, v2
	v_mad_u64_u32 v[160:161], s[2:3], v2, s2, v[0:1]
	v_xor_b32_e32 v1, v159, v222
	v_bfi_b32 v1, -8, v160, v1
	v_cmp_lt_i32_e32 vcc, 15, v1
	v_add_u32_e32 v2, s8, v2
	s_and_saveexec_b64 s[2:3], vcc
	s_xor_b64 s[2:3], exec, s[2:3]
	v_mov_b32_e32 v3, 0xbfff80
	v_lshl_add_u32 v153, v2, 6, v3
	s_or_saveexec_b64 s[2:3], s[2:3]
	v_mov_b32_e32 v145, 0x1000
	s_xor_b64 exec, exec, s[2:3]
	v_lshl_or_b32 v2, v2, 11, s17
	v_add_u32_e32 v153, 0x8000000, v2
	v_mov_b32_e32 v145, 0x20000
	s_or_b64 exec, exec, s[2:3]
	v_add_u32_e32 v2, 0x200, v0
	s_mov_b32 s2, 0x2aaaaaab
	v_mul_hi_i32 v3, v2, s2
	v_lshrrev_b32_e32 v4, 31, v3
	v_ashrrev_i32_e32 v3, 2, v3
	v_add_u32_e32 v4, v3, v4
	s_movk_i32 s2, 0xffe8
	v_mad_u64_u32 v[162:163], s[2:3], v4, s2, v[2:3]
	v_lshrrev_b32_e32 v163, 1, v4
	v_xor_b32_e32 v3, v163, v222
	v_bfi_b32 v3, -8, v162, v3
	v_cmp_lt_i32_e32 vcc, 15, v3
	v_add_u32_e32 v4, s8, v4
	s_and_saveexec_b64 s[2:3], vcc
	s_xor_b64 s[2:3], exec, s[2:3]
	v_mov_b32_e32 v5, 0xbfff80
	v_lshl_add_u32 v155, v4, 6, v5
	s_or_saveexec_b64 s[2:3], s[2:3]
	v_mov_b32_e32 v147, 0x1000
	s_xor_b64 exec, exec, s[2:3]
	v_lshl_or_b32 v4, v4, 11, s17
	v_add_u32_e32 v155, 0x8000000, v4
	v_mov_b32_e32 v147, 0x20000
	s_or_b64 exec, exec, s[2:3]
	v_add_u32_e32 v4, 0x400, v0
	s_mov_b32 s2, 0x2aaaaaab
	v_mul_hi_i32 v5, v4, s2
	v_lshrrev_b32_e32 v6, 31, v5
	v_ashrrev_i32_e32 v5, 2, v5
	v_add_u32_e32 v5, v5, v6
	s_movk_i32 s2, 0xffe8
	v_mad_u64_u32 v[164:165], s[2:3], v5, s2, v[4:5]
	v_lshrrev_b32_e32 v165, 1, v5
	v_xor_b32_e32 v4, v165, v222
	v_bfi_b32 v4, -8, v164, v4
	v_cmp_lt_i32_e32 vcc, 15, v4
	v_add_u32_e32 v5, s8, v5
	s_and_saveexec_b64 s[2:3], vcc
	s_xor_b64 s[2:3], exec, s[2:3]
	v_mov_b32_e32 v6, 0xbfff80
	v_lshl_add_u32 v161, v5, 6, v6
	s_or_saveexec_b64 s[2:3], s[2:3]
	v_mov_b32_e32 v149, 0x1000
	s_xor_b64 exec, exec, s[2:3]
	v_lshl_or_b32 v5, v5, 11, s17
	v_add_u32_e32 v161, 0x8000000, v5
	v_mov_b32_e32 v149, 0x20000
	s_or_b64 exec, exec, s[2:3]
	s_lshr_b32 s21, s12, 6
	s_xor_b32 s22, s16, 0xf00
	s_lshl_b32 s23, s21, 5
	s_or_b32 s2, s8, s22
	s_add_u32 s19, s2, s23
	v_or_b32_e32 v5, s19, v194
	s_movk_i32 s2, 0x1800
	v_mov_b64_e32 v[6:7], s[4:5]
	s_addc_u32 s20, s9, 0
	v_mad_u64_u32 v[6:7], s[2:3], v5, s2, v[6:7]
	v_mov_b32_e32 v5, 0x1800
	s_mov_b32 s7, 0
	v_mad_i32_i24 v7, s20, v5, v7
	v_lshl_add_u32 v8, v1, 3, v153
	v_ashrrev_i32_e32 v1, 31, v0
	v_lshl_add_u64 v[6:7], v[6:7], 0, s[6:7]
	v_mov_b32_e32 v157, 0
	v_lshrrev_b32_e32 v10, 28, v1
	v_lshl_add_u64 v[6:7], v[6:7], 0, v[156:157]
	v_lshl_add_u32 v4, v4, 3, v161
	v_mov_b32_e32 v5, v157
	v_add_u32_e32 v16, v0, v10
	global_load_dwordx4 v[96:99], v[6:7], off
	global_load_dwordx4 v[100:103], v[6:7], off offset:32
	global_load_dwordx4 v[104:107], v[6:7], off offset:64
	global_load_dwordx4 v[108:111], v[6:7], off offset:96
	global_load_dwordx4 v[112:115], v[6:7], off offset:128
	global_load_dwordx4 v[116:119], v[6:7], off offset:160
	global_load_dwordx4 v[120:123], v[6:7], off offset:192
	global_load_dwordx4 v[124:127], v[6:7], off offset:224
	global_load_dwordx4 v[128:131], v[6:7], off offset:256
	global_load_dwordx4 v[132:135], v[6:7], off offset:288
	global_load_dwordx4 v[136:139], v[6:7], off offset:320
	global_load_dwordx4 v[140:143], v[6:7], off offset:352
	v_lshl_add_u32 v6, v3, 3, v155
	v_ashrrev_i32_e32 v3, 31, v2
	v_lshl_add_u64 v[14:15], v[4:5], 1, s[84:85]
	v_ashrrev_i32_e32 v167, 4, v16
	v_and_b32_e32 v5, 0x1ffffff0, v16
	v_lshrrev_b32_e32 v11, 28, v3
	v_mov_b32_e32 v9, v157
	s_lshl_b32 s2, s21, 10
	v_sub_u32_e32 v0, v0, v5
	v_lshlrev_b32_e32 v5, 2, v167
	v_mov_b32_e32 v7, v157
	v_add_u32_e32 v17, v2, v11
	v_lshl_add_u64 v[10:11], v[8:9], 1, s[84:85]
	v_bfe_u32 v9, v167, 2, 2
	s_add_i32 s7, s2, 0
	v_and_b32_e32 v5, 12, v5
	v_lshl_add_u64 v[12:13], v[6:7], 1, s[84:85]
	v_ashrrev_i32_e32 v166, 4, v17
	v_and_b32_e32 v7, 0x1ffffff0, v17
	v_bitop3_b32 v0, v5, v0, v9 bitop3:0x36
	s_mov_b32 m0, s7
	v_add_lshl_u32 v16, v167, s8, 11
	v_sub_u32_e32 v2, v2, v7
	v_lshlrev_b32_e32 v7, 2, v166
	global_load_lds_dwordx4 v[10:11], off
	s_add_i32 m0, s7, 0x2000
	v_lshlrev_b32_e32 v168, 3, v0
	v_mov_b32_e32 v1, v157
	v_bfe_u32 v17, v166, 2, 2
	v_and_b32_e32 v7, 12, v7
	global_load_lds_dwordx4 v[12:13], off
	s_add_i32 m0, s7, 0x4000
	v_add3_u32 v0, s18, v16, v168
	v_bitop3_b32 v2, v7, v2, v17 bitop3:0x36
	global_load_lds_dwordx4 v[14:15], off
	s_add_i32 m0, s7, 0x6000
	v_lshl_add_u64 v[10:11], v[0:1], 1, s[84:85]
	v_add_lshl_u32 v18, v166, s8, 11
	v_lshlrev_b32_e32 v169, 3, v2
	global_load_lds_dwordx4 v[10:11], off
	s_add_i32 m0, s7, 0x8000
	v_mov_b32_e32 v3, v157
	v_add3_u32 v2, s18, v18, v169
	s_cmpk_gt_u32 s12, 0xff
	v_lshl_add_u64 v[12:13], v[2:3], 1, s[84:85]
	s_cselect_b64 s[10:11], -1, 0
	s_cmpk_lt_u32 s12, 0x100
	v_add_u32_e32 v8, v8, v145
	v_mov_b32_e32 v9, v157
	global_load_lds_dwordx4 v[12:13], off
	s_cselect_b64 s[12:13], -1, 0
	s_add_i32 m0, s7, 0xa000
	v_lshl_add_u64 v[8:9], v[8:9], 1, s[84:85]
	v_add_u32_e32 v6, v6, v147
	v_mov_b32_e32 v7, v157
	s_waitcnt vmcnt(0) lgkmcnt(0)
	s_barrier
	s_waitcnt vmcnt(0)
	global_load_lds_dwordx4 v[8:9], off
	v_lshl_add_u64 v[6:7], v[6:7], 1, s[84:85]
	s_add_i32 m0, s7, 0xc000
	v_add_u32_e32 v4, v4, v149
	v_mov_b32_e32 v5, v157
	global_load_lds_dwordx4 v[6:7], off
	v_lshl_add_u64 v[4:5], v[4:5], 1, s[84:85]
	s_add_i32 m0, s7, 0xe000
	v_add_u32_e32 v0, 0x20000, v0
	v_mov_b32_e32 v1, v157
	global_load_lds_dwordx4 v[4:5], off
	s_add_i32 m0, s7, 0x10000
	v_lshl_add_u64 v[0:1], v[0:1], 1, s[84:85]
	global_load_lds_dwordx4 v[0:1], off
	v_add_u32_e32 v0, 0x20000, v2
	v_mov_b32_e32 v1, v157
	v_lshl_add_u64 v[0:1], v[0:1], 1, s[84:85]
	s_add_i32 m0, s7, 0x12000
	s_and_b64 vcc, exec, s[12:13]
	global_load_lds_dwordx4 v[0:1], off
	ds_read_b128 v[0:3], v190
	ds_read_b128 v[4:7], v191
	ds_read_b128 v[8:11], v192
	ds_read_b128 v[12:15], v193
	s_waitcnt lgkmcnt(3)
	v_mfma_f32_32x32x16_bf16 v[48:63], v[0:3], v[96:99], 0
	ds_read_b128 v[0:3], v190 offset:128
	s_waitcnt lgkmcnt(3)
	v_mfma_f32_32x32x16_bf16 v[48:63], v[4:7], v[100:103], v[48:63]
	ds_read_b128 v[4:7], v191 offset:128
	s_waitcnt lgkmcnt(3)
	v_mfma_f32_32x32x16_bf16 v[48:63], v[8:11], v[104:107], v[48:63]
	ds_read_b128 v[8:11], v192 offset:128
	s_waitcnt lgkmcnt(3)
	v_mfma_f32_32x32x16_bf16 v[48:63], v[12:15], v[108:111], v[48:63]
	ds_read_b128 v[12:15], v193 offset:128
	s_waitcnt lgkmcnt(3)
	v_mfma_f32_32x32x16_bf16 v[48:63], v[0:3], v[112:115], v[48:63]
	ds_read_b128 v[0:3], v190 offset:256
	s_waitcnt lgkmcnt(3)
	v_mfma_f32_32x32x16_bf16 v[48:63], v[4:7], v[116:119], v[48:63]
	ds_read_b128 v[4:7], v191 offset:256
	s_waitcnt lgkmcnt(3)
	v_mfma_f32_32x32x16_bf16 v[48:63], v[8:11], v[120:123], v[48:63]
	ds_read_b128 v[8:11], v192 offset:256
	s_waitcnt lgkmcnt(3)
	v_mfma_f32_32x32x16_bf16 v[48:63], v[12:15], v[124:127], v[48:63]
	ds_read_b128 v[12:15], v193 offset:256
	s_waitcnt lgkmcnt(3)
	v_mfma_f32_32x32x16_bf16 v[48:63], v[0:3], v[128:131], v[48:63]
	ds_read_b128 v[0:3], v190 offset:12288
	s_waitcnt lgkmcnt(3)
	v_mfma_f32_32x32x16_bf16 v[48:63], v[4:7], v[132:135], v[48:63]
	ds_read_b128 v[4:7], v191 offset:12288
	s_waitcnt lgkmcnt(3)
	v_mfma_f32_32x32x16_bf16 v[48:63], v[8:11], v[136:139], v[48:63]
	ds_read_b128 v[8:11], v192 offset:12288
	s_waitcnt lgkmcnt(2)
	v_mfma_f32_32x32x16_bf16 v[80:95], v[0:3], v[96:99], 0
	ds_read_b128 v[16:19], v193 offset:12288
	s_waitcnt lgkmcnt(2)
	v_mfma_f32_32x32x16_bf16 v[80:95], v[4:7], v[100:103], v[80:95]
	ds_read_b128 v[20:23], v190 offset:12416
	s_waitcnt lgkmcnt(2)
	v_mfma_f32_32x32x16_bf16 v[80:95], v[8:11], v[104:107], v[80:95]
	ds_read_b128 v[24:27], v191 offset:12416
	s_waitcnt lgkmcnt(2)
	v_mfma_f32_32x32x16_bf16 v[80:95], v[16:19], v[108:111], v[80:95]
	ds_read_b128 v[28:31], v192 offset:12416
	s_waitcnt lgkmcnt(2)
	v_mfma_f32_32x32x16_bf16 v[80:95], v[20:23], v[112:115], v[80:95]
	ds_read_b128 v[32:35], v193 offset:12416
	s_waitcnt lgkmcnt(2)
	v_mfma_f32_32x32x16_bf16 v[80:95], v[24:27], v[116:119], v[80:95]
	ds_read_b128 v[36:39], v190 offset:12544
	s_waitcnt lgkmcnt(2)
	v_mfma_f32_32x32x16_bf16 v[80:95], v[28:31], v[120:123], v[80:95]
	ds_read_b128 v[40:43], v191 offset:12544
	s_waitcnt lgkmcnt(2)
	v_mfma_f32_32x32x16_bf16 v[80:95], v[32:35], v[124:127], v[80:95]
	ds_read_b128 v[44:47], v192 offset:12544
	s_waitcnt lgkmcnt(2)
	v_mfma_f32_32x32x16_bf16 v[80:95], v[36:39], v[128:131], v[80:95]
	ds_read_b128 v[64:67], v193 offset:12544
	s_waitcnt lgkmcnt(2)
	v_mfma_f32_32x32x16_bf16 v[80:95], v[40:43], v[132:135], v[80:95]
	s_waitcnt lgkmcnt(1)
	v_mfma_f32_32x32x16_bf16 v[80:95], v[44:47], v[136:139], v[80:95]
	s_waitcnt lgkmcnt(0)
	v_mfma_f32_32x32x16_bf16 v[80:95], v[64:67], v[140:143], v[80:95]
	v_mfma_f32_32x32x16_bf16 v[48:63], v[12:15], v[140:143], v[48:63]
	s_cbranch_vccnz .LBB0_1945
	s_waitcnt vmcnt(0) lgkmcnt(0)
	s_barrier

.LBB0_1965:
	s_setprio 0
	v_mov_b32_e32 v48, v157
	s_nop 1
	v_permlane32_swap_b32_e32 v157, v48
	v_add_f32_e32 v48, v157, v48
	v_div_scale_f32 v49, s[2:3], v48, v48, 1.0
	v_rcp_f32_e32 v50, v49
	s_mulk_i32 s21, 0x2200
	s_add_i32 s7, s21, 0
	s_waitcnt vmcnt(0) lgkmcnt(0)
	s_barrier
	v_fma_f32 v51, -v49, v50, 1.0
	v_fmac_f32_e32 v50, v51, v50
	v_div_scale_f32 v51, vcc, 1.0, v48, 1.0
	v_mul_f32_e32 v52, v51, v50
	v_fma_f32 v53, -v49, v52, v51
	v_fmac_f32_e32 v52, v53, v50
	v_fma_f32 v49, -v49, v52, v51
	v_div_fmas_f32 v49, v49, v50, v52
	v_div_fixup_f32 v48, v49, v48, 1.0
	v_add3_u32 v49, s7, v195, v181
	v_pk_mul_f32 v[50:51], v[64:65], v[48:49] op_sel_hi:[1,0]
	v_pk_mul_f32 v[52:53], v[66:67], v[48:49] op_sel_hi:[1,0]
	v_cvt_pk_bf16_f32 v50, v50, v51
	v_cvt_pk_bf16_f32 v51, v52, v53
	v_pk_mul_f32 v[52:53], v[68:69], v[48:49] op_sel_hi:[1,0]
	v_pk_mul_f32 v[54:55], v[70:71], v[48:49] op_sel_hi:[1,0]
	v_add_u32_e32 v49, 0xa000, v49
	v_pk_mul_f32 v[32:33], v[32:33], v[48:49] op_sel_hi:[1,0]
	v_pk_mul_f32 v[34:35], v[34:35], v[48:49] op_sel_hi:[1,0]
	v_pk_mul_f32 v[16:17], v[16:17], v[48:49] op_sel_hi:[1,0]
	v_pk_mul_f32 v[18:19], v[18:19], v[48:49] op_sel_hi:[1,0]
	v_pk_mul_f32 v[0:1], v[0:1], v[48:49] op_sel_hi:[1,0]
	v_pk_mul_f32 v[2:3], v[2:3], v[48:49] op_sel_hi:[1,0]
	v_cvt_pk_bf16_f32 v32, v32, v33
	v_cvt_pk_bf16_f32 v33, v34, v35
	v_pk_mul_f32 v[34:35], v[36:37], v[48:49] op_sel_hi:[1,0]
	v_pk_mul_f32 v[36:37], v[38:39], v[48:49] op_sel_hi:[1,0]
	v_cvt_pk_bf16_f32 v16, v16, v17
	v_cvt_pk_bf16_f32 v17, v18, v19
	v_pk_mul_f32 v[18:19], v[20:21], v[48:49] op_sel_hi:[1,0]
	v_pk_mul_f32 v[20:21], v[22:23], v[48:49] op_sel_hi:[1,0]
	v_cvt_pk_bf16_f32 v0, v0, v1
	v_cvt_pk_bf16_f32 v1, v2, v3
	v_pk_mul_f32 v[2:3], v[4:5], v[48:49] op_sel_hi:[1,0]
	v_pk_mul_f32 v[4:5], v[6:7], v[48:49] op_sel_hi:[1,0]
	v_cvt_pk_bf16_f32 v52, v52, v53
	v_cvt_pk_bf16_f32 v53, v54, v55
	v_cvt_pk_bf16_f32 v34, v34, v35
	v_cvt_pk_bf16_f32 v35, v36, v37
	v_cvt_pk_bf16_f32 v18, v18, v19
	v_cvt_pk_bf16_f32 v19, v20, v21
	v_cvt_pk_bf16_f32 v2, v2, v3
	v_cvt_pk_bf16_f32 v3, v4, v5
	ds_write2_b64 v49, v[50:51], v[52:53] offset1:2
	v_pk_mul_f32 v[50:51], v[72:73], v[48:49] op_sel_hi:[1,0]
	v_pk_mul_f32 v[52:53], v[74:75], v[48:49] op_sel_hi:[1,0]
	ds_write2_b64 v49, v[32:33], v[34:35] offset0:8 offset1:10
	v_pk_mul_f32 v[32:33], v[40:41], v[48:49] op_sel_hi:[1,0]
	v_pk_mul_f32 v[34:35], v[42:43], v[48:49] op_sel_hi:[1,0]
	ds_write2_b64 v49, v[16:17], v[18:19] offset0:16 offset1:18
	v_pk_mul_f32 v[16:17], v[24:25], v[48:49] op_sel_hi:[1,0]
	v_pk_mul_f32 v[18:19], v[26:27], v[48:49] op_sel_hi:[1,0]
	ds_write2_b64 v49, v[0:1], v[2:3] offset0:24 offset1:26
	v_pk_mul_f32 v[0:1], v[8:9], v[48:49] op_sel_hi:[1,0]
	v_pk_mul_f32 v[2:3], v[10:11], v[48:49] op_sel_hi:[1,0]
	v_cvt_pk_bf16_f32 v50, v50, v51
	v_cvt_pk_bf16_f32 v51, v52, v53
	v_pk_mul_f32 v[52:53], v[76:77], v[48:49] op_sel_hi:[1,0]
	v_pk_mul_f32 v[54:55], v[78:79], v[48:49] op_sel_hi:[1,0]
	v_cvt_pk_bf16_f32 v32, v32, v33
	v_cvt_pk_bf16_f32 v33, v34, v35
	v_pk_mul_f32 v[34:35], v[44:45], v[48:49] op_sel_hi:[1,0]
	v_pk_mul_f32 v[36:37], v[46:47], v[48:49] op_sel_hi:[1,0]
	v_cvt_pk_bf16_f32 v16, v16, v17
	v_cvt_pk_bf16_f32 v17, v18, v19
	v_pk_mul_f32 v[18:19], v[28:29], v[48:49] op_sel_hi:[1,0]
	v_pk_mul_f32 v[20:21], v[30:31], v[48:49] op_sel_hi:[1,0]
	v_cvt_pk_bf16_f32 v0, v0, v1
	v_cvt_pk_bf16_f32 v1, v2, v3
	v_pk_mul_f32 v[2:3], v[12:13], v[48:49] op_sel_hi:[1,0]
	v_pk_mul_f32 v[4:5], v[14:15], v[48:49] op_sel_hi:[1,0]
	v_cvt_pk_bf16_f32 v52, v52, v53
	v_cvt_pk_bf16_f32 v53, v54, v55
	v_cvt_pk_bf16_f32 v34, v34, v35
	v_cvt_pk_bf16_f32 v35, v36, v37
	v_cvt_pk_bf16_f32 v18, v18, v19
	v_cvt_pk_bf16_f32 v19, v20, v21
	v_cvt_pk_bf16_f32 v2, v2, v3
	v_cvt_pk_bf16_f32 v3, v4, v5
	s_mulk_i32 s20, 0x1800
	s_mul_hi_u32 s2, s19, 0x1800
	ds_write2_b64 v49, v[50:51], v[52:53] offset0:4 offset1:6
	ds_write2_b64 v49, v[32:33], v[34:35] offset0:12 offset1:14
	ds_write2_b64 v49, v[16:17], v[18:19] offset0:20 offset1:22
	ds_write2_b64 v49, v[0:1], v[2:3] offset0:28 offset1:30
	s_add_i32 s2, s2, s20
	s_mulk_i32 s19, 0x1800
	s_nop 0
	s_add_u32 s3, s4, s19
	v_add3_u32 v14, s7, v144, v196
	s_addc_u32 s10, s5, s2
	ds_read_b128 v[0:3], v14 offset:40960
	s_add_u32 s2, s3, s6
	s_addc_u32 s3, s10, 0
	v_mov_b32_e32 v159, 0
	ds_read_b128 v[4:7], v14 offset:42048
	v_lshl_add_u64 v[8:9], s[2:3], 0, v[158:159]
	v_mov_b32_e32 v147, v159
	v_lshl_add_u64 v[10:11], v[8:9], 0, v[146:147]
	s_movk_i32 s2, 0x6000
	s_waitcnt lgkmcnt(1)
	global_store_dwordx4 v[10:11], v[0:3], off
	v_mov_b32_e32 v149, v159
	v_mov_b32_e32 v153, v159
	v_add_co_u32_e32 v0, vcc, s2, v10
	s_mov_b32 s2, 0xc000
	s_nop 0
	v_addc_co_u32_e32 v1, vcc, 0, v11, vcc
	s_waitcnt lgkmcnt(0)
	global_store_dwordx4 v[0:1], v[4:7], off
	ds_read_b128 v[0:3], v14 offset:43136
	ds_read_b128 v[4:7], v14 offset:44224
	v_add_co_u32_e32 v12, vcc, s2, v10
	s_mov_b32 s2, 0x12000
	s_nop 0
	v_addc_co_u32_e32 v13, vcc, 0, v11, vcc
	v_add_co_u32_e32 v10, vcc, s2, v10
	s_waitcnt lgkmcnt(1)
	global_store_dwordx4 v[12:13], v[0:3], off
	v_addc_co_u32_e32 v11, vcc, 0, v11, vcc
	ds_read_b128 v[0:3], v14 offset:45312
	s_waitcnt lgkmcnt(1)
	global_store_dwordx4 v[10:11], v[4:7], off
	ds_read_b128 v[4:7], v14 offset:46400
	v_lshl_add_u64 v[10:11], v[8:9], 0, v[148:149]
	v_mov_b32_e32 v151, v159
	s_waitcnt lgkmcnt(1)
	global_store_dwordx4 v[10:11], v[0:3], off
	v_lshl_add_u64 v[10:11], v[8:9], 0, v[152:153]
	ds_read_b128 v[0:3], v14 offset:47488
	s_waitcnt lgkmcnt(1)
	global_store_dwordx4 v[10:11], v[4:7], off
	ds_read_b128 v[4:7], v14 offset:48576
	v_lshl_add_u64 v[10:11], v[8:9], 0, v[150:151]
	v_mov_b32_e32 v155, v159
	v_readfirstlane_b32 s12, v222
	s_waitcnt lgkmcnt(1)
	global_store_dwordx4 v[10:11], v[0:3], off
	s_and_b32 s2, s12, 0xffffffc0
	s_nop 0
	v_lshl_add_u64 v[0:1], v[8:9], 0, v[154:155]
	s_waitcnt lgkmcnt(0)
	global_store_dwordx4 v[0:1], v[4:7], off
	v_or_b32_e32 v0, s2, v197
	s_mov_b32 s2, 0x2aaaaaab
	v_mul_hi_i32 v1, v0, s2
	v_lshrrev_b32_e32 v2, 31, v1
	v_ashrrev_i32_e32 v1, 2, v1
	v_add_u32_e32 v2, v1, v2
	s_movk_i32 s2, 0xffe8
	v_lshrrev_b32_e32 v159, 1, v2
	v_mad_u64_u32 v[160:161], s[2:3], v2, s2, v[0:1]
	v_xor_b32_e32 v1, v159, v222
	v_bfi_b32 v1, -8, v160, v1
	v_cmp_lt_i32_e32 vcc, 15, v1
	v_add_u32_e32 v2, s8, v2
	s_and_saveexec_b64 s[2:3], vcc
	s_xor_b64 s[2:3], exec, s[2:3]
	v_mov_b32_e32 v3, 0xbfff80
	v_lshl_add_u32 v153, v2, 6, v3
	s_or_saveexec_b64 s[2:3], s[2:3]
	v_mov_b32_e32 v145, 0x1000
	s_xor_b64 exec, exec, s[2:3]
	v_lshl_or_b32 v2, v2, 11, s17
	v_add_u32_e32 v153, 0x8000000, v2
	v_mov_b32_e32 v145, 0x20000
	s_or_b64 exec, exec, s[2:3]
	v_add_u32_e32 v2, 0x200, v0
	s_mov_b32 s2, 0x2aaaaaab
	v_mul_hi_i32 v3, v2, s2
	v_lshrrev_b32_e32 v4, 31, v3
	v_ashrrev_i32_e32 v3, 2, v3
	v_add_u32_e32 v4, v3, v4
	s_movk_i32 s2, 0xffe8
	v_mad_u64_u32 v[162:163], s[2:3], v4, s2, v[2:3]
	v_lshrrev_b32_e32 v163, 1, v4
	v_xor_b32_e32 v3, v163, v222
	v_bfi_b32 v3, -8, v162, v3
	v_cmp_lt_i32_e32 vcc, 15, v3
	v_add_u32_e32 v4, s8, v4
	s_and_saveexec_b64 s[2:3], vcc
	s_xor_b64 s[2:3], exec, s[2:3]
	v_mov_b32_e32 v5, 0xbfff80
	v_lshl_add_u32 v155, v4, 6, v5
	s_or_saveexec_b64 s[2:3], s[2:3]
	v_mov_b32_e32 v147, 0x1000
	s_xor_b64 exec, exec, s[2:3]
	v_lshl_or_b32 v4, v4, 11, s17
	v_add_u32_e32 v155, 0x8000000, v4
	v_mov_b32_e32 v147, 0x20000
	s_or_b64 exec, exec, s[2:3]
	v_add_u32_e32 v4, 0x400, v0
	s_mov_b32 s2, 0x2aaaaaab
	v_mul_hi_i32 v5, v4, s2
	v_lshrrev_b32_e32 v6, 31, v5
	v_ashrrev_i32_e32 v5, 2, v5
	v_add_u32_e32 v5, v5, v6
	s_movk_i32 s2, 0xffe8
	v_mad_u64_u32 v[164:165], s[2:3], v5, s2, v[4:5]
	v_lshrrev_b32_e32 v165, 1, v5
	v_xor_b32_e32 v4, v165, v222
	v_bfi_b32 v4, -8, v164, v4
	v_cmp_lt_i32_e32 vcc, 15, v4
	v_add_u32_e32 v5, s8, v5
	s_and_saveexec_b64 s[2:3], vcc
	s_xor_b64 s[2:3], exec, s[2:3]
	v_mov_b32_e32 v6, 0xbfff80
	v_lshl_add_u32 v161, v5, 6, v6
	s_or_saveexec_b64 s[2:3], s[2:3]
	v_mov_b32_e32 v149, 0x1000
	s_xor_b64 exec, exec, s[2:3]
	v_lshl_or_b32 v5, v5, 11, s17
	v_add_u32_e32 v161, 0x8000000, v5
	v_mov_b32_e32 v149, 0x20000
	s_or_b64 exec, exec, s[2:3]
	s_lshr_b32 s21, s12, 6
	s_or_b32 s22, s16, 0x800
	s_lshl_b32 s23, s21, 5
	s_or_b32 s2, s8, s22
	s_add_u32 s19, s2, s23
	v_or_b32_e32 v5, s19, v194
	s_movk_i32 s2, 0x1800
	v_mov_b64_e32 v[6:7], s[4:5]
	s_addc_u32 s20, s9, 0
	v_mad_u64_u32 v[6:7], s[2:3], v5, s2, v[6:7]
	v_mov_b32_e32 v5, 0x1800
	s_mov_b32 s7, 0
	v_mad_i32_i24 v7, s20, v5, v7
	v_lshl_add_u32 v8, v1, 3, v153
	v_ashrrev_i32_e32 v1, 31, v0
	v_lshl_add_u64 v[6:7], v[6:7], 0, s[6:7]
	v_mov_b32_e32 v157, 0
	v_lshrrev_b32_e32 v10, 28, v1
	v_lshl_add_u64 v[6:7], v[6:7], 0, v[156:157]
	v_lshl_add_u32 v4, v4, 3, v161
	v_mov_b32_e32 v5, v157
	v_add_u32_e32 v16, v0, v10
	global_load_dwordx4 v[96:99], v[6:7], off
	global_load_dwordx4 v[100:103], v[6:7], off offset:32
	global_load_dwordx4 v[104:107], v[6:7], off offset:64
	global_load_dwordx4 v[108:111], v[6:7], off offset:96
	global_load_dwordx4 v[112:115], v[6:7], off offset:128
	global_load_dwordx4 v[116:119], v[6:7], off offset:160
	global_load_dwordx4 v[120:123], v[6:7], off offset:192
	global_load_dwordx4 v[124:127], v[6:7], off offset:224
	global_load_dwordx4 v[128:131], v[6:7], off offset:256
	global_load_dwordx4 v[132:135], v[6:7], off offset:288
	global_load_dwordx4 v[136:139], v[6:7], off offset:320
	global_load_dwordx4 v[140:143], v[6:7], off offset:352
	v_lshl_add_u32 v6, v3, 3, v155
	v_ashrrev_i32_e32 v3, 31, v2
	v_lshl_add_u64 v[14:15], v[4:5], 1, s[84:85]
	v_ashrrev_i32_e32 v167, 4, v16
	v_and_b32_e32 v5, 0x1ffffff0, v16
	v_lshrrev_b32_e32 v11, 28, v3
	v_mov_b32_e32 v9, v157
	s_lshl_b32 s2, s21, 10
	v_sub_u32_e32 v0, v0, v5
	v_lshlrev_b32_e32 v5, 2, v167
	v_mov_b32_e32 v7, v157
	v_add_u32_e32 v17, v2, v11
	v_lshl_add_u64 v[10:11], v[8:9], 1, s[84:85]
	v_bfe_u32 v9, v167, 2, 2
	s_add_i32 s7, s2, 0
	v_and_b32_e32 v5, 12, v5
	v_lshl_add_u64 v[12:13], v[6:7], 1, s[84:85]
	v_ashrrev_i32_e32 v166, 4, v17
	v_and_b32_e32 v7, 0x1ffffff0, v17
	v_bitop3_b32 v0, v5, v0, v9 bitop3:0x36
	s_mov_b32 m0, s7
	v_add_lshl_u32 v16, v167, s8, 11
	v_sub_u32_e32 v2, v2, v7
	v_lshlrev_b32_e32 v7, 2, v166
	global_load_lds_dwordx4 v[10:11], off
	s_add_i32 m0, s7, 0x2000
	v_lshlrev_b32_e32 v168, 3, v0
	v_mov_b32_e32 v1, v157
	v_bfe_u32 v17, v166, 2, 2
	v_and_b32_e32 v7, 12, v7
	global_load_lds_dwordx4 v[12:13], off
	s_add_i32 m0, s7, 0x4000
	v_add3_u32 v0, s18, v16, v168
	v_bitop3_b32 v2, v7, v2, v17 bitop3:0x36
	global_load_lds_dwordx4 v[14:15], off
	s_add_i32 m0, s7, 0x6000
	v_lshl_add_u64 v[10:11], v[0:1], 1, s[84:85]
	v_add_lshl_u32 v18, v166, s8, 11
	v_lshlrev_b32_e32 v169, 3, v2
	global_load_lds_dwordx4 v[10:11], off
	s_add_i32 m0, s7, 0x8000
	v_mov_b32_e32 v3, v157
	v_add3_u32 v2, s18, v18, v169
	s_cmpk_gt_u32 s12, 0xff
	v_lshl_add_u64 v[12:13], v[2:3], 1, s[84:85]
	s_cselect_b64 s[10:11], -1, 0
	s_cmpk_lt_u32 s12, 0x100
	v_add_u32_e32 v8, v8, v145
	v_mov_b32_e32 v9, v157
	global_load_lds_dwordx4 v[12:13], off
	s_cselect_b64 s[12:13], -1, 0
	s_add_i32 m0, s7, 0xa000
	v_lshl_add_u64 v[8:9], v[8:9], 1, s[84:85]
	v_add_u32_e32 v6, v6, v147
	v_mov_b32_e32 v7, v157
	s_waitcnt vmcnt(0) lgkmcnt(0)
	s_barrier
	s_waitcnt vmcnt(0)
	global_load_lds_dwordx4 v[8:9], off
	v_lshl_add_u64 v[6:7], v[6:7], 1, s[84:85]
	s_add_i32 m0, s7, 0xc000
	v_add_u32_e32 v4, v4, v149
	v_mov_b32_e32 v5, v157
	global_load_lds_dwordx4 v[6:7], off
	v_lshl_add_u64 v[4:5], v[4:5], 1, s[84:85]
	s_add_i32 m0, s7, 0xe000
	v_add_u32_e32 v0, 0x20000, v0
	v_mov_b32_e32 v1, v157
	global_load_lds_dwordx4 v[4:5], off
	s_add_i32 m0, s7, 0x10000
	v_lshl_add_u64 v[0:1], v[0:1], 1, s[84:85]
	global_load_lds_dwordx4 v[0:1], off
	v_add_u32_e32 v0, 0x20000, v2
	v_mov_b32_e32 v1, v157
	v_lshl_add_u64 v[0:1], v[0:1], 1, s[84:85]
	s_add_i32 m0, s7, 0x12000
	s_and_b64 vcc, exec, s[12:13]
	global_load_lds_dwordx4 v[0:1], off
	ds_read_b128 v[0:3], v190
	ds_read_b128 v[4:7], v191
	ds_read_b128 v[8:11], v192
	ds_read_b128 v[12:15], v193
	s_waitcnt lgkmcnt(3)
	v_mfma_f32_32x32x16_bf16 v[48:63], v[0:3], v[96:99], 0
	ds_read_b128 v[0:3], v190 offset:128
	s_waitcnt lgkmcnt(3)
	v_mfma_f32_32x32x16_bf16 v[48:63], v[4:7], v[100:103], v[48:63]
	ds_read_b128 v[4:7], v191 offset:128
	s_waitcnt lgkmcnt(3)
	v_mfma_f32_32x32x16_bf16 v[48:63], v[8:11], v[104:107], v[48:63]
	ds_read_b128 v[8:11], v192 offset:128
	s_waitcnt lgkmcnt(3)
	v_mfma_f32_32x32x16_bf16 v[48:63], v[12:15], v[108:111], v[48:63]
	ds_read_b128 v[12:15], v193 offset:128
	s_waitcnt lgkmcnt(3)
	v_mfma_f32_32x32x16_bf16 v[48:63], v[0:3], v[112:115], v[48:63]
	ds_read_b128 v[0:3], v190 offset:256
	s_waitcnt lgkmcnt(3)
	v_mfma_f32_32x32x16_bf16 v[48:63], v[4:7], v[116:119], v[48:63]
	ds_read_b128 v[4:7], v191 offset:256
	s_waitcnt lgkmcnt(3)
	v_mfma_f32_32x32x16_bf16 v[48:63], v[8:11], v[120:123], v[48:63]
	ds_read_b128 v[8:11], v192 offset:256
	s_waitcnt lgkmcnt(3)
	v_mfma_f32_32x32x16_bf16 v[48:63], v[12:15], v[124:127], v[48:63]
	ds_read_b128 v[12:15], v193 offset:256
	s_waitcnt lgkmcnt(3)
	v_mfma_f32_32x32x16_bf16 v[48:63], v[0:3], v[128:131], v[48:63]
	ds_read_b128 v[0:3], v190 offset:12288
	s_waitcnt lgkmcnt(3)
	v_mfma_f32_32x32x16_bf16 v[48:63], v[4:7], v[132:135], v[48:63]
	ds_read_b128 v[4:7], v191 offset:12288
	s_waitcnt lgkmcnt(3)
	v_mfma_f32_32x32x16_bf16 v[48:63], v[8:11], v[136:139], v[48:63]
	ds_read_b128 v[8:11], v192 offset:12288
	s_waitcnt lgkmcnt(2)
	v_mfma_f32_32x32x16_bf16 v[80:95], v[0:3], v[96:99], 0
	ds_read_b128 v[16:19], v193 offset:12288
	s_waitcnt lgkmcnt(2)
	v_mfma_f32_32x32x16_bf16 v[80:95], v[4:7], v[100:103], v[80:95]
	ds_read_b128 v[20:23], v190 offset:12416
	s_waitcnt lgkmcnt(2)
	v_mfma_f32_32x32x16_bf16 v[80:95], v[8:11], v[104:107], v[80:95]
	ds_read_b128 v[24:27], v191 offset:12416
	s_waitcnt lgkmcnt(2)
	v_mfma_f32_32x32x16_bf16 v[80:95], v[16:19], v[108:111], v[80:95]
	ds_read_b128 v[28:31], v192 offset:12416
	s_waitcnt lgkmcnt(2)
	v_mfma_f32_32x32x16_bf16 v[80:95], v[20:23], v[112:115], v[80:95]
	ds_read_b128 v[32:35], v193 offset:12416
	s_waitcnt lgkmcnt(2)
	v_mfma_f32_32x32x16_bf16 v[80:95], v[24:27], v[116:119], v[80:95]
	ds_read_b128 v[36:39], v190 offset:12544
	s_waitcnt lgkmcnt(2)
	v_mfma_f32_32x32x16_bf16 v[80:95], v[28:31], v[120:123], v[80:95]
	ds_read_b128 v[40:43], v191 offset:12544
	s_waitcnt lgkmcnt(2)
	v_mfma_f32_32x32x16_bf16 v[80:95], v[32:35], v[124:127], v[80:95]
	ds_read_b128 v[44:47], v192 offset:12544
	s_waitcnt lgkmcnt(2)
	v_mfma_f32_32x32x16_bf16 v[80:95], v[36:39], v[128:131], v[80:95]
	ds_read_b128 v[64:67], v193 offset:12544
	s_waitcnt lgkmcnt(2)
	v_mfma_f32_32x32x16_bf16 v[80:95], v[40:43], v[132:135], v[80:95]
	s_waitcnt lgkmcnt(1)
	v_mfma_f32_32x32x16_bf16 v[80:95], v[44:47], v[136:139], v[80:95]
	s_waitcnt lgkmcnt(0)
	v_mfma_f32_32x32x16_bf16 v[80:95], v[64:67], v[140:143], v[80:95]
	v_mfma_f32_32x32x16_bf16 v[48:63], v[12:15], v[140:143], v[48:63]
	s_cbranch_vccnz .LBB0_1979
	s_waitcnt vmcnt(0) lgkmcnt(0)
	s_barrier

.LBB0_1999:
	s_setprio 0
	v_mov_b32_e32 v48, v157
	s_nop 1
	v_permlane32_swap_b32_e32 v157, v48
	v_add_f32_e32 v48, v157, v48
	v_div_scale_f32 v49, s[2:3], v48, v48, 1.0
	v_rcp_f32_e32 v50, v49
	s_mulk_i32 s21, 0x2200
	s_add_i32 s7, s21, 0
	s_waitcnt vmcnt(0) lgkmcnt(0)
	s_barrier
	v_fma_f32 v51, -v49, v50, 1.0
	v_fmac_f32_e32 v50, v51, v50
	v_div_scale_f32 v51, vcc, 1.0, v48, 1.0
	v_mul_f32_e32 v52, v51, v50
	v_fma_f32 v53, -v49, v52, v51
	v_fmac_f32_e32 v52, v53, v50
	v_fma_f32 v49, -v49, v52, v51
	v_div_fmas_f32 v49, v49, v50, v52
	v_div_fixup_f32 v48, v49, v48, 1.0
	v_add3_u32 v49, s7, v195, v181
	v_pk_mul_f32 v[50:51], v[64:65], v[48:49] op_sel_hi:[1,0]
	v_pk_mul_f32 v[52:53], v[66:67], v[48:49] op_sel_hi:[1,0]
	v_cvt_pk_bf16_f32 v50, v50, v51
	v_cvt_pk_bf16_f32 v51, v52, v53
	v_pk_mul_f32 v[52:53], v[68:69], v[48:49] op_sel_hi:[1,0]
	v_pk_mul_f32 v[54:55], v[70:71], v[48:49] op_sel_hi:[1,0]
	v_add_u32_e32 v49, 0xa000, v49
	v_pk_mul_f32 v[32:33], v[32:33], v[48:49] op_sel_hi:[1,0]
	v_pk_mul_f32 v[34:35], v[34:35], v[48:49] op_sel_hi:[1,0]
	v_pk_mul_f32 v[16:17], v[16:17], v[48:49] op_sel_hi:[1,0]
	v_pk_mul_f32 v[18:19], v[18:19], v[48:49] op_sel_hi:[1,0]
	v_pk_mul_f32 v[0:1], v[0:1], v[48:49] op_sel_hi:[1,0]
	v_pk_mul_f32 v[2:3], v[2:3], v[48:49] op_sel_hi:[1,0]
	v_cvt_pk_bf16_f32 v32, v32, v33
	v_cvt_pk_bf16_f32 v33, v34, v35
	v_pk_mul_f32 v[34:35], v[36:37], v[48:49] op_sel_hi:[1,0]
	v_pk_mul_f32 v[36:37], v[38:39], v[48:49] op_sel_hi:[1,0]
	v_cvt_pk_bf16_f32 v16, v16, v17
	v_cvt_pk_bf16_f32 v17, v18, v19
	v_pk_mul_f32 v[18:19], v[20:21], v[48:49] op_sel_hi:[1,0]
	v_pk_mul_f32 v[20:21], v[22:23], v[48:49] op_sel_hi:[1,0]
	v_cvt_pk_bf16_f32 v0, v0, v1
	v_cvt_pk_bf16_f32 v1, v2, v3
	v_pk_mul_f32 v[2:3], v[4:5], v[48:49] op_sel_hi:[1,0]
	v_pk_mul_f32 v[4:5], v[6:7], v[48:49] op_sel_hi:[1,0]
	v_cvt_pk_bf16_f32 v52, v52, v53
	v_cvt_pk_bf16_f32 v53, v54, v55
	v_cvt_pk_bf16_f32 v34, v34, v35
	v_cvt_pk_bf16_f32 v35, v36, v37
	v_cvt_pk_bf16_f32 v18, v18, v19
	v_cvt_pk_bf16_f32 v19, v20, v21
	v_cvt_pk_bf16_f32 v2, v2, v3
	v_cvt_pk_bf16_f32 v3, v4, v5
	ds_write2_b64 v49, v[50:51], v[52:53] offset1:2
	v_pk_mul_f32 v[50:51], v[72:73], v[48:49] op_sel_hi:[1,0]
	v_pk_mul_f32 v[52:53], v[74:75], v[48:49] op_sel_hi:[1,0]
	ds_write2_b64 v49, v[32:33], v[34:35] offset0:8 offset1:10
	v_pk_mul_f32 v[32:33], v[40:41], v[48:49] op_sel_hi:[1,0]
	v_pk_mul_f32 v[34:35], v[42:43], v[48:49] op_sel_hi:[1,0]
	ds_write2_b64 v49, v[16:17], v[18:19] offset0:16 offset1:18
	v_pk_mul_f32 v[16:17], v[24:25], v[48:49] op_sel_hi:[1,0]
	v_pk_mul_f32 v[18:19], v[26:27], v[48:49] op_sel_hi:[1,0]
	ds_write2_b64 v49, v[0:1], v[2:3] offset0:24 offset1:26
	v_pk_mul_f32 v[0:1], v[8:9], v[48:49] op_sel_hi:[1,0]
	v_pk_mul_f32 v[2:3], v[10:11], v[48:49] op_sel_hi:[1,0]
	v_cvt_pk_bf16_f32 v50, v50, v51
	v_cvt_pk_bf16_f32 v51, v52, v53
	v_pk_mul_f32 v[52:53], v[76:77], v[48:49] op_sel_hi:[1,0]
	v_pk_mul_f32 v[54:55], v[78:79], v[48:49] op_sel_hi:[1,0]
	v_cvt_pk_bf16_f32 v32, v32, v33
	v_cvt_pk_bf16_f32 v33, v34, v35
	v_pk_mul_f32 v[34:35], v[44:45], v[48:49] op_sel_hi:[1,0]
	v_pk_mul_f32 v[36:37], v[46:47], v[48:49] op_sel_hi:[1,0]
	v_cvt_pk_bf16_f32 v16, v16, v17
	v_cvt_pk_bf16_f32 v17, v18, v19
	v_pk_mul_f32 v[18:19], v[28:29], v[48:49] op_sel_hi:[1,0]
	v_pk_mul_f32 v[20:21], v[30:31], v[48:49] op_sel_hi:[1,0]
	v_cvt_pk_bf16_f32 v0, v0, v1
	v_cvt_pk_bf16_f32 v1, v2, v3
	v_pk_mul_f32 v[2:3], v[12:13], v[48:49] op_sel_hi:[1,0]
	v_pk_mul_f32 v[4:5], v[14:15], v[48:49] op_sel_hi:[1,0]
	v_cvt_pk_bf16_f32 v52, v52, v53
	v_cvt_pk_bf16_f32 v53, v54, v55
	v_cvt_pk_bf16_f32 v34, v34, v35
	v_cvt_pk_bf16_f32 v35, v36, v37
	v_cvt_pk_bf16_f32 v18, v18, v19
	v_cvt_pk_bf16_f32 v19, v20, v21
	v_cvt_pk_bf16_f32 v2, v2, v3
	v_cvt_pk_bf16_f32 v3, v4, v5
	s_mulk_i32 s20, 0x1800
	s_mul_hi_u32 s2, s19, 0x1800
	ds_write2_b64 v49, v[50:51], v[52:53] offset0:4 offset1:6
	ds_write2_b64 v49, v[32:33], v[34:35] offset0:12 offset1:14
	ds_write2_b64 v49, v[16:17], v[18:19] offset0:20 offset1:22
	ds_write2_b64 v49, v[0:1], v[2:3] offset0:28 offset1:30
	s_add_i32 s2, s2, s20
	s_mulk_i32 s19, 0x1800
	s_nop 0
	s_add_u32 s3, s4, s19
	v_add3_u32 v14, s7, v144, v196
	s_addc_u32 s10, s5, s2
	ds_read_b128 v[0:3], v14 offset:40960
	s_add_u32 s2, s3, s6
	s_addc_u32 s3, s10, 0
	v_mov_b32_e32 v159, 0
	ds_read_b128 v[4:7], v14 offset:42048
	v_lshl_add_u64 v[8:9], s[2:3], 0, v[158:159]
	v_mov_b32_e32 v147, v159
	v_lshl_add_u64 v[10:11], v[8:9], 0, v[146:147]
	s_movk_i32 s2, 0x6000
	s_waitcnt lgkmcnt(1)
	global_store_dwordx4 v[10:11], v[0:3], off
	v_mov_b32_e32 v149, v159
	v_mov_b32_e32 v153, v159
	v_add_co_u32_e32 v0, vcc, s2, v10
	s_mov_b32 s2, 0xc000
	s_nop 0
	v_addc_co_u32_e32 v1, vcc, 0, v11, vcc
	s_waitcnt lgkmcnt(0)
	global_store_dwordx4 v[0:1], v[4:7], off
	ds_read_b128 v[0:3], v14 offset:43136
	ds_read_b128 v[4:7], v14 offset:44224
	v_add_co_u32_e32 v12, vcc, s2, v10
	s_mov_b32 s2, 0x12000
	s_nop 0
	v_addc_co_u32_e32 v13, vcc, 0, v11, vcc
	v_add_co_u32_e32 v10, vcc, s2, v10
	s_waitcnt lgkmcnt(1)
	global_store_dwordx4 v[12:13], v[0:3], off
	v_addc_co_u32_e32 v11, vcc, 0, v11, vcc
	ds_read_b128 v[0:3], v14 offset:45312
	s_waitcnt lgkmcnt(1)
	global_store_dwordx4 v[10:11], v[4:7], off
	ds_read_b128 v[4:7], v14 offset:46400
	v_lshl_add_u64 v[10:11], v[8:9], 0, v[148:149]
	v_mov_b32_e32 v151, v159
	s_waitcnt lgkmcnt(1)
	global_store_dwordx4 v[10:11], v[0:3], off
	v_lshl_add_u64 v[10:11], v[8:9], 0, v[152:153]
	ds_read_b128 v[0:3], v14 offset:47488
	s_waitcnt lgkmcnt(1)
	global_store_dwordx4 v[10:11], v[4:7], off
	ds_read_b128 v[4:7], v14 offset:48576
	v_lshl_add_u64 v[10:11], v[8:9], 0, v[150:151]
	v_mov_b32_e32 v155, v159
	v_readfirstlane_b32 s12, v222
	s_waitcnt lgkmcnt(1)
	global_store_dwordx4 v[10:11], v[0:3], off
	s_and_b32 s2, s12, 0xffffffc0
	s_nop 0
	v_lshl_add_u64 v[0:1], v[8:9], 0, v[154:155]
	s_waitcnt lgkmcnt(0)
	global_store_dwordx4 v[0:1], v[4:7], off
	v_or_b32_e32 v0, s2, v197
	s_mov_b32 s2, 0x2aaaaaab
	v_mul_hi_i32 v1, v0, s2
	v_lshrrev_b32_e32 v2, 31, v1
	v_ashrrev_i32_e32 v1, 2, v1
	v_add_u32_e32 v2, v1, v2
	s_movk_i32 s2, 0xffe8
	v_lshrrev_b32_e32 v159, 1, v2
	v_mad_u64_u32 v[160:161], s[2:3], v2, s2, v[0:1]
	v_xor_b32_e32 v1, v159, v222
	v_bfi_b32 v1, -8, v160, v1
	v_cmp_lt_i32_e32 vcc, 15, v1
	v_add_u32_e32 v2, s8, v2
	s_and_saveexec_b64 s[2:3], vcc
	s_xor_b64 s[2:3], exec, s[2:3]
	v_mov_b32_e32 v3, 0xbfff80
	v_lshl_add_u32 v153, v2, 6, v3
	s_or_saveexec_b64 s[2:3], s[2:3]
	v_mov_b32_e32 v145, 0x1000
	s_xor_b64 exec, exec, s[2:3]
	v_lshl_or_b32 v2, v2, 11, s17
	v_add_u32_e32 v153, 0x8000000, v2
	v_mov_b32_e32 v145, 0x20000
	s_or_b64 exec, exec, s[2:3]
	v_add_u32_e32 v2, 0x200, v0
	s_mov_b32 s2, 0x2aaaaaab
	v_mul_hi_i32 v3, v2, s2
	v_lshrrev_b32_e32 v4, 31, v3
	v_ashrrev_i32_e32 v3, 2, v3
	v_add_u32_e32 v4, v3, v4
	s_movk_i32 s2, 0xffe8
	v_mad_u64_u32 v[162:163], s[2:3], v4, s2, v[2:3]
	v_lshrrev_b32_e32 v163, 1, v4
	v_xor_b32_e32 v3, v163, v222
	v_bfi_b32 v3, -8, v162, v3
	v_cmp_lt_i32_e32 vcc, 15, v3
	v_add_u32_e32 v4, s8, v4
	s_and_saveexec_b64 s[2:3], vcc
	s_xor_b64 s[2:3], exec, s[2:3]
	v_mov_b32_e32 v5, 0xbfff80
	v_lshl_add_u32 v155, v4, 6, v5
	s_or_saveexec_b64 s[2:3], s[2:3]
	v_mov_b32_e32 v147, 0x1000
	s_xor_b64 exec, exec, s[2:3]
	v_lshl_or_b32 v4, v4, 11, s17
	v_add_u32_e32 v155, 0x8000000, v4
	v_mov_b32_e32 v147, 0x20000
	s_or_b64 exec, exec, s[2:3]
	v_add_u32_e32 v4, 0x400, v0
	s_mov_b32 s2, 0x2aaaaaab
	v_mul_hi_i32 v5, v4, s2
	v_lshrrev_b32_e32 v6, 31, v5
	v_ashrrev_i32_e32 v5, 2, v5
	v_add_u32_e32 v5, v5, v6
	s_movk_i32 s2, 0xffe8
	v_mad_u64_u32 v[164:165], s[2:3], v5, s2, v[4:5]
	v_lshrrev_b32_e32 v165, 1, v5
	v_xor_b32_e32 v4, v165, v222
	v_bfi_b32 v4, -8, v164, v4
	v_cmp_lt_i32_e32 vcc, 15, v4
	v_add_u32_e32 v5, s8, v5
	s_and_saveexec_b64 s[2:3], vcc
	s_xor_b64 s[2:3], exec, s[2:3]
	v_mov_b32_e32 v6, 0xbfff80
	v_lshl_add_u32 v161, v5, 6, v6
	s_or_saveexec_b64 s[2:3], s[2:3]
	v_mov_b32_e32 v149, 0x1000
	s_xor_b64 exec, exec, s[2:3]
	v_lshl_or_b32 v5, v5, 11, s17
	v_add_u32_e32 v161, 0x8000000, v5
	v_mov_b32_e32 v149, 0x20000
	s_or_b64 exec, exec, s[2:3]
	s_lshr_b32 s21, s12, 6
	s_xor_b32 s22, s16, 0x700
	s_lshl_b32 s23, s21, 5
	s_or_b32 s2, s8, s22
	s_add_u32 s19, s2, s23
	v_or_b32_e32 v5, s19, v194
	s_movk_i32 s2, 0x1800
	v_mov_b64_e32 v[6:7], s[4:5]
	s_addc_u32 s20, s9, 0
	v_mad_u64_u32 v[6:7], s[2:3], v5, s2, v[6:7]
	v_mov_b32_e32 v5, 0x1800
	s_mov_b32 s7, 0
	v_mad_i32_i24 v7, s20, v5, v7
	v_lshl_add_u32 v8, v1, 3, v153
	v_ashrrev_i32_e32 v1, 31, v0
	v_lshl_add_u64 v[6:7], v[6:7], 0, s[6:7]
	v_mov_b32_e32 v157, 0
	v_lshrrev_b32_e32 v10, 28, v1
	v_lshl_add_u64 v[6:7], v[6:7], 0, v[156:157]
	v_lshl_add_u32 v4, v4, 3, v161
	v_mov_b32_e32 v5, v157
	v_add_u32_e32 v16, v0, v10
	global_load_dwordx4 v[96:99], v[6:7], off
	global_load_dwordx4 v[100:103], v[6:7], off offset:32
	global_load_dwordx4 v[104:107], v[6:7], off offset:64
	global_load_dwordx4 v[108:111], v[6:7], off offset:96
	global_load_dwordx4 v[112:115], v[6:7], off offset:128
	global_load_dwordx4 v[116:119], v[6:7], off offset:160
	global_load_dwordx4 v[120:123], v[6:7], off offset:192
	global_load_dwordx4 v[124:127], v[6:7], off offset:224
	global_load_dwordx4 v[128:131], v[6:7], off offset:256
	global_load_dwordx4 v[132:135], v[6:7], off offset:288
	global_load_dwordx4 v[136:139], v[6:7], off offset:320
	global_load_dwordx4 v[140:143], v[6:7], off offset:352
	v_lshl_add_u32 v6, v3, 3, v155
	v_ashrrev_i32_e32 v3, 31, v2
	v_lshl_add_u64 v[14:15], v[4:5], 1, s[84:85]
	v_ashrrev_i32_e32 v167, 4, v16
	v_and_b32_e32 v5, 0x1ffffff0, v16
	v_lshrrev_b32_e32 v11, 28, v3
	v_mov_b32_e32 v9, v157
	s_lshl_b32 s2, s21, 10
	v_sub_u32_e32 v0, v0, v5
	v_lshlrev_b32_e32 v5, 2, v167
	v_mov_b32_e32 v7, v157
	v_add_u32_e32 v17, v2, v11
	v_lshl_add_u64 v[10:11], v[8:9], 1, s[84:85]
	v_bfe_u32 v9, v167, 2, 2
	s_add_i32 s7, s2, 0
	v_and_b32_e32 v5, 12, v5
	v_lshl_add_u64 v[12:13], v[6:7], 1, s[84:85]
	v_ashrrev_i32_e32 v166, 4, v17
	v_and_b32_e32 v7, 0x1ffffff0, v17
	v_bitop3_b32 v0, v5, v0, v9 bitop3:0x36
	s_mov_b32 m0, s7
	v_add_lshl_u32 v16, v167, s8, 11
	v_sub_u32_e32 v2, v2, v7
	v_lshlrev_b32_e32 v7, 2, v166
	global_load_lds_dwordx4 v[10:11], off
	s_add_i32 m0, s7, 0x2000
	v_lshlrev_b32_e32 v168, 3, v0
	v_mov_b32_e32 v1, v157
	v_bfe_u32 v17, v166, 2, 2
	v_and_b32_e32 v7, 12, v7
	global_load_lds_dwordx4 v[12:13], off
	s_add_i32 m0, s7, 0x4000
	v_add3_u32 v0, s18, v16, v168
	v_bitop3_b32 v2, v7, v2, v17 bitop3:0x36
	global_load_lds_dwordx4 v[14:15], off
	s_add_i32 m0, s7, 0x6000
	v_lshl_add_u64 v[10:11], v[0:1], 1, s[84:85]
	v_add_lshl_u32 v18, v166, s8, 11
	v_lshlrev_b32_e32 v169, 3, v2
	global_load_lds_dwordx4 v[10:11], off
	s_add_i32 m0, s7, 0x8000
	v_mov_b32_e32 v3, v157
	v_add3_u32 v2, s18, v18, v169
	s_cmpk_gt_u32 s12, 0xff
	v_lshl_add_u64 v[12:13], v[2:3], 1, s[84:85]
	s_cselect_b64 s[10:11], -1, 0
	s_cmpk_lt_u32 s12, 0x100
	v_add_u32_e32 v8, v8, v145
	v_mov_b32_e32 v9, v157
	global_load_lds_dwordx4 v[12:13], off
	s_cselect_b64 s[12:13], -1, 0
	s_add_i32 m0, s7, 0xa000
	v_lshl_add_u64 v[8:9], v[8:9], 1, s[84:85]
	v_add_u32_e32 v6, v6, v147
	v_mov_b32_e32 v7, v157
	s_waitcnt vmcnt(0) lgkmcnt(0)
	s_barrier
	s_waitcnt vmcnt(0)
	global_load_lds_dwordx4 v[8:9], off
	v_lshl_add_u64 v[6:7], v[6:7], 1, s[84:85]
	s_add_i32 m0, s7, 0xc000
	v_add_u32_e32 v4, v4, v149
	v_mov_b32_e32 v5, v157
	global_load_lds_dwordx4 v[6:7], off
	v_lshl_add_u64 v[4:5], v[4:5], 1, s[84:85]
	s_add_i32 m0, s7, 0xe000
	v_add_u32_e32 v0, 0x20000, v0
	v_mov_b32_e32 v1, v157
	global_load_lds_dwordx4 v[4:5], off
	s_add_i32 m0, s7, 0x10000
	v_lshl_add_u64 v[0:1], v[0:1], 1, s[84:85]
	global_load_lds_dwordx4 v[0:1], off
	v_add_u32_e32 v0, 0x20000, v2
	v_mov_b32_e32 v1, v157
	v_lshl_add_u64 v[0:1], v[0:1], 1, s[84:85]
	s_add_i32 m0, s7, 0x12000
	s_and_b64 vcc, exec, s[12:13]
	global_load_lds_dwordx4 v[0:1], off
	ds_read_b128 v[0:3], v190
	ds_read_b128 v[4:7], v191
	ds_read_b128 v[8:11], v192
	ds_read_b128 v[12:15], v193
	s_waitcnt lgkmcnt(3)
	v_mfma_f32_32x32x16_bf16 v[48:63], v[0:3], v[96:99], 0
	ds_read_b128 v[0:3], v190 offset:128
	s_waitcnt lgkmcnt(3)
	v_mfma_f32_32x32x16_bf16 v[48:63], v[4:7], v[100:103], v[48:63]
	ds_read_b128 v[4:7], v191 offset:128
	s_waitcnt lgkmcnt(3)
	v_mfma_f32_32x32x16_bf16 v[48:63], v[8:11], v[104:107], v[48:63]
	ds_read_b128 v[8:11], v192 offset:128
	s_waitcnt lgkmcnt(3)
	v_mfma_f32_32x32x16_bf16 v[48:63], v[12:15], v[108:111], v[48:63]
	ds_read_b128 v[12:15], v193 offset:128
	s_waitcnt lgkmcnt(3)
	v_mfma_f32_32x32x16_bf16 v[48:63], v[0:3], v[112:115], v[48:63]
	ds_read_b128 v[0:3], v190 offset:256
	s_waitcnt lgkmcnt(3)
	v_mfma_f32_32x32x16_bf16 v[48:63], v[4:7], v[116:119], v[48:63]
	ds_read_b128 v[4:7], v191 offset:256
	s_waitcnt lgkmcnt(3)
	v_mfma_f32_32x32x16_bf16 v[48:63], v[8:11], v[120:123], v[48:63]
	ds_read_b128 v[8:11], v192 offset:256
	s_waitcnt lgkmcnt(3)
	v_mfma_f32_32x32x16_bf16 v[48:63], v[12:15], v[124:127], v[48:63]
	ds_read_b128 v[12:15], v193 offset:256
	s_waitcnt lgkmcnt(3)
	v_mfma_f32_32x32x16_bf16 v[48:63], v[0:3], v[128:131], v[48:63]
	ds_read_b128 v[0:3], v190 offset:12288
	s_waitcnt lgkmcnt(3)
	v_mfma_f32_32x32x16_bf16 v[48:63], v[4:7], v[132:135], v[48:63]
	ds_read_b128 v[4:7], v191 offset:12288
	s_waitcnt lgkmcnt(3)
	v_mfma_f32_32x32x16_bf16 v[48:63], v[8:11], v[136:139], v[48:63]
	ds_read_b128 v[8:11], v192 offset:12288
	s_waitcnt lgkmcnt(2)
	v_mfma_f32_32x32x16_bf16 v[80:95], v[0:3], v[96:99], 0
	ds_read_b128 v[16:19], v193 offset:12288
	s_waitcnt lgkmcnt(2)
	v_mfma_f32_32x32x16_bf16 v[80:95], v[4:7], v[100:103], v[80:95]
	ds_read_b128 v[20:23], v190 offset:12416
	s_waitcnt lgkmcnt(2)
	v_mfma_f32_32x32x16_bf16 v[80:95], v[8:11], v[104:107], v[80:95]
	ds_read_b128 v[24:27], v191 offset:12416
	s_waitcnt lgkmcnt(2)
	v_mfma_f32_32x32x16_bf16 v[80:95], v[16:19], v[108:111], v[80:95]
	ds_read_b128 v[28:31], v192 offset:12416
	s_waitcnt lgkmcnt(2)
	v_mfma_f32_32x32x16_bf16 v[80:95], v[20:23], v[112:115], v[80:95]
	ds_read_b128 v[32:35], v193 offset:12416
	s_waitcnt lgkmcnt(2)
	v_mfma_f32_32x32x16_bf16 v[80:95], v[24:27], v[116:119], v[80:95]
	ds_read_b128 v[36:39], v190 offset:12544
	s_waitcnt lgkmcnt(2)
	v_mfma_f32_32x32x16_bf16 v[80:95], v[28:31], v[120:123], v[80:95]
	ds_read_b128 v[40:43], v191 offset:12544
	s_waitcnt lgkmcnt(2)
	v_mfma_f32_32x32x16_bf16 v[80:95], v[32:35], v[124:127], v[80:95]
	ds_read_b128 v[44:47], v192 offset:12544
	s_waitcnt lgkmcnt(2)
	v_mfma_f32_32x32x16_bf16 v[80:95], v[36:39], v[128:131], v[80:95]
	ds_read_b128 v[64:67], v193 offset:12544
	s_waitcnt lgkmcnt(2)
	v_mfma_f32_32x32x16_bf16 v[80:95], v[40:43], v[132:135], v[80:95]
	s_waitcnt lgkmcnt(1)
	v_mfma_f32_32x32x16_bf16 v[80:95], v[44:47], v[136:139], v[80:95]
	s_waitcnt lgkmcnt(0)
	v_mfma_f32_32x32x16_bf16 v[80:95], v[64:67], v[140:143], v[80:95]
	v_mfma_f32_32x32x16_bf16 v[48:63], v[12:15], v[140:143], v[48:63]
	s_cbranch_vccnz .LBB0_2013
	s_waitcnt vmcnt(0) lgkmcnt(0)
	s_barrier

.LBB0_2033:
	s_setprio 0
	v_mov_b32_e32 v48, v157
	s_nop 1
	v_permlane32_swap_b32_e32 v157, v48
	v_add_f32_e32 v48, v157, v48
	v_div_scale_f32 v49, s[2:3], v48, v48, 1.0
	v_rcp_f32_e32 v50, v49
	s_mulk_i32 s21, 0x2200
	s_add_i32 s7, s21, 0
	s_waitcnt vmcnt(0) lgkmcnt(0)
	s_barrier
	v_fma_f32 v51, -v49, v50, 1.0
	v_fmac_f32_e32 v50, v51, v50
	v_div_scale_f32 v51, vcc, 1.0, v48, 1.0
	v_mul_f32_e32 v52, v51, v50
	v_fma_f32 v53, -v49, v52, v51
	v_fmac_f32_e32 v52, v53, v50
	v_fma_f32 v49, -v49, v52, v51
	v_div_fmas_f32 v49, v49, v50, v52
	v_div_fixup_f32 v48, v49, v48, 1.0
	v_add3_u32 v49, s7, v195, v181
	v_pk_mul_f32 v[50:51], v[64:65], v[48:49] op_sel_hi:[1,0]
	v_pk_mul_f32 v[52:53], v[66:67], v[48:49] op_sel_hi:[1,0]
	v_cvt_pk_bf16_f32 v50, v50, v51
	v_cvt_pk_bf16_f32 v51, v52, v53
	v_pk_mul_f32 v[52:53], v[68:69], v[48:49] op_sel_hi:[1,0]
	v_pk_mul_f32 v[54:55], v[70:71], v[48:49] op_sel_hi:[1,0]
	v_add_u32_e32 v49, 0xa000, v49
	v_pk_mul_f32 v[32:33], v[32:33], v[48:49] op_sel_hi:[1,0]
	v_pk_mul_f32 v[34:35], v[34:35], v[48:49] op_sel_hi:[1,0]
	v_pk_mul_f32 v[16:17], v[16:17], v[48:49] op_sel_hi:[1,0]
	v_pk_mul_f32 v[18:19], v[18:19], v[48:49] op_sel_hi:[1,0]
	v_pk_mul_f32 v[0:1], v[0:1], v[48:49] op_sel_hi:[1,0]
	v_pk_mul_f32 v[2:3], v[2:3], v[48:49] op_sel_hi:[1,0]
	v_cvt_pk_bf16_f32 v32, v32, v33
	v_cvt_pk_bf16_f32 v33, v34, v35
	v_pk_mul_f32 v[34:35], v[36:37], v[48:49] op_sel_hi:[1,0]
	v_pk_mul_f32 v[36:37], v[38:39], v[48:49] op_sel_hi:[1,0]
	v_cvt_pk_bf16_f32 v16, v16, v17
	v_cvt_pk_bf16_f32 v17, v18, v19
	v_pk_mul_f32 v[18:19], v[20:21], v[48:49] op_sel_hi:[1,0]
	v_pk_mul_f32 v[20:21], v[22:23], v[48:49] op_sel_hi:[1,0]
	v_cvt_pk_bf16_f32 v0, v0, v1
	v_cvt_pk_bf16_f32 v1, v2, v3
	v_pk_mul_f32 v[2:3], v[4:5], v[48:49] op_sel_hi:[1,0]
	v_pk_mul_f32 v[4:5], v[6:7], v[48:49] op_sel_hi:[1,0]
	v_cvt_pk_bf16_f32 v52, v52, v53
	v_cvt_pk_bf16_f32 v53, v54, v55
	v_cvt_pk_bf16_f32 v34, v34, v35
	v_cvt_pk_bf16_f32 v35, v36, v37
	v_cvt_pk_bf16_f32 v18, v18, v19
	v_cvt_pk_bf16_f32 v19, v20, v21
	v_cvt_pk_bf16_f32 v2, v2, v3
	v_cvt_pk_bf16_f32 v3, v4, v5
	ds_write2_b64 v49, v[50:51], v[52:53] offset1:2
	v_pk_mul_f32 v[50:51], v[72:73], v[48:49] op_sel_hi:[1,0]
	v_pk_mul_f32 v[52:53], v[74:75], v[48:49] op_sel_hi:[1,0]
	ds_write2_b64 v49, v[32:33], v[34:35] offset0:8 offset1:10
	v_pk_mul_f32 v[32:33], v[40:41], v[48:49] op_sel_hi:[1,0]
	v_pk_mul_f32 v[34:35], v[42:43], v[48:49] op_sel_hi:[1,0]
	ds_write2_b64 v49, v[16:17], v[18:19] offset0:16 offset1:18
	v_pk_mul_f32 v[16:17], v[24:25], v[48:49] op_sel_hi:[1,0]
	v_pk_mul_f32 v[18:19], v[26:27], v[48:49] op_sel_hi:[1,0]
	ds_write2_b64 v49, v[0:1], v[2:3] offset0:24 offset1:26
	v_pk_mul_f32 v[0:1], v[8:9], v[48:49] op_sel_hi:[1,0]
	v_pk_mul_f32 v[2:3], v[10:11], v[48:49] op_sel_hi:[1,0]
	v_cvt_pk_bf16_f32 v50, v50, v51
	v_cvt_pk_bf16_f32 v51, v52, v53
	v_pk_mul_f32 v[52:53], v[76:77], v[48:49] op_sel_hi:[1,0]
	v_pk_mul_f32 v[54:55], v[78:79], v[48:49] op_sel_hi:[1,0]
	v_cvt_pk_bf16_f32 v32, v32, v33
	v_cvt_pk_bf16_f32 v33, v34, v35
	v_pk_mul_f32 v[34:35], v[44:45], v[48:49] op_sel_hi:[1,0]
	v_pk_mul_f32 v[36:37], v[46:47], v[48:49] op_sel_hi:[1,0]
	v_cvt_pk_bf16_f32 v16, v16, v17
	v_cvt_pk_bf16_f32 v17, v18, v19
	v_pk_mul_f32 v[18:19], v[28:29], v[48:49] op_sel_hi:[1,0]
	v_pk_mul_f32 v[20:21], v[30:31], v[48:49] op_sel_hi:[1,0]
	v_cvt_pk_bf16_f32 v0, v0, v1
	v_cvt_pk_bf16_f32 v1, v2, v3
	v_pk_mul_f32 v[2:3], v[12:13], v[48:49] op_sel_hi:[1,0]
	v_pk_mul_f32 v[4:5], v[14:15], v[48:49] op_sel_hi:[1,0]
	v_cvt_pk_bf16_f32 v52, v52, v53
	v_cvt_pk_bf16_f32 v53, v54, v55
	v_cvt_pk_bf16_f32 v34, v34, v35
	v_cvt_pk_bf16_f32 v35, v36, v37
	v_cvt_pk_bf16_f32 v18, v18, v19
	v_cvt_pk_bf16_f32 v19, v20, v21
	v_cvt_pk_bf16_f32 v2, v2, v3
	v_cvt_pk_bf16_f32 v3, v4, v5
	s_mulk_i32 s20, 0x1800
	s_mul_hi_u32 s2, s19, 0x1800
	ds_write2_b64 v49, v[50:51], v[52:53] offset0:4 offset1:6
	ds_write2_b64 v49, v[32:33], v[34:35] offset0:12 offset1:14
	ds_write2_b64 v49, v[16:17], v[18:19] offset0:20 offset1:22
	ds_write2_b64 v49, v[0:1], v[2:3] offset0:28 offset1:30
	s_add_i32 s2, s2, s20
	s_mulk_i32 s19, 0x1800
	s_nop 0
	s_add_u32 s3, s4, s19
	v_add3_u32 v14, s7, v144, v196
	s_addc_u32 s10, s5, s2
	ds_read_b128 v[0:3], v14 offset:40960
	s_add_u32 s2, s3, s6
	s_addc_u32 s3, s10, 0
	v_mov_b32_e32 v159, 0
	ds_read_b128 v[4:7], v14 offset:42048
	v_lshl_add_u64 v[8:9], s[2:3], 0, v[158:159]
	v_mov_b32_e32 v147, v159
	v_lshl_add_u64 v[10:11], v[8:9], 0, v[146:147]
	s_movk_i32 s2, 0x6000
	s_waitcnt lgkmcnt(1)
	global_store_dwordx4 v[10:11], v[0:3], off
	v_mov_b32_e32 v149, v159
	v_mov_b32_e32 v153, v159
	v_add_co_u32_e32 v0, vcc, s2, v10
	s_mov_b32 s2, 0xc000
	s_nop 0
	v_addc_co_u32_e32 v1, vcc, 0, v11, vcc
	s_waitcnt lgkmcnt(0)
	global_store_dwordx4 v[0:1], v[4:7], off
	ds_read_b128 v[0:3], v14 offset:43136
	ds_read_b128 v[4:7], v14 offset:44224
	v_add_co_u32_e32 v12, vcc, s2, v10
	s_mov_b32 s2, 0x12000
	s_nop 0
	v_addc_co_u32_e32 v13, vcc, 0, v11, vcc
	v_add_co_u32_e32 v10, vcc, s2, v10
	s_waitcnt lgkmcnt(1)
	global_store_dwordx4 v[12:13], v[0:3], off
	v_addc_co_u32_e32 v11, vcc, 0, v11, vcc
	ds_read_b128 v[0:3], v14 offset:45312
	s_waitcnt lgkmcnt(1)
	global_store_dwordx4 v[10:11], v[4:7], off
	ds_read_b128 v[4:7], v14 offset:46400
	v_lshl_add_u64 v[10:11], v[8:9], 0, v[148:149]
	v_mov_b32_e32 v151, v159
	s_waitcnt lgkmcnt(1)
	global_store_dwordx4 v[10:11], v[0:3], off
	v_lshl_add_u64 v[10:11], v[8:9], 0, v[152:153]
	ds_read_b128 v[0:3], v14 offset:47488
	s_waitcnt lgkmcnt(1)
	global_store_dwordx4 v[10:11], v[4:7], off
	ds_read_b128 v[4:7], v14 offset:48576
	v_lshl_add_u64 v[10:11], v[8:9], 0, v[150:151]
	v_mov_b32_e32 v155, v159
	v_readfirstlane_b32 s10, v222
	s_waitcnt lgkmcnt(1)
	global_store_dwordx4 v[10:11], v[0:3], off
	s_and_b32 s2, s10, 0xffffffc0
	s_nop 0
	v_lshl_add_u64 v[0:1], v[8:9], 0, v[154:155]
	s_waitcnt lgkmcnt(0)
	global_store_dwordx4 v[0:1], v[4:7], off
	v_or_b32_e32 v0, s2, v197
	s_mov_b32 s2, 0x2aaaaaab
	v_mul_hi_i32 v1, v0, s2
	v_lshrrev_b32_e32 v2, 31, v1
	v_ashrrev_i32_e32 v1, 2, v1
	v_add_u32_e32 v2, v1, v2
	s_movk_i32 s2, 0xffe8
	v_lshrrev_b32_e32 v159, 1, v2
	v_mad_u64_u32 v[160:161], s[2:3], v2, s2, v[0:1]
	v_xor_b32_e32 v1, v159, v222
	v_bfi_b32 v1, -8, v160, v1
	v_cmp_lt_i32_e32 vcc, 15, v1
	v_add_u32_e32 v2, s8, v2
	s_and_saveexec_b64 s[2:3], vcc
	s_xor_b64 s[2:3], exec, s[2:3]
	v_mov_b32_e32 v3, 0xbfff80
	v_lshl_add_u32 v153, v2, 6, v3
	s_or_saveexec_b64 s[2:3], s[2:3]
	v_mov_b32_e32 v145, 0x1000
	s_xor_b64 exec, exec, s[2:3]
	v_lshl_or_b32 v2, v2, 11, s17
	v_add_u32_e32 v153, 0x8000000, v2
	v_mov_b32_e32 v145, 0x20000
	s_or_b64 exec, exec, s[2:3]
	v_add_u32_e32 v2, 0x200, v0
	s_mov_b32 s2, 0x2aaaaaab
	v_mul_hi_i32 v3, v2, s2
	v_lshrrev_b32_e32 v4, 31, v3
	v_ashrrev_i32_e32 v3, 2, v3
	v_add_u32_e32 v4, v3, v4
	s_movk_i32 s2, 0xffe8
	v_mad_u64_u32 v[162:163], s[2:3], v4, s2, v[2:3]
	v_lshrrev_b32_e32 v163, 1, v4
	v_xor_b32_e32 v3, v163, v222
	v_bfi_b32 v3, -8, v162, v3
	v_cmp_lt_i32_e32 vcc, 15, v3
	v_add_u32_e32 v4, s8, v4
	s_and_saveexec_b64 s[2:3], vcc
	s_xor_b64 s[2:3], exec, s[2:3]
	v_mov_b32_e32 v5, 0xbfff80
	v_lshl_add_u32 v155, v4, 6, v5
	s_or_saveexec_b64 s[2:3], s[2:3]
	v_mov_b32_e32 v147, 0x1000
	s_xor_b64 exec, exec, s[2:3]
	v_lshl_or_b32 v4, v4, 11, s17
	v_add_u32_e32 v155, 0x8000000, v4
	v_mov_b32_e32 v147, 0x20000
	s_or_b64 exec, exec, s[2:3]
	v_add_u32_e32 v4, 0x400, v0
	s_mov_b32 s2, 0x2aaaaaab
	v_mul_hi_i32 v5, v4, s2
	v_lshrrev_b32_e32 v6, 31, v5
	v_ashrrev_i32_e32 v5, 2, v5
	v_add_u32_e32 v5, v5, v6
	s_movk_i32 s2, 0xffe8
	v_mad_u64_u32 v[164:165], s[2:3], v5, s2, v[4:5]
	v_lshrrev_b32_e32 v165, 1, v5
	v_xor_b32_e32 v4, v165, v222
	v_bfi_b32 v4, -8, v164, v4
	v_cmp_lt_i32_e32 vcc, 15, v4
	v_add_u32_e32 v5, s8, v5
	s_and_saveexec_b64 s[2:3], vcc
	s_xor_b64 s[2:3], exec, s[2:3]
	v_mov_b32_e32 v6, 0xbfff80
	v_lshl_add_u32 v161, v5, 6, v6
	s_or_saveexec_b64 s[2:3], s[2:3]
	v_mov_b32_e32 v149, 0x1000
	s_xor_b64 exec, exec, s[2:3]
	v_lshl_or_b32 v5, v5, 11, s17
	v_add_u32_e32 v161, 0x8000000, v5
	v_mov_b32_e32 v149, 0x20000
	s_or_b64 exec, exec, s[2:3]
	s_lshr_b32 s17, s10, 6
	s_lshl_b32 s19, s17, 5
	s_or_b32 s2, s8, s16
	s_add_u32 s12, s2, s19
	v_or_b32_e32 v5, s12, v194
	s_movk_i32 s2, 0x1800
	v_mov_b64_e32 v[6:7], s[4:5]
	s_addc_u32 s13, s9, 0
	v_mad_u64_u32 v[6:7], s[2:3], v5, s2, v[6:7]
	v_mov_b32_e32 v5, 0x1800
	s_mov_b32 s7, 0
	v_mad_i32_i24 v7, s13, v5, v7
	v_lshl_add_u32 v8, v1, 3, v153
	v_ashrrev_i32_e32 v1, 31, v0
	v_lshl_add_u64 v[6:7], v[6:7], 0, s[6:7]
	v_mov_b32_e32 v157, 0
	v_lshrrev_b32_e32 v10, 28, v1
	v_lshl_add_u64 v[6:7], v[6:7], 0, v[156:157]
	v_lshl_add_u32 v4, v4, 3, v161
	v_mov_b32_e32 v5, v157
	v_add_u32_e32 v16, v0, v10
	global_load_dwordx4 v[96:99], v[6:7], off
	global_load_dwordx4 v[100:103], v[6:7], off offset:32
	global_load_dwordx4 v[104:107], v[6:7], off offset:64
	global_load_dwordx4 v[108:111], v[6:7], off offset:96
	global_load_dwordx4 v[112:115], v[6:7], off offset:128
	global_load_dwordx4 v[116:119], v[6:7], off offset:160
	global_load_dwordx4 v[120:123], v[6:7], off offset:192
	global_load_dwordx4 v[124:127], v[6:7], off offset:224
	global_load_dwordx4 v[128:131], v[6:7], off offset:256
	global_load_dwordx4 v[132:135], v[6:7], off offset:288
	global_load_dwordx4 v[136:139], v[6:7], off offset:320
	global_load_dwordx4 v[140:143], v[6:7], off offset:352
	v_lshl_add_u32 v6, v3, 3, v155
	v_ashrrev_i32_e32 v3, 31, v2
	v_lshl_add_u64 v[14:15], v[4:5], 1, s[84:85]
	v_ashrrev_i32_e32 v166, 4, v16
	v_and_b32_e32 v5, 0x1ffffff0, v16
	v_lshrrev_b32_e32 v11, 28, v3
	v_mov_b32_e32 v9, v157
	s_lshl_b32 s2, s17, 10
	v_sub_u32_e32 v0, v0, v5
	v_lshlrev_b32_e32 v5, 2, v166
	v_mov_b32_e32 v7, v157
	v_add_u32_e32 v17, v2, v11
	v_lshl_add_u64 v[10:11], v[8:9], 1, s[84:85]
	v_bfe_u32 v9, v166, 2, 2
	s_add_i32 s7, s2, 0
	v_and_b32_e32 v5, 12, v5
	v_lshl_add_u64 v[12:13], v[6:7], 1, s[84:85]
	v_ashrrev_i32_e32 v167, 4, v17
	v_and_b32_e32 v7, 0x1ffffff0, v17
	v_bitop3_b32 v0, v5, v0, v9 bitop3:0x36
	s_mov_b32 m0, s7
	v_add_lshl_u32 v16, v166, s8, 11
	v_sub_u32_e32 v2, v2, v7
	v_lshlrev_b32_e32 v7, 2, v167
	global_load_lds_dwordx4 v[10:11], off
	s_add_i32 m0, s7, 0x2000
	v_lshlrev_b32_e32 v168, 3, v0
	v_mov_b32_e32 v1, v157
	v_bfe_u32 v17, v167, 2, 2
	v_and_b32_e32 v7, 12, v7
	global_load_lds_dwordx4 v[12:13], off
	s_add_i32 m0, s7, 0x4000
	v_add3_u32 v0, s18, v16, v168
	v_bitop3_b32 v2, v7, v2, v17 bitop3:0x36
	global_load_lds_dwordx4 v[14:15], off
	s_add_i32 m0, s7, 0x6000
	v_lshl_add_u64 v[10:11], v[0:1], 1, s[84:85]
	v_add_lshl_u32 v18, v167, s8, 11
	v_lshlrev_b32_e32 v169, 3, v2
	global_load_lds_dwordx4 v[10:11], off
	s_add_i32 m0, s7, 0x8000
	v_mov_b32_e32 v3, v157
	v_add3_u32 v2, s18, v18, v169
	s_cmpk_gt_u32 s10, 0xff
	v_lshl_add_u64 v[12:13], v[2:3], 1, s[84:85]
	s_cselect_b64 s[8:9], -1, 0
	s_cmpk_lt_u32 s10, 0x100
	v_add_u32_e32 v156, v8, v145
	global_load_lds_dwordx4 v[12:13], off
	s_cselect_b64 s[10:11], -1, 0
	s_add_i32 m0, s7, 0xa000
	v_lshl_add_u64 v[8:9], v[156:157], 1, s[84:85]
	v_add_u32_e32 v156, v6, v147
	s_waitcnt vmcnt(0) lgkmcnt(0)
	s_barrier
	s_waitcnt vmcnt(0)
	global_load_lds_dwordx4 v[8:9], off
	v_lshl_add_u64 v[6:7], v[156:157], 1, s[84:85]
	s_add_i32 m0, s7, 0xc000
	v_add_u32_e32 v156, v4, v149
	global_load_lds_dwordx4 v[6:7], off
	v_lshl_add_u64 v[4:5], v[156:157], 1, s[84:85]
	s_add_i32 m0, s7, 0xe000
	v_add_u32_e32 v156, 0x20000, v0
	global_load_lds_dwordx4 v[4:5], off
	s_add_i32 m0, s7, 0x10000
	v_lshl_add_u64 v[0:1], v[156:157], 1, s[84:85]
	v_add_u32_e32 v156, 0x20000, v2
	global_load_lds_dwordx4 v[0:1], off
	v_lshl_add_u64 v[0:1], v[156:157], 1, s[84:85]
	s_add_i32 m0, s7, 0x12000
	s_and_b64 vcc, exec, s[10:11]
	global_load_lds_dwordx4 v[0:1], off
	ds_read_b128 v[0:3], v190
	ds_read_b128 v[4:7], v191
	ds_read_b128 v[8:11], v192
	ds_read_b128 v[12:15], v193
	s_waitcnt lgkmcnt(3)
	v_mfma_f32_32x32x16_bf16 v[48:63], v[0:3], v[96:99], 0
	ds_read_b128 v[0:3], v190 offset:128
	s_waitcnt lgkmcnt(3)
	v_mfma_f32_32x32x16_bf16 v[48:63], v[4:7], v[100:103], v[48:63]
	ds_read_b128 v[4:7], v191 offset:128
	s_waitcnt lgkmcnt(3)
	v_mfma_f32_32x32x16_bf16 v[48:63], v[8:11], v[104:107], v[48:63]
	ds_read_b128 v[8:11], v192 offset:128
	s_waitcnt lgkmcnt(3)
	v_mfma_f32_32x32x16_bf16 v[48:63], v[12:15], v[108:111], v[48:63]
	ds_read_b128 v[12:15], v193 offset:128
	s_waitcnt lgkmcnt(3)
	v_mfma_f32_32x32x16_bf16 v[48:63], v[0:3], v[112:115], v[48:63]
	ds_read_b128 v[0:3], v190 offset:256
	s_waitcnt lgkmcnt(3)
	v_mfma_f32_32x32x16_bf16 v[48:63], v[4:7], v[116:119], v[48:63]
	ds_read_b128 v[4:7], v191 offset:256
	s_waitcnt lgkmcnt(3)
	v_mfma_f32_32x32x16_bf16 v[48:63], v[8:11], v[120:123], v[48:63]
	ds_read_b128 v[8:11], v192 offset:256
	s_waitcnt lgkmcnt(3)
	v_mfma_f32_32x32x16_bf16 v[48:63], v[12:15], v[124:127], v[48:63]
	ds_read_b128 v[12:15], v193 offset:256
	s_waitcnt lgkmcnt(3)
	v_mfma_f32_32x32x16_bf16 v[48:63], v[0:3], v[128:131], v[48:63]
	ds_read_b128 v[0:3], v190 offset:12288
	s_waitcnt lgkmcnt(3)
	v_mfma_f32_32x32x16_bf16 v[48:63], v[4:7], v[132:135], v[48:63]
	ds_read_b128 v[4:7], v191 offset:12288
	s_waitcnt lgkmcnt(3)
	v_mfma_f32_32x32x16_bf16 v[48:63], v[8:11], v[136:139], v[48:63]
	ds_read_b128 v[8:11], v192 offset:12288
	s_waitcnt lgkmcnt(2)
	v_mfma_f32_32x32x16_bf16 v[80:95], v[0:3], v[96:99], 0
	ds_read_b128 v[16:19], v193 offset:12288
	s_waitcnt lgkmcnt(2)
	v_mfma_f32_32x32x16_bf16 v[80:95], v[4:7], v[100:103], v[80:95]
	ds_read_b128 v[20:23], v190 offset:12416
	s_waitcnt lgkmcnt(2)
	v_mfma_f32_32x32x16_bf16 v[80:95], v[8:11], v[104:107], v[80:95]
	ds_read_b128 v[24:27], v191 offset:12416
	s_waitcnt lgkmcnt(2)
	v_mfma_f32_32x32x16_bf16 v[80:95], v[16:19], v[108:111], v[80:95]
	ds_read_b128 v[28:31], v192 offset:12416
	s_waitcnt lgkmcnt(2)
	v_mfma_f32_32x32x16_bf16 v[80:95], v[20:23], v[112:115], v[80:95]
	ds_read_b128 v[32:35], v193 offset:12416
	s_waitcnt lgkmcnt(2)
	v_mfma_f32_32x32x16_bf16 v[80:95], v[24:27], v[116:119], v[80:95]
	ds_read_b128 v[36:39], v190 offset:12544
	s_waitcnt lgkmcnt(2)
	v_mfma_f32_32x32x16_bf16 v[80:95], v[28:31], v[120:123], v[80:95]
	ds_read_b128 v[40:43], v191 offset:12544
	s_waitcnt lgkmcnt(2)
	v_mfma_f32_32x32x16_bf16 v[80:95], v[32:35], v[124:127], v[80:95]
	ds_read_b128 v[44:47], v192 offset:12544
	s_waitcnt lgkmcnt(2)
	v_mfma_f32_32x32x16_bf16 v[80:95], v[36:39], v[128:131], v[80:95]
	ds_read_b128 v[64:67], v193 offset:12544
	s_waitcnt lgkmcnt(2)
	v_mfma_f32_32x32x16_bf16 v[80:95], v[40:43], v[132:135], v[80:95]
	s_waitcnt lgkmcnt(1)
	v_mfma_f32_32x32x16_bf16 v[80:95], v[44:47], v[136:139], v[80:95]
	s_waitcnt lgkmcnt(0)
	v_mfma_f32_32x32x16_bf16 v[80:95], v[64:67], v[140:143], v[80:95]
	v_mfma_f32_32x32x16_bf16 v[48:63], v[12:15], v[140:143], v[48:63]
	s_cbranch_vccnz .LBB0_2047
	s_waitcnt vmcnt(0) lgkmcnt(0)
	s_barrier
.LBB0_2047:
	s_nop 10
	v_max_f32_e32 v0, v48, v49
	v_max3_f32 v0, v0, v50, v51
	v_max3_f32 v0, v0, v52, v53
	v_max3_f32 v0, v0, v54, v55
	v_max3_f32 v0, v0, v56, v57
	v_max3_f32 v0, v0, v58, v59
	v_max3_f32 v0, v0, v60, v61
	v_max3_f32 v0, v0, v62, v63
	v_mov_b32_e32 v1, v0
	s_nop 1
	v_permlane32_swap_b32_e32 v0, v1
	v_max_f32_e32 v0, v0, v1
	s_cmp_lg_u64 exec, 0
	v_add_f32_e32 v0, 0, v0
	s_cselect_b64 vcc, -1, 0
	v_cndmask_b32_e32 v151, 0, v0, vcc
	v_sub_f32_e32 v0, v48, v151
	v_exp_f32_e32 v48, v0
	v_sub_f32_e32 v0, v49, v151
	v_exp_f32_e32 v49, v0
	v_sub_f32_e32 v0, v50, v151
	v_exp_f32_e32 v50, v0
	v_sub_f32_e32 v0, v51, v151
	v_exp_f32_e32 v51, v0
	v_sub_f32_e32 v0, v52, v151
	v_exp_f32_e32 v52, v0
	v_sub_f32_e32 v0, v53, v151
	v_exp_f32_e32 v53, v0
	v_sub_f32_e32 v0, v54, v151
	v_exp_f32_e32 v54, v0
	v_sub_f32_e32 v0, v55, v151
	v_exp_f32_e32 v55, v0
	v_sub_f32_e32 v0, v56, v151
	v_exp_f32_e32 v56, v0
	ds_read_b64_tr_b16 v[0:1], v183 offset:24576
	ds_read_b64_tr_b16 v[2:3], v185 offset:26624
	v_cvt_pk_bf16_f32 v4, v48, v49
	v_cvt_pk_bf16_f32 v5, v50, v51
	v_cvt_pk_bf16_f32 v6, v52, v53
	v_cvt_pk_bf16_f32 v7, v54, v55
	ds_read_b64_tr_b16 v[8:9], v182 offset:24576
	ds_read_b64_tr_b16 v[10:11], v184 offset:26624
	ds_read_b64_tr_b16 v[192:193], v185 offset:30720
	ds_read_b64_tr_b16 v[190:191], v183 offset:28672
	s_waitcnt lgkmcnt(4)
	v_mfma_f32_32x32x16_bf16 v[64:79], v[0:3], v[4:7], 0
	v_sub_f32_e32 v0, v57, v151
	v_exp_f32_e32 v57, v0
	ds_read_b64_tr_b16 v[0:1], v186 offset:24576
	ds_read_b64_tr_b16 v[2:3], v188 offset:26624
	ds_read_b64_tr_b16 v[200:201], v184 offset:30720
	ds_read_b64_tr_b16 v[198:199], v182 offset:28672
	v_sub_f32_e32 v12, v58, v151
	v_sub_f32_e32 v62, v62, v151
	v_sub_f32_e32 v63, v63, v151
	v_exp_f32_e32 v58, v12
	s_waitcnt lgkmcnt(2)
	v_mfma_f32_32x32x16_bf16 v[16:31], v[0:3], v[4:7], 0
	v_sub_f32_e32 v0, v60, v151
	v_exp_f32_e32 v60, v0
	v_sub_f32_e32 v0, v61, v151
	v_exp_f32_e32 v61, v0
	v_exp_f32_e32 v62, v62
	v_exp_f32_e32 v63, v63
	v_add_f32_e32 v156, 0, v48
	v_mfma_f32_32x32x16_bf16 v[32:47], v[8:11], v[4:7], 0
	v_sub_f32_e32 v8, v59, v151
	v_exp_f32_e32 v59, v8
	ds_read_b64_tr_b16 v[8:9], v187 offset:24576
	ds_read_b64_tr_b16 v[10:11], v189 offset:26624
	ds_read_b64_tr_b16 v[204:205], v188 offset:30720
	ds_read_b64_tr_b16 v[202:203], v186 offset:28672
	v_cvt_pk_bf16_f32 v210, v56, v57
	v_cvt_pk_bf16_f32 v212, v60, v61
	v_cvt_pk_bf16_f32 v211, v58, v59
	v_cvt_pk_bf16_f32 v213, v62, v63
	s_waitcnt lgkmcnt(2)
	v_mfma_f32_32x32x16_bf16 v[0:15], v[8:11], v[4:7], 0
	v_add_f32_e32 v156, v49, v156
	v_add_f32_e32 v156, v50, v156
	v_max_f32_e32 v157, v81, v81
	v_add_f32_e32 v156, v51, v156
	ds_read_b64_tr_b16 v[208:209], v189 offset:30720
	ds_read_b64_tr_b16 v[206:207], v187 offset:28672
	v_add_f32_e32 v156, v52, v156
	v_add_f32_e32 v156, v53, v156
	v_mfma_f32_32x32x16_bf16 v[64:79], v[190:193], v[210:213], v[64:79]
	v_max_f32_e32 v190, v80, v80
	v_max_f32_e32 v157, v190, v157
	v_max3_f32 v157, v157, v82, v83
	v_max3_f32 v157, v157, v84, v85
	v_add_f32_e32 v156, v54, v156
	v_max3_f32 v157, v157, v86, v87
	v_add_f32_e32 v156, v55, v156
	v_max3_f32 v157, v157, v88, v89
	v_add_f32_e32 v156, v56, v156
	v_max3_f32 v157, v157, v90, v91
	v_mfma_f32_32x32x16_bf16 v[32:47], v[198:201], v[210:213], v[32:47]
	v_add_f32_e32 v156, v57, v156
	v_max3_f32 v157, v157, v92, v93
	v_add_f32_e32 v156, v58, v156
	v_max3_f32 v157, v157, v94, v95
	v_add_f32_e32 v156, v59, v156
	v_mov_b32_e32 v190, v157
	v_add_f32_e32 v156, v60, v156
	s_waitcnt lgkmcnt(2)
	v_mfma_f32_32x32x16_bf16 v[16:31], v[202:205], v[210:213], v[16:31]
	v_permlane32_swap_b32_e32 v157, v190
	v_add_f32_e32 v156, v61, v156
	v_max_f32_e32 v190, v190, v190
	v_max_f32_e32 v157, v157, v157
	v_add_f32_e32 v156, v62, v156
	v_max_f32_e32 v157, v157, v190
	s_waitcnt lgkmcnt(0)
	v_mfma_f32_32x32x16_bf16 v[0:15], v[206:209], v[210:213], v[0:15]
	v_add_f32_e32 v156, v63, v156
	v_sub_f32_e32 v157, v157, v151
	s_mov_b32 s2, 0x41000000
	v_add_f32_e32 v156, 0, v156
	v_cmp_lt_f32_e32 vcc, s2, v157
	s_cbranch_vccz .LBB0_2049
	v_max_f32_e32 v157, v157, v157
	v_max_f32_e32 v157, 0, v157
	v_exp_f32_e64 v190, -v157
	v_add_f32_e32 v151, v151, v157
	v_pk_mul_f32 v[78:79], v[78:79], v[190:191] op_sel_hi:[1,0]
	v_pk_mul_f32 v[76:77], v[76:77], v[190:191] op_sel_hi:[1,0]
	v_pk_mul_f32 v[74:75], v[74:75], v[190:191] op_sel_hi:[1,0]
	v_pk_mul_f32 v[72:73], v[72:73], v[190:191] op_sel_hi:[1,0]
	v_pk_mul_f32 v[70:71], v[70:71], v[190:191] op_sel_hi:[1,0]
	v_pk_mul_f32 v[68:69], v[68:69], v[190:191] op_sel_hi:[1,0]
	v_pk_mul_f32 v[66:67], v[66:67], v[190:191] op_sel_hi:[1,0]
	v_pk_mul_f32 v[64:65], v[64:65], v[190:191] op_sel_hi:[1,0]
	v_pk_mul_f32 v[46:47], v[46:47], v[190:191] op_sel_hi:[1,0]
	v_pk_mul_f32 v[44:45], v[44:45], v[190:191] op_sel_hi:[1,0]
	v_pk_mul_f32 v[42:43], v[42:43], v[190:191] op_sel_hi:[1,0]
	v_pk_mul_f32 v[40:41], v[40:41], v[190:191] op_sel_hi:[1,0]
	v_pk_mul_f32 v[38:39], v[38:39], v[190:191] op_sel_hi:[1,0]
	v_pk_mul_f32 v[36:37], v[36:37], v[190:191] op_sel_hi:[1,0]
	v_pk_mul_f32 v[34:35], v[34:35], v[190:191] op_sel_hi:[1,0]
	v_pk_mul_f32 v[32:33], v[32:33], v[190:191] op_sel_hi:[1,0]
	v_pk_mul_f32 v[30:31], v[30:31], v[190:191] op_sel_hi:[1,0]
	v_pk_mul_f32 v[28:29], v[28:29], v[190:191] op_sel_hi:[1,0]
	v_pk_mul_f32 v[26:27], v[26:27], v[190:191] op_sel_hi:[1,0]
	v_pk_mul_f32 v[24:25], v[24:25], v[190:191] op_sel_hi:[1,0]
	v_pk_mul_f32 v[22:23], v[22:23], v[190:191] op_sel_hi:[1,0]
	v_pk_mul_f32 v[20:21], v[20:21], v[190:191] op_sel_hi:[1,0]
	v_pk_mul_f32 v[18:19], v[18:19], v[190:191] op_sel_hi:[1,0]
	v_pk_mul_f32 v[16:17], v[16:17], v[190:191] op_sel_hi:[1,0]
	v_pk_mul_f32 v[14:15], v[14:15], v[190:191] op_sel_hi:[1,0]
	v_pk_mul_f32 v[12:13], v[12:13], v[190:191] op_sel_hi:[1,0]
	v_pk_mul_f32 v[10:11], v[10:11], v[190:191] op_sel_hi:[1,0]
	v_pk_mul_f32 v[8:9], v[8:9], v[190:191] op_sel_hi:[1,0]
	v_pk_mul_f32 v[6:7], v[6:7], v[190:191] op_sel_hi:[1,0]
	v_pk_mul_f32 v[4:5], v[4:5], v[190:191] op_sel_hi:[1,0]
	v_pk_mul_f32 v[2:3], v[2:3], v[190:191] op_sel_hi:[1,0]
	v_pk_mul_f32 v[0:1], v[0:1], v[190:191] op_sel_hi:[1,0]
	v_mul_f32_e32 v156, v156, v190

.LBB0_2060:
	s_setprio 0
	v_add_u32_e32 v153, s21, v170
	ds_read_b128 v[48:51], v153
	v_add_u32_e32 v155, s21, v171
	v_add_u32_e32 v161, s21, v172
	v_add_u32_e32 v163, s21, v173
	ds_read_b128 v[80:83], v155
	ds_read_b128 v[84:87], v161
	ds_read_b128 v[88:91], v163
	s_waitcnt lgkmcnt(3)
	v_mfma_f32_32x32x16_bf16 v[48:63], v[48:51], v[96:99], 0
	ds_read_b128 v[92:95], v153 offset:128
	s_waitcnt lgkmcnt(3)
	v_mfma_f32_32x32x16_bf16 v[48:63], v[80:83], v[100:103], v[48:63]
	ds_read_b128 v[80:83], v155 offset:128
	s_waitcnt lgkmcnt(3)
	v_mfma_f32_32x32x16_bf16 v[48:63], v[84:87], v[104:107], v[48:63]
	ds_read_b128 v[84:87], v161 offset:128
	s_waitcnt lgkmcnt(3)
	v_mfma_f32_32x32x16_bf16 v[48:63], v[88:91], v[108:111], v[48:63]
	ds_read_b128 v[88:91], v163 offset:128
	s_waitcnt lgkmcnt(3)
	v_mfma_f32_32x32x16_bf16 v[48:63], v[92:95], v[112:115], v[48:63]
	ds_read_b128 v[92:95], v153 offset:256
	s_waitcnt lgkmcnt(3)
	v_mfma_f32_32x32x16_bf16 v[48:63], v[80:83], v[116:119], v[48:63]
	ds_read_b128 v[80:83], v155 offset:256
	s_waitcnt lgkmcnt(3)
	v_mfma_f32_32x32x16_bf16 v[48:63], v[84:87], v[120:123], v[48:63]
	ds_read_b128 v[84:87], v161 offset:256
	s_waitcnt lgkmcnt(3)
	v_mfma_f32_32x32x16_bf16 v[48:63], v[88:91], v[124:127], v[48:63]
	ds_read_b128 v[182:185], v163 offset:256
	s_waitcnt lgkmcnt(3)
	v_mfma_f32_32x32x16_bf16 v[48:63], v[92:95], v[128:131], v[48:63]
	ds_read_b128 v[88:91], v153 offset:12288
	s_waitcnt lgkmcnt(3)
	v_mfma_f32_32x32x16_bf16 v[48:63], v[80:83], v[132:135], v[48:63]
	ds_read_b128 v[186:189], v155 offset:12288
	s_waitcnt lgkmcnt(3)
	v_mfma_f32_32x32x16_bf16 v[48:63], v[84:87], v[136:139], v[48:63]
	ds_read_b128 v[190:193], v161 offset:12288
	s_waitcnt lgkmcnt(2)
	v_mfma_f32_32x32x16_bf16 v[80:95], v[88:91], v[96:99], 0
	ds_read_b128 v[198:201], v163 offset:12288
	s_waitcnt lgkmcnt(2)
	v_mfma_f32_32x32x16_bf16 v[80:95], v[186:189], v[100:103], v[80:95]
	ds_read_b128 v[202:205], v153 offset:12416
	s_waitcnt lgkmcnt(2)
	v_mfma_f32_32x32x16_bf16 v[80:95], v[190:193], v[104:107], v[80:95]
	ds_read_b128 v[206:209], v155 offset:12416
	s_waitcnt lgkmcnt(2)
	v_mfma_f32_32x32x16_bf16 v[80:95], v[198:201], v[108:111], v[80:95]
	ds_read_b128 v[210:213], v161 offset:12416
	s_waitcnt lgkmcnt(2)
	v_mfma_f32_32x32x16_bf16 v[80:95], v[202:205], v[112:115], v[80:95]
	ds_read_b128 v[214:217], v163 offset:12416
	s_waitcnt lgkmcnt(2)
	v_mfma_f32_32x32x16_bf16 v[80:95], v[206:209], v[116:119], v[80:95]
	ds_read_b128 v[218:221], v153 offset:12544
	s_waitcnt lgkmcnt(2)
	v_mfma_f32_32x32x16_bf16 v[80:95], v[210:213], v[120:123], v[80:95]
	ds_read_b128 v[224:227], v155 offset:12544
	s_waitcnt lgkmcnt(2)
	v_mfma_f32_32x32x16_bf16 v[80:95], v[214:217], v[124:127], v[80:95]
	ds_read_b128 v[228:231], v161 offset:12544
	s_waitcnt lgkmcnt(2)
	v_mfma_f32_32x32x16_bf16 v[80:95], v[218:221], v[128:131], v[80:95]
	ds_read_b128 v[232:235], v163 offset:12544
	s_waitcnt lgkmcnt(2)
	v_mfma_f32_32x32x16_bf16 v[80:95], v[224:227], v[132:135], v[80:95]
	s_waitcnt lgkmcnt(1)
	v_mfma_f32_32x32x16_bf16 v[80:95], v[228:231], v[136:139], v[80:95]
	s_waitcnt lgkmcnt(0)
	v_mfma_f32_32x32x16_bf16 v[80:95], v[232:235], v[140:143], v[80:95]
	v_mfma_f32_32x32x16_bf16 v[48:63], v[182:185], v[140:143], v[48:63]
	s_andn2_b64 vcc, exec, s[8:9]
	s_cbranch_vccnz .LBB0_2055

.LBB0_2064:
	v_add_u32_e32 v167, s21, v174
	v_add_u32_e32 v169, s21, v175
	v_sub_f32_e32 v48, v48, v151
	v_sub_f32_e32 v49, v49, v151
	v_sub_f32_e32 v50, v50, v151
	v_sub_f32_e32 v51, v51, v151
	v_sub_f32_e32 v52, v52, v151
	v_sub_f32_e32 v53, v53, v151
	v_sub_f32_e32 v54, v54, v151
	v_sub_f32_e32 v55, v55, v151
	v_add_u32_e32 v155, v167, v177
	v_exp_f32_e32 v48, v48
	v_exp_f32_e32 v49, v49
	v_exp_f32_e32 v50, v50
	v_exp_f32_e32 v51, v51
	v_exp_f32_e32 v52, v52
	v_exp_f32_e32 v53, v53
	v_exp_f32_e32 v54, v54
	v_exp_f32_e32 v55, v55
	v_add_u32_e32 v163, v169, v177
	ds_read_b64_tr_b16 v[186:187], v155 offset:24576
	ds_read_b64_tr_b16 v[188:189], v163 offset:26624
	v_add_u32_e32 v153, v167, v178
	v_add_u32_e32 v161, v169, v178
	ds_read_b64_tr_b16 v[190:191], v153 offset:24576
	ds_read_b64_tr_b16 v[192:193], v161 offset:26624
	ds_read_b64_tr_b16 v[200:201], v163 offset:30720
	ds_read_b64_tr_b16 v[198:199], v155 offset:28672
	v_cvt_pk_bf16_f32 v182, v48, v49
	v_cvt_pk_bf16_f32 v183, v50, v51
	v_cvt_pk_bf16_f32 v184, v52, v53
	v_cvt_pk_bf16_f32 v185, v54, v55
	v_add_u32_e32 v165, v167, v179
	v_add_u32_e32 v167, v167, v180
	s_waitcnt lgkmcnt(4)
	v_mfma_f32_32x32x16_bf16 v[64:79], v[186:189], v[182:185], v[64:79]
	v_add_u32_e32 v168, v169, v179
	ds_read_b64_tr_b16 v[186:187], v165 offset:24576
	ds_read_b64_tr_b16 v[188:189], v168 offset:26624
	ds_read_b64_tr_b16 v[204:205], v161 offset:30720
	ds_read_b64_tr_b16 v[202:203], v153 offset:28672
	v_add_u32_e32 v169, v169, v180
	v_sub_f32_e32 v56, v56, v151
	v_sub_f32_e32 v57, v57, v151
	v_sub_f32_e32 v58, v58, v151
	v_sub_f32_e32 v59, v59, v151
	s_waitcnt lgkmcnt(6)
	v_mfma_f32_32x32x16_bf16 v[32:47], v[190:193], v[182:185], v[32:47]
	ds_read_b64_tr_b16 v[190:191], v167 offset:24576
	ds_read_b64_tr_b16 v[192:193], v169 offset:26624
	ds_read_b64_tr_b16 v[208:209], v168 offset:30720
	ds_read_b64_tr_b16 v[206:207], v165 offset:28672
	v_sub_f32_e32 v60, v60, v151
	v_sub_f32_e32 v61, v61, v151
	v_sub_f32_e32 v62, v62, v151
	v_sub_f32_e32 v63, v63, v151
	v_exp_f32_e32 v56, v56
	v_exp_f32_e32 v57, v57
	s_waitcnt lgkmcnt(6)
	v_mfma_f32_32x32x16_bf16 v[16:31], v[186:189], v[182:185], v[16:31]
	v_exp_f32_e32 v58, v58
	v_exp_f32_e32 v59, v59
	v_exp_f32_e32 v60, v60
	v_exp_f32_e32 v61, v61
	ds_read_b64_tr_b16 v[188:189], v169 offset:30720
	ds_read_b64_tr_b16 v[186:187], v167 offset:28672
	v_exp_f32_e32 v62, v62
	v_exp_f32_e32 v63, v63
	s_waitcnt lgkmcnt(4)
	v_mfma_f32_32x32x16_bf16 v[0:15], v[190:193], v[182:185], v[0:15]
	v_add_f32_e32 v190, 0, v48
	v_cvt_pk_bf16_f32 v182, v56, v57
	v_cvt_pk_bf16_f32 v183, v58, v59
	v_cvt_pk_bf16_f32 v184, v60, v61
	v_cvt_pk_bf16_f32 v185, v62, v63
	v_add_f32_e32 v190, v49, v190
	v_add_f32_e32 v190, v50, v190
	v_mfma_f32_32x32x16_bf16 v[64:79], v[198:201], v[182:185], v[64:79]
	v_add_f32_e32 v190, v51, v190
	v_add_f32_e32 v190, v52, v190
	v_add_f32_e32 v190, v53, v190
	v_add_f32_e32 v190, v54, v190
	v_add_f32_e32 v190, v55, v190
	v_add_f32_e32 v190, v56, v190
	v_add_f32_e32 v190, v57, v190
	v_mfma_f32_32x32x16_bf16 v[32:47], v[202:205], v[182:185], v[32:47]
	v_add_f32_e32 v190, v58, v190
	v_add_f32_e32 v190, v59, v190
	v_add_f32_e32 v190, v60, v190
	v_add_f32_e32 v190, v61, v190
	v_add_f32_e32 v190, v62, v190
	v_add_f32_e32 v190, v63, v190
	v_add_f32_e32 v159, v159, v190
	s_waitcnt lgkmcnt(2)
	v_mfma_f32_32x32x16_bf16 v[16:31], v[206:209], v[182:185], v[16:31]
	s_waitcnt lgkmcnt(0)
	v_mfma_f32_32x32x16_bf16 v[0:15], v[186:189], v[182:185], v[0:15]
	v_max_f32_e32 v182, v80, v81
	v_max3_f32 v182, v182, v82, v83
	v_max3_f32 v182, v182, v84, v85
	v_max3_f32 v182, v182, v86, v87
	v_max3_f32 v182, v182, v88, v89
	v_max3_f32 v182, v182, v90, v91
	v_max3_f32 v182, v182, v92, v93
	v_max3_f32 v182, v182, v94, v95
	v_mov_b32_e32 v183, v182
	s_nop 1
	v_permlane32_swap_b32_e32 v182, v183
	v_max_f32_e32 v182, v182, v183
	v_sub_f32_e32 v182, v182, v151
	v_cmp_lt_f32_e32 vcc, s20, v182
	s_cbranch_vccz .LBB0_2066
	v_max_f32_e32 v182, v182, v182
	v_max_f32_e32 v183, 0, v182
	v_exp_f32_e64 v182, -v183
	v_add_f32_e32 v151, v151, v183
	v_pk_mul_f32 v[78:79], v[78:79], v[182:183] op_sel_hi:[1,0]
	v_pk_mul_f32 v[76:77], v[76:77], v[182:183] op_sel_hi:[1,0]
	v_pk_mul_f32 v[74:75], v[74:75], v[182:183] op_sel_hi:[1,0]
	v_pk_mul_f32 v[72:73], v[72:73], v[182:183] op_sel_hi:[1,0]
	v_pk_mul_f32 v[70:71], v[70:71], v[182:183] op_sel_hi:[1,0]
	v_pk_mul_f32 v[68:69], v[68:69], v[182:183] op_sel_hi:[1,0]
	v_pk_mul_f32 v[66:67], v[66:67], v[182:183] op_sel_hi:[1,0]
	v_pk_mul_f32 v[64:65], v[64:65], v[182:183] op_sel_hi:[1,0]
	v_pk_mul_f32 v[46:47], v[46:47], v[182:183] op_sel_hi:[1,0]
	v_pk_mul_f32 v[44:45], v[44:45], v[182:183] op_sel_hi:[1,0]
	v_pk_mul_f32 v[42:43], v[42:43], v[182:183] op_sel_hi:[1,0]
	v_pk_mul_f32 v[40:41], v[40:41], v[182:183] op_sel_hi:[1,0]
	v_pk_mul_f32 v[38:39], v[38:39], v[182:183] op_sel_hi:[1,0]
	v_pk_mul_f32 v[36:37], v[36:37], v[182:183] op_sel_hi:[1,0]
	v_pk_mul_f32 v[34:35], v[34:35], v[182:183] op_sel_hi:[1,0]
	v_pk_mul_f32 v[32:33], v[32:33], v[182:183] op_sel_hi:[1,0]
	v_pk_mul_f32 v[30:31], v[30:31], v[182:183] op_sel_hi:[1,0]
	v_pk_mul_f32 v[28:29], v[28:29], v[182:183] op_sel_hi:[1,0]
	v_pk_mul_f32 v[26:27], v[26:27], v[182:183] op_sel_hi:[1,0]
	v_pk_mul_f32 v[24:25], v[24:25], v[182:183] op_sel_hi:[1,0]
	v_pk_mul_f32 v[22:23], v[22:23], v[182:183] op_sel_hi:[1,0]
	v_pk_mul_f32 v[20:21], v[20:21], v[182:183] op_sel_hi:[1,0]
	v_pk_mul_f32 v[18:19], v[18:19], v[182:183] op_sel_hi:[1,0]
	v_pk_mul_f32 v[16:17], v[16:17], v[182:183] op_sel_hi:[1,0]
	v_pk_mul_f32 v[14:15], v[14:15], v[182:183] op_sel_hi:[1,0]
	v_pk_mul_f32 v[12:13], v[12:13], v[182:183] op_sel_hi:[1,0]
	v_pk_mul_f32 v[10:11], v[10:11], v[182:183] op_sel_hi:[1,0]
	v_pk_mul_f32 v[8:9], v[8:9], v[182:183] op_sel_hi:[1,0]
	v_pk_mul_f32 v[6:7], v[6:7], v[182:183] op_sel_hi:[1,0]
	v_pk_mul_f32 v[4:5], v[4:5], v[182:183] op_sel_hi:[1,0]
	v_pk_mul_f32 v[2:3], v[2:3], v[182:183] op_sel_hi:[1,0]
	v_pk_mul_f32 v[0:1], v[0:1], v[182:183] op_sel_hi:[1,0]
	v_mul_f32_e32 v159, v159, v182
